# K-loop heads aligned to 64 bytes on the priority-raise version (code placement check)
# baseline (speedup 1.0000x reference)
; #define PG8_STAGE(bufoff, gbase, voff) do { _Pragma("unroll") for (int _i = 0; _i < 2; ++_i) \
;         __builtin_amdgcn_global_load_lds((const unsigned*)((const char*)(gbase) + (voff)[_i]), (PG8_LAS unsigned*)(lds + (bufoff) + ldsw + _i * 8192), 16, 0, 0); } while (0)
; #define PG8_LDA(dst, b, h) do { _Pragma("unroll") for (int m = 0; m < 4; ++m) _Pragma("unroll") for (int k = 0; k < 2; ++k) dst[m][k] = *(const PG8_LAS bf16x8*)(lds + PG8_SA(b, h) + aoff + m * 2048 + k * 1024); } while (0)
; #define PG8_LDB(dst, b, h) do { _Pragma("unroll") for (int n = 0; n < 2; ++n) _Pragma("unroll") for (int k = 0; k < 2; ++k) dst[n][k] = *(const PG8_LAS bf16x8*)(lds + PG8_SB(b, h) + boff + n * 2048 + k * 1024); } while (0)
; #define PG8_MMA(ai, bj, At, Bt) do { __builtin_amdgcn_s_setprio(1); _Pragma("unroll") for (int m = 0; m < 4; ++m) _Pragma("unroll") for (int n = 0; n < 2; ++n) _Pragma("unroll") for (int k = 0; k < 2; ++k) \
;         acc[ai][bj][m][n] = __builtin_amdgcn_mfma_f32_16x16x32_bf16(Bt[n][k], At[m][k], acc[ai][bj][m][n], 0, 0, 0); __builtin_amdgcn_s_setprio(0); } while (0)
; #define PG8_BAR __builtin_amdgcn_s_barrier()
; template <class Epi, class Sched, bool ALIGN_EPI = false, bool SP2 = false>
; __device__ __forceinline__ void gemm_phase(PG8_LAS unsigned char* lds, const Gemm g, const Sched& S, const Epi& E) {
;     ...
;         const bool has_next = S.next(ui + 1, nxt);
;         const char* nA = has_next ? (const char*)g.A + (size_t)nxt.pm * tstep : cA; const char* nB = has_next ? (const char*)g.Bt + (size_t)nxt.pn * tstep : cB;
;         for (int t = 0; t < nt; t += 2) {
;             const bool last = (t == nt - 2);
;             const char* a1 = cA + (size_t)(t + 1) * kstep;
;             const char* a2 = last ? nA : cA + (size_t)(t + 2) * kstep; const char* b2 = last ? nB : cB + (size_t)(t + 2) * kstep;
;             const char* a3 = a2 + kstep; const char* b3 = b2 + kstep;
;             if (last && has_next) S.a_ready(nxt);
;             if constexpr (SP2) {
;             PG8_LDB(B0, 0, 0); PG8_LDB(B1, 0, 1); PG8_SCHED; PG8_LDA(At, 0, 0); PG8_STAGE(PG8_SA(1, 1), a1 + hstep, voffA);
;             PG8_WAIT_V(8); PG8_WAIT_L(0); PG8_BAR; PG8_MMA(0, 0, At, B0); PG8_MMA(0, 1, At, B1); PG8_BAR; PG8_SCHED;
;             PG8_LDA(At, 0, 1); PG8_STAGE(PG8_SB(0, 0), b2, voffB); PG8_STAGE(PG8_SB(0, 1), b2 + hstep, voffB); PG8_STAGE(PG8_SA(0, 0), a2, voffA);
.LBB0_128:
	s_ashr_i32 s25, s24, 31
	s_lshl_b64 s[28:29], s[24:25], 20
	v_readlane_b32 s30, v254, 51
	v_readlane_b32 s31, v254, 52
	s_add_u32 s28, s30, s28
	s_addc_u32 s29, s31, s29
	s_and_b64 s[30:31], s[26:27], exec
	s_cselect_b32 s25, s29, s9
	s_cselect_b32 s35, s28, s8
	s_ashr_i32 s23, s22, 31
	s_lshl_b64 s[30:31], s[22:23], 20
	s_add_u32 s30, s94, s30
	s_addc_u32 s31, s95, s31
	s_and_b64 s[46:47], s[26:27], exec
	s_cselect_b32 s23, s31, s45
	s_cselect_b32 s43, s30, s44
	s_add_u32 s8, s8, 0x80080
	s_addc_u32 s9, s9, 0
	s_add_u32 s48, s44, 0x100
	s_addc_u32 s49, s45, 0
	s_mov_b32 s54, -2
	s_waitcnt lgkmcnt(0)
	ds_read_b128 v[96:99], v173
	ds_read_b128 v[100:103], v173 offset:1024
	ds_read_b128 v[104:107], v173 offset:2048
	ds_read_b128 v[112:115], v173 offset:3072
	ds_read_b128 v[178:181], v175
	ds_read_b128 v[182:185], v175 offset:1024
	ds_read_b128 v[186:189], v175 offset:2048
	ds_read_b128 v[190:193], v175 offset:3072
	s_add_u32 s44, s8, 0xfff80080
	s_addc_u32 s45, s9, -1
	s_cmp_eq_u32 s54, 28
	s_cselect_b32 s47, s25, s45
	s_cselect_b32 s46, s35, s44
	s_cselect_b32 s45, s23, s49
	s_cselect_b32 s44, s43, s48
	s_add_i32 m0, s63, 0xc000
	ds_read_b128 v[198:201], v177
	ds_read_b128 v[202:205], v177 offset:1024
	ds_read_b128 v[206:209], v177 offset:2048
	ds_read_b128 v[210:213], v177 offset:3072
	ds_read_b128 v[214:217], v177 offset:4096
	ds_read_b128 v[218:221], v177 offset:5120
	ds_read_b128 v[222:225], v177 offset:6144
	ds_read_b128 v[226:229], v177 offset:7168
	global_load_lds_dwordx4 v154, s[8:9]
	s_add_i32 m0, s63, 0xe000
	s_nop 0
	global_load_lds_dwordx4 v156, s[8:9]
	s_waitcnt lgkmcnt(0)
	s_setprio 1
	s_barrier
	v_mfma_f32_16x16x32_bf16 v[140:143], v[96:99], v[198:201], 0
	v_mfma_f32_16x16x32_bf16 v[132:135], v[104:107], v[198:201], 0
	v_mfma_f32_16x16x32_bf16 v[116:119], v[96:99], v[206:209], 0
	v_mfma_f32_16x16x32_bf16 v[124:127], v[104:107], v[206:209], 0
	v_mfma_f32_16x16x32_bf16 v[84:87], v[96:99], v[214:217], 0
	v_mfma_f32_16x16x32_bf16 v[92:95], v[104:107], v[214:217], 0
	v_mfma_f32_16x16x32_bf16 v[68:71], v[96:99], v[222:225], 0
	v_mfma_f32_16x16x32_bf16 v[76:79], v[104:107], v[222:225], 0
	v_mfma_f32_16x16x32_bf16 v[140:143], v[100:103], v[202:205], v[140:143]
	v_mfma_f32_16x16x32_bf16 v[132:135], v[112:115], v[202:205], v[132:135]
	v_mfma_f32_16x16x32_bf16 v[116:119], v[100:103], v[210:213], v[116:119]
	v_mfma_f32_16x16x32_bf16 v[124:127], v[112:115], v[210:213], v[124:127]
	v_mfma_f32_16x16x32_bf16 v[84:87], v[100:103], v[218:221], v[84:87]
	v_mfma_f32_16x16x32_bf16 v[92:95], v[112:115], v[218:221], v[92:95]
	v_mfma_f32_16x16x32_bf16 v[68:71], v[100:103], v[226:229], v[68:71]
	v_mfma_f32_16x16x32_bf16 v[76:79], v[112:115], v[226:229], v[76:79]
	v_mfma_f32_16x16x32_bf16 v[128:131], v[178:181], v[198:201], 0
	v_mfma_f32_16x16x32_bf16 v[136:139], v[186:189], v[198:201], 0
	v_mfma_f32_16x16x32_bf16 v[120:123], v[178:181], v[206:209], 0
	v_mfma_f32_16x16x32_bf16 v[108:111], v[186:189], v[206:209], 0
	v_mfma_f32_16x16x32_bf16 v[88:91], v[178:181], v[214:217], 0
	v_mfma_f32_16x16x32_bf16 v[80:83], v[186:189], v[214:217], 0
	v_mfma_f32_16x16x32_bf16 v[72:75], v[178:181], v[222:225], 0
	v_mfma_f32_16x16x32_bf16 v[64:67], v[186:189], v[222:225], 0
	v_mfma_f32_16x16x32_bf16 v[128:131], v[182:185], v[202:205], v[128:131]
	v_mfma_f32_16x16x32_bf16 v[136:139], v[190:193], v[202:205], v[136:139]
	v_mfma_f32_16x16x32_bf16 v[120:123], v[182:185], v[210:213], v[120:123]
	v_mfma_f32_16x16x32_bf16 v[108:111], v[190:193], v[210:213], v[108:111]
	v_mfma_f32_16x16x32_bf16 v[88:91], v[182:185], v[218:221], v[88:91]
	v_mfma_f32_16x16x32_bf16 v[80:83], v[190:193], v[218:221], v[80:83]
	v_mfma_f32_16x16x32_bf16 v[72:75], v[182:185], v[226:229], v[72:75]
	v_mfma_f32_16x16x32_bf16 v[64:67], v[190:193], v[226:229], v[64:67]
	s_barrier
	s_setprio 0
	s_add_i32 s55, s52, s62
	v_lshl_add_u64 v[160:161], s[44:45], 0, v[144:145]
	s_mov_b32 m0, s55
	ds_read_b128 v[198:201], v177 offset:16384
	ds_read_b128 v[202:205], v177 offset:17408
	ds_read_b128 v[206:209], v177 offset:18432
	ds_read_b128 v[210:213], v177 offset:19456
	ds_read_b128 v[214:217], v177 offset:20480
	ds_read_b128 v[218:221], v177 offset:21504
	ds_read_b128 v[222:225], v177 offset:22528
	ds_read_b128 v[226:229], v177 offset:23552
	global_load_lds_dwordx4 v[160:161], off
	s_add_i32 m0, s55, 0x2000
	s_add_u32 s56, s44, 0x80000
	v_lshl_add_u64 v[164:165], s[44:45], 0, v[146:147]
	s_addc_u32 s57, s45, 0
	s_add_i32 s55, s53, s62
	global_load_lds_dwordx4 v[164:165], off
	s_mov_b32 m0, s55
	v_lshl_add_u64 v[194:195], s[46:47], 0, v[146:147]
	global_load_lds_dwordx4 v144, s[56:57]
	s_add_i32 m0, s55, 0x2000
	s_nop 0
	global_load_lds_dwordx4 v146, s[56:57]
	s_mov_b32 m0, s63
	v_lshl_add_u64 v[170:171], s[46:47], 0, v[144:145]
	global_load_lds_dwordx4 v[170:171], off
	s_mov_b32 m0, s64
	s_nop 0
	global_load_lds_dwordx4 v[194:195], off
	s_waitcnt lgkmcnt(0)
	s_setprio 1
	s_barrier
; #define PG8_STAGE(bufoff, gbase, voff) do { _Pragma("unroll") for (int _i = 0; _i < 2; ++_i) \
;         __builtin_amdgcn_global_load_lds((const unsigned*)((const char*)(gbase) + (voff)[_i]), (PG8_LAS unsigned*)(lds + (bufoff) + ldsw + _i * 8192), 16, 0, 0); } while (0)
; #define PG8_LDA(dst, b, h) do { _Pragma("unroll") for (int m = 0; m < 4; ++m) _Pragma("unroll") for (int k = 0; k < 2; ++k) dst[m][k] = *(const PG8_LAS bf16x8*)(lds + PG8_SA(b, h) + aoff + m * 2048 + k * 1024); } while (0)
; #define PG8_LDB(dst, b, h) do { _Pragma("unroll") for (int n = 0; n < 2; ++n) _Pragma("unroll") for (int k = 0; k < 2; ++k) dst[n][k] = *(const PG8_LAS bf16x8*)(lds + PG8_SB(b, h) + boff + n * 2048 + k * 1024); } while (0)
; #define PG8_MMA(ai, bj, At, Bt) do { __builtin_amdgcn_s_setprio(1); _Pragma("unroll") for (int m = 0; m < 4; ++m) _Pragma("unroll") for (int n = 0; n < 2; ++n) _Pragma("unroll") for (int k = 0; k < 2; ++k) \
;         acc[ai][bj][m][n] = __builtin_amdgcn_mfma_f32_16x16x32_bf16(Bt[n][k], At[m][k], acc[ai][bj][m][n], 0, 0, 0); __builtin_amdgcn_s_setprio(0); } while (0)
; #define PG8_WAIT_V(n) asm volatile("s_waitcnt vmcnt(" #n ")" ::: "memory")
; #define PG8_WAIT_L(n) asm volatile("s_waitcnt lgkmcnt(" #n ")" ::: "memory")
; #define PG8_BAR __builtin_amdgcn_s_barrier()
; #define PG8_SCHED __builtin_amdgcn_sched_barrier(0)
; template <class Epi, class Sched, bool ALIGN_EPI = false, bool SP2 = false>
; __device__ __forceinline__ void gemm_phase(PG8_LAS unsigned char* lds, const Gemm g, const Sched& S, const Epi& E) {
;     ...
;             PG8_WAIT_V(8); PG8_WAIT_L(0); PG8_BAR; PG8_MMA(1, 0, At, B0); PG8_MMA(1, 1, At, B1); PG8_BAR; PG8_SCHED;
;             PG8_LDB(B0, 1, 0); PG8_LDB(B1, 1, 1); PG8_SCHED; PG8_LDA(At, 1, 0); PG8_STAGE(PG8_SA(0, 1), a2 + hstep, voffA);
;             PG8_WAIT_V(8); PG8_WAIT_L(0); PG8_BAR; PG8_MMA(0, 0, At, B0); PG8_MMA(0, 1, At, B1); PG8_BAR; PG8_SCHED;
	v_mfma_f32_16x16x32_bf16 v[60:63], v[96:99], v[198:201], 0
	v_mfma_f32_16x16x32_bf16 v[52:55], v[104:107], v[198:201], 0
	v_mfma_f32_16x16x32_bf16 v[36:39], v[96:99], v[206:209], 0
	v_mfma_f32_16x16x32_bf16 v[44:47], v[104:107], v[206:209], 0
	v_mfma_f32_16x16x32_bf16 v[20:23], v[96:99], v[214:217], 0
	v_mfma_f32_16x16x32_bf16 v[28:31], v[104:107], v[214:217], 0
	v_mfma_f32_16x16x32_bf16 v[4:7], v[96:99], v[222:225], 0
	v_mfma_f32_16x16x32_bf16 v[12:15], v[104:107], v[222:225], 0
	v_mfma_f32_16x16x32_bf16 v[60:63], v[100:103], v[202:205], v[60:63]
	v_mfma_f32_16x16x32_bf16 v[52:55], v[112:115], v[202:205], v[52:55]
	v_mfma_f32_16x16x32_bf16 v[36:39], v[100:103], v[210:213], v[36:39]
	v_mfma_f32_16x16x32_bf16 v[44:47], v[112:115], v[210:213], v[44:47]
	v_mfma_f32_16x16x32_bf16 v[20:23], v[100:103], v[218:221], v[20:23]
	v_mfma_f32_16x16x32_bf16 v[28:31], v[112:115], v[218:221], v[28:31]
	v_mfma_f32_16x16x32_bf16 v[4:7], v[100:103], v[226:229], v[4:7]
	v_mfma_f32_16x16x32_bf16 v[12:15], v[112:115], v[226:229], v[12:15]
	v_mfma_f32_16x16x32_bf16 v[48:51], v[178:181], v[198:201], 0
	v_mfma_f32_16x16x32_bf16 v[56:59], v[186:189], v[198:201], 0
	v_mfma_f32_16x16x32_bf16 v[40:43], v[178:181], v[206:209], 0
	v_mfma_f32_16x16x32_bf16 v[32:35], v[186:189], v[206:209], 0
	v_mfma_f32_16x16x32_bf16 v[24:27], v[178:181], v[214:217], 0
	v_mfma_f32_16x16x32_bf16 v[16:19], v[186:189], v[214:217], 0
	v_mfma_f32_16x16x32_bf16 v[8:11], v[178:181], v[222:225], 0
	v_mfma_f32_16x16x32_bf16 v[0:3], v[186:189], v[222:225], 0
	v_mfma_f32_16x16x32_bf16 v[48:51], v[182:185], v[202:205], v[48:51]
	v_mfma_f32_16x16x32_bf16 v[56:59], v[190:193], v[202:205], v[56:59]
	v_mfma_f32_16x16x32_bf16 v[40:43], v[182:185], v[210:213], v[40:43]
	v_mfma_f32_16x16x32_bf16 v[32:35], v[190:193], v[210:213], v[32:35]
	v_mfma_f32_16x16x32_bf16 v[24:27], v[182:185], v[218:221], v[24:27]
	v_mfma_f32_16x16x32_bf16 v[16:19], v[190:193], v[218:221], v[16:19]
	v_mfma_f32_16x16x32_bf16 v[8:11], v[182:185], v[226:229], v[8:11]
	v_mfma_f32_16x16x32_bf16 v[0:3], v[190:193], v[226:229], v[0:3]
	s_barrier
	s_setprio 0
	s_add_i32 s55, 0, 0x18000
	s_add_i32 s56, 0, 0x1c000
	v_add_u32_e32 v112, s55, v167
	v_add_u32_e32 v162, s56, v167
	ds_read_b128 v[96:99], v112
	ds_read_b128 v[100:103], v112 offset:1024
	ds_read_b128 v[104:107], v112 offset:2048
	ds_read_b128 v[112:115], v112 offset:3072
	ds_read_b128 v[178:181], v162
	ds_read_b128 v[182:185], v162 offset:1024
	ds_read_b128 v[186:189], v162 offset:2048
	ds_read_b128 v[190:193], v162 offset:3072
	s_add_u32 s46, s46, 0x80000
	s_addc_u32 s47, s47, 0
	s_mov_b32 m0, s65
	ds_read_b128 v[198:201], v177 offset:32768
	ds_read_b128 v[202:205], v177 offset:33792
	ds_read_b128 v[206:209], v177 offset:34816
	ds_read_b128 v[210:213], v177 offset:35840
	ds_read_b128 v[214:217], v177 offset:36864
	ds_read_b128 v[218:221], v177 offset:37888
	ds_read_b128 v[222:225], v177 offset:38912
	ds_read_b128 v[226:229], v177 offset:39936
	global_load_lds_dwordx4 v144, s[46:47]
	s_mov_b32 m0, s66
	v_lshl_add_u64 v[230:231], s[46:47], 0, v[146:147]
	global_load_lds_dwordx4 v[230:231], off
	s_waitcnt vmcnt(8) lgkmcnt(0)
	s_setprio 1
	s_barrier
	v_mfma_f32_16x16x32_bf16 v[140:143], v[96:99], v[198:201], v[140:143]
	v_mfma_f32_16x16x32_bf16 v[132:135], v[104:107], v[198:201], v[132:135]
	v_mfma_f32_16x16x32_bf16 v[116:119], v[96:99], v[206:209], v[116:119]
	v_mfma_f32_16x16x32_bf16 v[124:127], v[104:107], v[206:209], v[124:127]
	v_mfma_f32_16x16x32_bf16 v[84:87], v[96:99], v[214:217], v[84:87]
	v_mfma_f32_16x16x32_bf16 v[92:95], v[104:107], v[214:217], v[92:95]
	v_mfma_f32_16x16x32_bf16 v[68:71], v[96:99], v[222:225], v[68:71]
	v_mfma_f32_16x16x32_bf16 v[76:79], v[104:107], v[222:225], v[76:79]
	v_mfma_f32_16x16x32_bf16 v[140:143], v[100:103], v[202:205], v[140:143]
	v_mfma_f32_16x16x32_bf16 v[132:135], v[112:115], v[202:205], v[132:135]
	v_mfma_f32_16x16x32_bf16 v[116:119], v[100:103], v[210:213], v[116:119]
	v_mfma_f32_16x16x32_bf16 v[124:127], v[112:115], v[210:213], v[124:127]
	v_mfma_f32_16x16x32_bf16 v[84:87], v[100:103], v[218:221], v[84:87]
	v_mfma_f32_16x16x32_bf16 v[92:95], v[112:115], v[218:221], v[92:95]
	v_mfma_f32_16x16x32_bf16 v[68:71], v[100:103], v[226:229], v[68:71]
	v_mfma_f32_16x16x32_bf16 v[76:79], v[112:115], v[226:229], v[76:79]
	v_mfma_f32_16x16x32_bf16 v[128:131], v[178:181], v[198:201], v[128:131]
	v_mfma_f32_16x16x32_bf16 v[136:139], v[186:189], v[198:201], v[136:139]
	v_mfma_f32_16x16x32_bf16 v[120:123], v[178:181], v[206:209], v[120:123]
	v_mfma_f32_16x16x32_bf16 v[108:111], v[186:189], v[206:209], v[108:111]
	v_mfma_f32_16x16x32_bf16 v[88:91], v[178:181], v[214:217], v[88:91]
	v_mfma_f32_16x16x32_bf16 v[80:83], v[186:189], v[214:217], v[80:83]
	v_mfma_f32_16x16x32_bf16 v[72:75], v[178:181], v[222:225], v[72:75]
	v_mfma_f32_16x16x32_bf16 v[64:67], v[186:189], v[222:225], v[64:67]
	v_mfma_f32_16x16x32_bf16 v[128:131], v[182:185], v[202:205], v[128:131]
	v_mfma_f32_16x16x32_bf16 v[136:139], v[190:193], v[202:205], v[136:139]
	v_mfma_f32_16x16x32_bf16 v[120:123], v[182:185], v[210:213], v[120:123]
	v_mfma_f32_16x16x32_bf16 v[108:111], v[190:193], v[210:213], v[108:111]
	v_mfma_f32_16x16x32_bf16 v[88:91], v[182:185], v[218:221], v[88:91]
	v_mfma_f32_16x16x32_bf16 v[80:83], v[190:193], v[218:221], v[80:83]
	v_mfma_f32_16x16x32_bf16 v[72:75], v[182:185], v[226:229], v[72:75]
	v_mfma_f32_16x16x32_bf16 v[64:67], v[190:193], v[226:229], v[64:67]
	s_barrier
; #define PG8_STAGE(bufoff, gbase, voff) do { _Pragma("unroll") for (int _i = 0; _i < 2; ++_i) \
;         __builtin_amdgcn_global_load_lds((const unsigned*)((const char*)(gbase) + (voff)[_i]), (PG8_LAS unsigned*)(lds + (bufoff) + ldsw + _i * 8192), 16, 0, 0); } while (0)
; #define PG8_LDA(dst, b, h) do { _Pragma("unroll") for (int m = 0; m < 4; ++m) _Pragma("unroll") for (int k = 0; k < 2; ++k) dst[m][k] = *(const PG8_LAS bf16x8*)(lds + PG8_SA(b, h) + aoff + m * 2048 + k * 1024); } while (0)
; #define PG8_MMA(ai, bj, At, Bt) do { __builtin_amdgcn_s_setprio(1); _Pragma("unroll") for (int m = 0; m < 4; ++m) _Pragma("unroll") for (int n = 0; n < 2; ++n) _Pragma("unroll") for (int k = 0; k < 2; ++k) \
;         acc[ai][bj][m][n] = __builtin_amdgcn_mfma_f32_16x16x32_bf16(Bt[n][k], At[m][k], acc[ai][bj][m][n], 0, 0, 0); __builtin_amdgcn_s_setprio(0); } while (0)
; #define PG8_WAIT_V(n) asm volatile("s_waitcnt vmcnt(" #n ")" ::: "memory")
; #define PG8_WAIT_L(n) asm volatile("s_waitcnt lgkmcnt(" #n ")" ::: "memory")
; #define PG8_BAR __builtin_amdgcn_s_barrier()
; #define PG8_SCHED __builtin_amdgcn_sched_barrier(0)
; template <class Epi, class Sched, bool ALIGN_EPI = false, bool SP2 = false>
; __device__ __forceinline__ void gemm_phase(PG8_LAS unsigned char* lds, const Gemm g, const Sched& S, const Epi& E) {
;     ...
;         for (int t = 0; t < nt; t += 2) {
;     ...
;             PG8_LDA(At, 1, 1); PG8_STAGE(PG8_SB(1, 0), b3, voffB); PG8_STAGE(PG8_SB(1, 1), b3 + hstep, voffB); PG8_STAGE(PG8_SA(1, 0), a3, voffA);
;             PG8_WAIT_V(8); PG8_WAIT_L(0); PG8_BAR; PG8_MMA(1, 0, At, B0); PG8_MMA(1, 1, At, B1); PG8_BAR; PG8_SCHED;
	s_setprio 0
	s_add_i32 s46, s55, s62
	v_lshl_add_u64 v[160:161], v[160:161], 0, s[12:13]
	s_mov_b32 m0, s46
	ds_read_b128 v[198:201], v177 offset:49152
	ds_read_b128 v[202:205], v177 offset:50176
	ds_read_b128 v[206:209], v177 offset:51200
	ds_read_b128 v[210:213], v177 offset:52224
	ds_read_b128 v[214:217], v177 offset:53248
	ds_read_b128 v[218:221], v177 offset:54272
	ds_read_b128 v[222:225], v177 offset:55296
	ds_read_b128 v[226:229], v177 offset:56320
	global_load_lds_dwordx4 v[160:161], off
	s_add_i32 m0, s46, 0x2000
	s_add_u32 s44, s44, 0x80080
	v_lshl_add_u64 v[160:161], v[164:165], 0, s[12:13]
	s_addc_u32 s45, s45, 0
	s_add_i32 s46, s56, s62
	global_load_lds_dwordx4 v[160:161], off
	s_mov_b32 m0, s46
	s_nop 0
	global_load_lds_dwordx4 v144, s[44:45]
	s_add_i32 m0, s46, 0x2000
	v_lshl_add_u64 v[160:161], s[44:45], 0, v[146:147]
	global_load_lds_dwordx4 v[160:161], off
	s_mov_b32 m0, s68
	v_lshl_add_u64 v[160:161], v[170:171], 0, s[12:13]
	global_load_lds_dwordx4 v[160:161], off
	s_mov_b32 m0, s69
	v_lshl_add_u64 v[160:161], v[194:195], 0, s[12:13]
	global_load_lds_dwordx4 v[160:161], off
	s_waitcnt vmcnt(8) lgkmcnt(0)
	s_setprio 1
	s_barrier
	v_mfma_f32_16x16x32_bf16 v[60:63], v[96:99], v[198:201], v[60:63]
	v_mfma_f32_16x16x32_bf16 v[52:55], v[104:107], v[198:201], v[52:55]
	v_mfma_f32_16x16x32_bf16 v[36:39], v[96:99], v[206:209], v[36:39]
	v_mfma_f32_16x16x32_bf16 v[44:47], v[104:107], v[206:209], v[44:47]
	v_mfma_f32_16x16x32_bf16 v[20:23], v[96:99], v[214:217], v[20:23]
	v_mfma_f32_16x16x32_bf16 v[28:31], v[104:107], v[214:217], v[28:31]
	v_mfma_f32_16x16x32_bf16 v[4:7], v[96:99], v[222:225], v[4:7]
	v_mfma_f32_16x16x32_bf16 v[12:15], v[104:107], v[222:225], v[12:15]
	v_mfma_f32_16x16x32_bf16 v[60:63], v[100:103], v[202:205], v[60:63]
	v_mfma_f32_16x16x32_bf16 v[52:55], v[112:115], v[202:205], v[52:55]
	v_mfma_f32_16x16x32_bf16 v[36:39], v[100:103], v[210:213], v[36:39]
	v_mfma_f32_16x16x32_bf16 v[44:47], v[112:115], v[210:213], v[44:47]
	v_mfma_f32_16x16x32_bf16 v[20:23], v[100:103], v[218:221], v[20:23]
	v_mfma_f32_16x16x32_bf16 v[28:31], v[112:115], v[218:221], v[28:31]
	v_mfma_f32_16x16x32_bf16 v[4:7], v[100:103], v[226:229], v[4:7]
	v_mfma_f32_16x16x32_bf16 v[12:15], v[112:115], v[226:229], v[12:15]
	v_mfma_f32_16x16x32_bf16 v[48:51], v[178:181], v[198:201], v[48:51]
	v_mfma_f32_16x16x32_bf16 v[56:59], v[186:189], v[198:201], v[56:59]
	v_mfma_f32_16x16x32_bf16 v[40:43], v[178:181], v[206:209], v[40:43]
	v_mfma_f32_16x16x32_bf16 v[32:35], v[186:189], v[206:209], v[32:35]
	v_mfma_f32_16x16x32_bf16 v[24:27], v[178:181], v[214:217], v[24:27]
	v_mfma_f32_16x16x32_bf16 v[16:19], v[186:189], v[214:217], v[16:19]
	v_mfma_f32_16x16x32_bf16 v[8:11], v[178:181], v[222:225], v[8:11]
	v_mfma_f32_16x16x32_bf16 v[0:3], v[186:189], v[222:225], v[0:3]
	v_mfma_f32_16x16x32_bf16 v[48:51], v[182:185], v[202:205], v[48:51]
	v_mfma_f32_16x16x32_bf16 v[56:59], v[190:193], v[202:205], v[56:59]
	v_mfma_f32_16x16x32_bf16 v[40:43], v[182:185], v[210:213], v[40:43]
	v_mfma_f32_16x16x32_bf16 v[32:35], v[190:193], v[210:213], v[32:35]
	v_mfma_f32_16x16x32_bf16 v[24:27], v[182:185], v[218:221], v[24:27]
	v_mfma_f32_16x16x32_bf16 v[16:19], v[190:193], v[218:221], v[16:19]
	v_mfma_f32_16x16x32_bf16 v[8:11], v[182:185], v[226:229], v[8:11]
	v_mfma_f32_16x16x32_bf16 v[0:3], v[190:193], v[226:229], v[0:3]
	s_barrier
	s_setprio 0
	s_add_i32 s54, s54, 2
	s_add_u32 s8, s8, 0x100
	s_addc_u32 s9, s9, 0
	s_add_u32 s48, s48, 0x100
	s_addc_u32 s49, s49, 0
	.p2align	6

; #define PG8_STAGE(bufoff, gbase, voff) do { _Pragma("unroll") for (int _i = 0; _i < 2; ++_i) \
;         __builtin_amdgcn_global_load_lds((const unsigned*)((const char*)(gbase) + (voff)[_i]), (PG8_LAS unsigned*)(lds + (bufoff) + ldsw + _i * 8192), 16, 0, 0); } while (0)
; #define PG8_LDA(dst, b, h) do { _Pragma("unroll") for (int m = 0; m < 4; ++m) _Pragma("unroll") for (int k = 0; k < 2; ++k) dst[m][k] = *(const PG8_LAS bf16x8*)(lds + PG8_SA(b, h) + aoff + m * 2048 + k * 1024); } while (0)
; #define PG8_LDB(dst, b, h) do { _Pragma("unroll") for (int n = 0; n < 2; ++n) _Pragma("unroll") for (int k = 0; k < 2; ++k) dst[n][k] = *(const PG8_LAS bf16x8*)(lds + PG8_SB(b, h) + boff + n * 2048 + k * 1024); } while (0)
; #define PG8_MMA(ai, bj, At, Bt) do { __builtin_amdgcn_s_setprio(1); _Pragma("unroll") for (int m = 0; m < 4; ++m) _Pragma("unroll") for (int n = 0; n < 2; ++n) _Pragma("unroll") for (int k = 0; k < 2; ++k) \
;         acc[ai][bj][m][n] = __builtin_amdgcn_mfma_f32_16x16x32_bf16(Bt[n][k], At[m][k], acc[ai][bj][m][n], 0, 0, 0); __builtin_amdgcn_s_setprio(0); } while (0)
; #define PG8_BAR __builtin_amdgcn_s_barrier()
; template <class Epi, class Sched, bool ALIGN_EPI = false, bool SP2 = false>
; __device__ __forceinline__ void gemm_phase(PG8_LAS unsigned char* lds, const Gemm g, const Sched& S, const Epi& E) {
;     ...
;         const bool has_next = S.next(ui + 1, nxt);
;         const char* nA = has_next ? (const char*)g.A + (size_t)nxt.pm * tstep : cA; const char* nB = has_next ? (const char*)g.Bt + (size_t)nxt.pn * tstep : cB;
;         for (int t = 0; t < nt; t += 2) {
;             const bool last = (t == nt - 2);
;             const char* a1 = cA + (size_t)(t + 1) * kstep;
;             const char* a2 = last ? nA : cA + (size_t)(t + 2) * kstep; const char* b2 = last ? nB : cB + (size_t)(t + 2) * kstep;
;             const char* a3 = a2 + kstep; const char* b3 = b2 + kstep;
;             if (last && has_next) S.a_ready(nxt);
;             if constexpr (SP2) {
;             PG8_LDB(B0, 0, 0); PG8_LDB(B1, 0, 1); PG8_SCHED; PG8_LDA(At, 0, 0); PG8_STAGE(PG8_SA(1, 1), a1 + hstep, voffA);
;             PG8_WAIT_V(8); PG8_WAIT_L(0); PG8_BAR; PG8_MMA(0, 0, At, B0); PG8_MMA(0, 1, At, B1); PG8_BAR; PG8_SCHED;
;             PG8_LDA(At, 0, 1); PG8_STAGE(PG8_SB(0, 0), b2, voffB); PG8_STAGE(PG8_SB(0, 1), b2 + hstep, voffB); PG8_STAGE(PG8_SA(0, 0), a2, voffA);
.LBB0_306:
	s_ashr_i32 s21, s20, 31
	s_lshl_b64 s[22:23], s[20:21], 20
	s_add_u32 s22, s60, s22
	s_addc_u32 s23, s61, s23
	s_and_b64 s[24:25], s[4:5], exec
	s_cselect_b32 s7, s23, s27
	s_cselect_b32 s21, s22, s26
	s_ashr_i32 s19, s18, 31
	s_lshl_b64 s[24:25], s[18:19], 20
	s_add_u32 s24, s68, s24
	s_addc_u32 s25, s69, s25
	s_and_b64 s[30:31], s[4:5], exec
	s_cselect_b32 s19, s25, s29
	s_cselect_b32 s33, s24, s28
	s_add_u32 s26, s26, 0x80080
	s_addc_u32 s27, s27, 0
	s_add_u32 s48, s28, 0x100
	s_addc_u32 s49, s29, 0
	s_mov_b32 s50, -2
	s_waitcnt lgkmcnt(0)
	s_waitcnt lgkmcnt(0)
	ds_read_b128 v[128:131], v181
	ds_read_b128 v[132:135], v181 offset:1024
	ds_read_b128 v[136:139], v181 offset:2048
	ds_read_b128 v[140:143], v181 offset:3072
	ds_read_b128 v[144:147], v182
	ds_read_b128 v[148:151], v182 offset:1024
	ds_read_b128 v[168:171], v182 offset:2048
	ds_read_b128 v[172:175], v182 offset:3072
	s_add_u32 s28, s26, 0xfff80080
	s_addc_u32 s29, s27, -1
	s_cmp_eq_u32 s50, 28
	s_cselect_b32 s31, s7, s29
	s_cselect_b32 s30, s21, s28
	s_cselect_b32 s29, s19, s49
	s_cselect_b32 s28, s33, s48
	s_add_i32 m0, s35, 0xc000
	ds_read_b128 v[186:189], v183
	ds_read_b128 v[190:193], v183 offset:1024
	ds_read_b128 v[198:201], v183 offset:2048
	ds_read_b128 v[202:205], v183 offset:3072
	ds_read_b128 v[206:209], v183 offset:4096
	ds_read_b128 v[210:213], v183 offset:5120
	ds_read_b128 v[214:217], v183 offset:6144
	ds_read_b128 v[218:221], v183 offset:7168
	global_load_lds_dwordx4 v160, s[26:27]
	s_add_i32 m0, s35, 0xe000
	s_nop 0
	global_load_lds_dwordx4 v162, s[26:27]
	s_waitcnt lgkmcnt(0)
	s_setprio 1
	s_barrier
	v_mfma_f32_16x16x32_bf16 v[124:127], v[128:131], v[186:189], 0
	v_mfma_f32_16x16x32_bf16 v[120:123], v[136:139], v[186:189], 0
	v_mfma_f32_16x16x32_bf16 v[104:107], v[128:131], v[198:201], 0
	v_mfma_f32_16x16x32_bf16 v[108:111], v[136:139], v[198:201], 0
	v_mfma_f32_16x16x32_bf16 v[88:91], v[128:131], v[206:209], 0
	v_mfma_f32_16x16x32_bf16 v[92:95], v[136:139], v[206:209], 0
	v_mfma_f32_16x16x32_bf16 v[72:75], v[128:131], v[214:217], 0
	v_mfma_f32_16x16x32_bf16 v[76:79], v[136:139], v[214:217], 0
	v_mfma_f32_16x16x32_bf16 v[124:127], v[132:135], v[190:193], v[124:127]
	v_mfma_f32_16x16x32_bf16 v[120:123], v[140:143], v[190:193], v[120:123]
	v_mfma_f32_16x16x32_bf16 v[104:107], v[132:135], v[202:205], v[104:107]
	v_mfma_f32_16x16x32_bf16 v[108:111], v[140:143], v[202:205], v[108:111]
	v_mfma_f32_16x16x32_bf16 v[88:91], v[132:135], v[210:213], v[88:91]
	v_mfma_f32_16x16x32_bf16 v[92:95], v[140:143], v[210:213], v[92:95]
	v_mfma_f32_16x16x32_bf16 v[72:75], v[132:135], v[218:221], v[72:75]
	v_mfma_f32_16x16x32_bf16 v[76:79], v[140:143], v[218:221], v[76:79]
	v_mfma_f32_16x16x32_bf16 v[116:119], v[144:147], v[186:189], 0
	v_mfma_f32_16x16x32_bf16 v[112:115], v[168:171], v[186:189], 0
	v_mfma_f32_16x16x32_bf16 v[100:103], v[144:147], v[198:201], 0
	v_mfma_f32_16x16x32_bf16 v[96:99], v[168:171], v[198:201], 0
	v_mfma_f32_16x16x32_bf16 v[84:87], v[144:147], v[206:209], 0
	v_mfma_f32_16x16x32_bf16 v[80:83], v[168:171], v[206:209], 0
	v_mfma_f32_16x16x32_bf16 v[68:71], v[144:147], v[214:217], 0
	v_mfma_f32_16x16x32_bf16 v[64:67], v[168:171], v[214:217], 0
	v_mfma_f32_16x16x32_bf16 v[116:119], v[148:151], v[190:193], v[116:119]
	v_mfma_f32_16x16x32_bf16 v[112:115], v[172:175], v[190:193], v[112:115]
	v_mfma_f32_16x16x32_bf16 v[100:103], v[148:151], v[202:205], v[100:103]
	v_mfma_f32_16x16x32_bf16 v[96:99], v[172:175], v[202:205], v[96:99]
	v_mfma_f32_16x16x32_bf16 v[84:87], v[148:151], v[210:213], v[84:87]
	v_mfma_f32_16x16x32_bf16 v[80:83], v[172:175], v[210:213], v[80:83]
	v_mfma_f32_16x16x32_bf16 v[68:71], v[148:151], v[218:221], v[68:71]
	v_mfma_f32_16x16x32_bf16 v[64:67], v[172:175], v[218:221], v[64:67]
	s_barrier
	s_setprio 0
	s_add_i32 s51, s62, s34
	v_lshl_add_u64 v[176:177], s[28:29], 0, v[154:155]
	s_mov_b32 m0, s51
	ds_read_b128 v[186:189], v183 offset:16384
	ds_read_b128 v[190:193], v183 offset:17408
	ds_read_b128 v[198:201], v183 offset:18432
	ds_read_b128 v[202:205], v183 offset:19456
	ds_read_b128 v[206:209], v183 offset:20480
	ds_read_b128 v[210:213], v183 offset:21504
	ds_read_b128 v[214:217], v183 offset:22528
	ds_read_b128 v[218:221], v183 offset:23552
	global_load_lds_dwordx4 v[176:177], off
	s_add_i32 m0, s51, 0x2000
	s_add_u32 s52, s28, 0x80000
	v_lshl_add_u64 v[194:195], s[28:29], 0, v[158:159]
	s_addc_u32 s53, s29, 0
	s_add_i32 s51, s63, s34
	global_load_lds_dwordx4 v[194:195], off
	s_mov_b32 m0, s51
	v_lshl_add_u64 v[224:225], s[30:31], 0, v[156:157]
	global_load_lds_dwordx4 v154, s[52:53]
	s_add_i32 m0, s51, 0x2000
	s_nop 0
	global_load_lds_dwordx4 v158, s[52:53]
	s_mov_b32 m0, s35
	v_lshl_add_u64 v[222:223], s[30:31], 0, v[152:153]
	global_load_lds_dwordx4 v[222:223], off
	s_mov_b32 m0, s37
	s_nop 0
	global_load_lds_dwordx4 v[224:225], off
	s_waitcnt lgkmcnt(0)
	s_setprio 1
	s_barrier
; #define PG8_STAGE(bufoff, gbase, voff) do { _Pragma("unroll") for (int _i = 0; _i < 2; ++_i) \
;         __builtin_amdgcn_global_load_lds((const unsigned*)((const char*)(gbase) + (voff)[_i]), (PG8_LAS unsigned*)(lds + (bufoff) + ldsw + _i * 8192), 16, 0, 0); } while (0)
; #define PG8_LDA(dst, b, h) do { _Pragma("unroll") for (int m = 0; m < 4; ++m) _Pragma("unroll") for (int k = 0; k < 2; ++k) dst[m][k] = *(const PG8_LAS bf16x8*)(lds + PG8_SA(b, h) + aoff + m * 2048 + k * 1024); } while (0)
; #define PG8_LDB(dst, b, h) do { _Pragma("unroll") for (int n = 0; n < 2; ++n) _Pragma("unroll") for (int k = 0; k < 2; ++k) dst[n][k] = *(const PG8_LAS bf16x8*)(lds + PG8_SB(b, h) + boff + n * 2048 + k * 1024); } while (0)
; #define PG8_MMA(ai, bj, At, Bt) do { __builtin_amdgcn_s_setprio(1); _Pragma("unroll") for (int m = 0; m < 4; ++m) _Pragma("unroll") for (int n = 0; n < 2; ++n) _Pragma("unroll") for (int k = 0; k < 2; ++k) \
;         acc[ai][bj][m][n] = __builtin_amdgcn_mfma_f32_16x16x32_bf16(Bt[n][k], At[m][k], acc[ai][bj][m][n], 0, 0, 0); __builtin_amdgcn_s_setprio(0); } while (0)
; #define PG8_WAIT_V(n) asm volatile("s_waitcnt vmcnt(" #n ")" ::: "memory")
; #define PG8_WAIT_L(n) asm volatile("s_waitcnt lgkmcnt(" #n ")" ::: "memory")
; #define PG8_BAR __builtin_amdgcn_s_barrier()
; #define PG8_SCHED __builtin_amdgcn_sched_barrier(0)
; template <class Epi, class Sched, bool ALIGN_EPI = false, bool SP2 = false>
; __device__ __forceinline__ void gemm_phase(PG8_LAS unsigned char* lds, const Gemm g, const Sched& S, const Epi& E) {
;     ...
;             PG8_WAIT_V(8); PG8_WAIT_L(0); PG8_BAR; PG8_MMA(1, 0, At, B0); PG8_MMA(1, 1, At, B1); PG8_BAR; PG8_SCHED;
;             PG8_LDB(B0, 1, 0); PG8_LDB(B1, 1, 1); PG8_SCHED; PG8_LDA(At, 1, 0); PG8_STAGE(PG8_SA(0, 1), a2 + hstep, voffA);
;             PG8_WAIT_V(8); PG8_WAIT_L(0); PG8_BAR; PG8_MMA(0, 0, At, B0); PG8_MMA(0, 1, At, B1); PG8_BAR; PG8_SCHED;
	v_mfma_f32_16x16x32_bf16 v[56:59], v[128:131], v[186:189], 0
	v_mfma_f32_16x16x32_bf16 v[60:63], v[136:139], v[186:189], 0
	v_mfma_f32_16x16x32_bf16 v[40:43], v[128:131], v[198:201], 0
	v_mfma_f32_16x16x32_bf16 v[44:47], v[136:139], v[198:201], 0
	v_mfma_f32_16x16x32_bf16 v[24:27], v[128:131], v[206:209], 0
	v_mfma_f32_16x16x32_bf16 v[28:31], v[136:139], v[206:209], 0
	v_mfma_f32_16x16x32_bf16 v[8:11], v[128:131], v[214:217], 0
	v_mfma_f32_16x16x32_bf16 v[12:15], v[136:139], v[214:217], 0
	v_mfma_f32_16x16x32_bf16 v[56:59], v[132:135], v[190:193], v[56:59]
	v_mfma_f32_16x16x32_bf16 v[60:63], v[140:143], v[190:193], v[60:63]
	v_mfma_f32_16x16x32_bf16 v[40:43], v[132:135], v[202:205], v[40:43]
	v_mfma_f32_16x16x32_bf16 v[44:47], v[140:143], v[202:205], v[44:47]
	v_mfma_f32_16x16x32_bf16 v[24:27], v[132:135], v[210:213], v[24:27]
	v_mfma_f32_16x16x32_bf16 v[28:31], v[140:143], v[210:213], v[28:31]
	v_mfma_f32_16x16x32_bf16 v[8:11], v[132:135], v[218:221], v[8:11]
	v_mfma_f32_16x16x32_bf16 v[12:15], v[140:143], v[218:221], v[12:15]
	v_mfma_f32_16x16x32_bf16 v[52:55], v[144:147], v[186:189], 0
	v_mfma_f32_16x16x32_bf16 v[48:51], v[168:171], v[186:189], 0
	v_mfma_f32_16x16x32_bf16 v[36:39], v[144:147], v[198:201], 0
	v_mfma_f32_16x16x32_bf16 v[32:35], v[168:171], v[198:201], 0
	v_mfma_f32_16x16x32_bf16 v[20:23], v[144:147], v[206:209], 0
	v_mfma_f32_16x16x32_bf16 v[16:19], v[168:171], v[206:209], 0
	v_mfma_f32_16x16x32_bf16 v[4:7], v[144:147], v[214:217], 0
	v_mfma_f32_16x16x32_bf16 v[0:3], v[168:171], v[214:217], 0
	v_mfma_f32_16x16x32_bf16 v[52:55], v[148:151], v[190:193], v[52:55]
	v_mfma_f32_16x16x32_bf16 v[48:51], v[172:175], v[190:193], v[48:51]
	v_mfma_f32_16x16x32_bf16 v[36:39], v[148:151], v[202:205], v[36:39]
	v_mfma_f32_16x16x32_bf16 v[32:35], v[172:175], v[202:205], v[32:35]
	v_mfma_f32_16x16x32_bf16 v[20:23], v[148:151], v[210:213], v[20:23]
	v_mfma_f32_16x16x32_bf16 v[16:19], v[172:175], v[210:213], v[16:19]
	v_mfma_f32_16x16x32_bf16 v[4:7], v[148:151], v[218:221], v[4:7]
	v_mfma_f32_16x16x32_bf16 v[0:3], v[172:175], v[218:221], v[0:3]
	s_barrier
	s_setprio 0
	s_add_i32 s51, 0, 0x18000
	s_add_i32 s52, 0, 0x1c000
	v_add_u32_e32 v140, s51, v179
	v_add_u32_e32 v172, s52, v179
	ds_read_b128 v[128:131], v140
	ds_read_b128 v[132:135], v140 offset:1024
	ds_read_b128 v[136:139], v140 offset:2048
	ds_read_b128 v[140:143], v140 offset:3072
	ds_read_b128 v[144:147], v172
	ds_read_b128 v[148:151], v172 offset:1024
	ds_read_b128 v[168:171], v172 offset:2048
	ds_read_b128 v[172:175], v172 offset:3072
	s_add_u32 s30, s30, 0x80000
	s_addc_u32 s31, s31, 0
	s_mov_b32 m0, s39
	ds_read_b128 v[186:189], v183 offset:32768
	ds_read_b128 v[190:193], v183 offset:33792
	ds_read_b128 v[198:201], v183 offset:34816
	ds_read_b128 v[202:205], v183 offset:35840
	ds_read_b128 v[206:209], v183 offset:36864
	ds_read_b128 v[210:213], v183 offset:37888
	ds_read_b128 v[214:217], v183 offset:38912
	ds_read_b128 v[218:221], v183 offset:39936
	global_load_lds_dwordx4 v152, s[30:31]
	s_mov_b32 m0, s42
	v_lshl_add_u64 v[226:227], s[30:31], 0, v[156:157]
	global_load_lds_dwordx4 v[226:227], off
	s_waitcnt vmcnt(8) lgkmcnt(0)
	s_setprio 1
	s_barrier
	v_mfma_f32_16x16x32_bf16 v[124:127], v[128:131], v[186:189], v[124:127]
	v_mfma_f32_16x16x32_bf16 v[120:123], v[136:139], v[186:189], v[120:123]
	v_mfma_f32_16x16x32_bf16 v[104:107], v[128:131], v[198:201], v[104:107]
	v_mfma_f32_16x16x32_bf16 v[108:111], v[136:139], v[198:201], v[108:111]
	v_mfma_f32_16x16x32_bf16 v[88:91], v[128:131], v[206:209], v[88:91]
	v_mfma_f32_16x16x32_bf16 v[92:95], v[136:139], v[206:209], v[92:95]
	v_mfma_f32_16x16x32_bf16 v[72:75], v[128:131], v[214:217], v[72:75]
	v_mfma_f32_16x16x32_bf16 v[76:79], v[136:139], v[214:217], v[76:79]
	v_mfma_f32_16x16x32_bf16 v[124:127], v[132:135], v[190:193], v[124:127]
	v_mfma_f32_16x16x32_bf16 v[120:123], v[140:143], v[190:193], v[120:123]
	v_mfma_f32_16x16x32_bf16 v[104:107], v[132:135], v[202:205], v[104:107]
	v_mfma_f32_16x16x32_bf16 v[108:111], v[140:143], v[202:205], v[108:111]
	v_mfma_f32_16x16x32_bf16 v[88:91], v[132:135], v[210:213], v[88:91]
	v_mfma_f32_16x16x32_bf16 v[92:95], v[140:143], v[210:213], v[92:95]
	v_mfma_f32_16x16x32_bf16 v[72:75], v[132:135], v[218:221], v[72:75]
	v_mfma_f32_16x16x32_bf16 v[76:79], v[140:143], v[218:221], v[76:79]
	v_mfma_f32_16x16x32_bf16 v[116:119], v[144:147], v[186:189], v[116:119]
	v_mfma_f32_16x16x32_bf16 v[112:115], v[168:171], v[186:189], v[112:115]
	v_mfma_f32_16x16x32_bf16 v[100:103], v[144:147], v[198:201], v[100:103]
	v_mfma_f32_16x16x32_bf16 v[96:99], v[168:171], v[198:201], v[96:99]
	v_mfma_f32_16x16x32_bf16 v[84:87], v[144:147], v[206:209], v[84:87]
	v_mfma_f32_16x16x32_bf16 v[80:83], v[168:171], v[206:209], v[80:83]
	v_mfma_f32_16x16x32_bf16 v[68:71], v[144:147], v[214:217], v[68:71]
	v_mfma_f32_16x16x32_bf16 v[64:67], v[168:171], v[214:217], v[64:67]
	v_mfma_f32_16x16x32_bf16 v[116:119], v[148:151], v[190:193], v[116:119]
	v_mfma_f32_16x16x32_bf16 v[112:115], v[172:175], v[190:193], v[112:115]
	v_mfma_f32_16x16x32_bf16 v[100:103], v[148:151], v[202:205], v[100:103]
	v_mfma_f32_16x16x32_bf16 v[96:99], v[172:175], v[202:205], v[96:99]
	v_mfma_f32_16x16x32_bf16 v[84:87], v[148:151], v[210:213], v[84:87]
	v_mfma_f32_16x16x32_bf16 v[80:83], v[172:175], v[210:213], v[80:83]
	v_mfma_f32_16x16x32_bf16 v[68:71], v[148:151], v[218:221], v[68:71]
	v_mfma_f32_16x16x32_bf16 v[64:67], v[172:175], v[218:221], v[64:67]
	s_barrier
; #define PG8_STAGE(bufoff, gbase, voff) do { _Pragma("unroll") for (int _i = 0; _i < 2; ++_i) \
;         __builtin_amdgcn_global_load_lds((const unsigned*)((const char*)(gbase) + (voff)[_i]), (PG8_LAS unsigned*)(lds + (bufoff) + ldsw + _i * 8192), 16, 0, 0); } while (0)
; #define PG8_LDA(dst, b, h) do { _Pragma("unroll") for (int m = 0; m < 4; ++m) _Pragma("unroll") for (int k = 0; k < 2; ++k) dst[m][k] = *(const PG8_LAS bf16x8*)(lds + PG8_SA(b, h) + aoff + m * 2048 + k * 1024); } while (0)
; #define PG8_MMA(ai, bj, At, Bt) do { __builtin_amdgcn_s_setprio(1); _Pragma("unroll") for (int m = 0; m < 4; ++m) _Pragma("unroll") for (int n = 0; n < 2; ++n) _Pragma("unroll") for (int k = 0; k < 2; ++k) \
;         acc[ai][bj][m][n] = __builtin_amdgcn_mfma_f32_16x16x32_bf16(Bt[n][k], At[m][k], acc[ai][bj][m][n], 0, 0, 0); __builtin_amdgcn_s_setprio(0); } while (0)
; #define PG8_WAIT_V(n) asm volatile("s_waitcnt vmcnt(" #n ")" ::: "memory")
; #define PG8_WAIT_L(n) asm volatile("s_waitcnt lgkmcnt(" #n ")" ::: "memory")
; #define PG8_BAR __builtin_amdgcn_s_barrier()
; #define PG8_SCHED __builtin_amdgcn_sched_barrier(0)
; template <class Epi, class Sched, bool ALIGN_EPI = false, bool SP2 = false>
; __device__ __forceinline__ void gemm_phase(PG8_LAS unsigned char* lds, const Gemm g, const Sched& S, const Epi& E) {
;     ...
;         for (int t = 0; t < nt; t += 2) {
;     ...
;             PG8_LDA(At, 1, 1); PG8_STAGE(PG8_SB(1, 0), b3, voffB); PG8_STAGE(PG8_SB(1, 1), b3 + hstep, voffB); PG8_STAGE(PG8_SA(1, 0), a3, voffA);
;             PG8_WAIT_V(8); PG8_WAIT_L(0); PG8_BAR; PG8_MMA(1, 0, At, B0); PG8_MMA(1, 1, At, B1); PG8_BAR; PG8_SCHED;
	s_setprio 0
	s_add_i32 s30, s51, s34
	v_lshl_add_u64 v[176:177], v[176:177], 0, s[12:13]
	s_mov_b32 m0, s30
	ds_read_b128 v[186:189], v183 offset:49152
	ds_read_b128 v[190:193], v183 offset:50176
	ds_read_b128 v[198:201], v183 offset:51200
	ds_read_b128 v[202:205], v183 offset:52224
	ds_read_b128 v[206:209], v183 offset:53248
	ds_read_b128 v[210:213], v183 offset:54272
	ds_read_b128 v[214:217], v183 offset:55296
	ds_read_b128 v[218:221], v183 offset:56320
	global_load_lds_dwordx4 v[176:177], off
	s_add_i32 m0, s30, 0x2000
	s_add_u32 s28, s28, 0x80080
	v_lshl_add_u64 v[176:177], v[194:195], 0, s[12:13]
	s_addc_u32 s29, s29, 0
	s_add_i32 s30, s52, s34
	global_load_lds_dwordx4 v[176:177], off
	s_mov_b32 m0, s30
	s_nop 0
	global_load_lds_dwordx4 v154, s[28:29]
	s_add_i32 m0, s30, 0x2000
	v_lshl_add_u64 v[176:177], s[28:29], 0, v[158:159]
	global_load_lds_dwordx4 v[176:177], off
	s_mov_b32 m0, s44
	v_lshl_add_u64 v[176:177], v[222:223], 0, s[12:13]
	global_load_lds_dwordx4 v[176:177], off
	s_mov_b32 m0, s45
	v_lshl_add_u64 v[176:177], v[224:225], 0, s[12:13]
	global_load_lds_dwordx4 v[176:177], off
	s_waitcnt vmcnt(8) lgkmcnt(0)
	s_setprio 1
	s_barrier
	v_mfma_f32_16x16x32_bf16 v[56:59], v[128:131], v[186:189], v[56:59]
	v_mfma_f32_16x16x32_bf16 v[60:63], v[136:139], v[186:189], v[60:63]
	v_mfma_f32_16x16x32_bf16 v[40:43], v[128:131], v[198:201], v[40:43]
	v_mfma_f32_16x16x32_bf16 v[44:47], v[136:139], v[198:201], v[44:47]
	v_mfma_f32_16x16x32_bf16 v[24:27], v[128:131], v[206:209], v[24:27]
	v_mfma_f32_16x16x32_bf16 v[28:31], v[136:139], v[206:209], v[28:31]
	v_mfma_f32_16x16x32_bf16 v[8:11], v[128:131], v[214:217], v[8:11]
	v_mfma_f32_16x16x32_bf16 v[12:15], v[136:139], v[214:217], v[12:15]
	v_mfma_f32_16x16x32_bf16 v[56:59], v[132:135], v[190:193], v[56:59]
	v_mfma_f32_16x16x32_bf16 v[60:63], v[140:143], v[190:193], v[60:63]
	v_mfma_f32_16x16x32_bf16 v[40:43], v[132:135], v[202:205], v[40:43]
	v_mfma_f32_16x16x32_bf16 v[44:47], v[140:143], v[202:205], v[44:47]
	v_mfma_f32_16x16x32_bf16 v[24:27], v[132:135], v[210:213], v[24:27]
	v_mfma_f32_16x16x32_bf16 v[28:31], v[140:143], v[210:213], v[28:31]
	v_mfma_f32_16x16x32_bf16 v[8:11], v[132:135], v[218:221], v[8:11]
	v_mfma_f32_16x16x32_bf16 v[12:15], v[140:143], v[218:221], v[12:15]
	v_mfma_f32_16x16x32_bf16 v[52:55], v[144:147], v[186:189], v[52:55]
	v_mfma_f32_16x16x32_bf16 v[48:51], v[168:171], v[186:189], v[48:51]
	v_mfma_f32_16x16x32_bf16 v[36:39], v[144:147], v[198:201], v[36:39]
	v_mfma_f32_16x16x32_bf16 v[32:35], v[168:171], v[198:201], v[32:35]
	v_mfma_f32_16x16x32_bf16 v[20:23], v[144:147], v[206:209], v[20:23]
	v_mfma_f32_16x16x32_bf16 v[16:19], v[168:171], v[206:209], v[16:19]
	v_mfma_f32_16x16x32_bf16 v[4:7], v[144:147], v[214:217], v[4:7]
	v_mfma_f32_16x16x32_bf16 v[0:3], v[168:171], v[214:217], v[0:3]
	v_mfma_f32_16x16x32_bf16 v[52:55], v[148:151], v[190:193], v[52:55]
	v_mfma_f32_16x16x32_bf16 v[48:51], v[172:175], v[190:193], v[48:51]
	v_mfma_f32_16x16x32_bf16 v[36:39], v[148:151], v[202:205], v[36:39]
	v_mfma_f32_16x16x32_bf16 v[32:35], v[172:175], v[202:205], v[32:35]
	v_mfma_f32_16x16x32_bf16 v[20:23], v[148:151], v[210:213], v[20:23]
	v_mfma_f32_16x16x32_bf16 v[16:19], v[172:175], v[210:213], v[16:19]
	v_mfma_f32_16x16x32_bf16 v[4:7], v[148:151], v[218:221], v[4:7]
	v_mfma_f32_16x16x32_bf16 v[0:3], v[172:175], v[218:221], v[0:3]
	s_barrier
	s_setprio 0
	s_add_i32 s50, s50, 2
	s_add_u32 s26, s26, 0x100
	s_addc_u32 s27, s27, 0
	s_add_u32 s48, s48, 0x100
	s_addc_u32 s49, s49, 0
	.p2align	6

; #define PG8_STAGE(bufoff, gbase, voff) do { _Pragma("unroll") for (int _i = 0; _i < 2; ++_i) \
;         __builtin_amdgcn_global_load_lds((const unsigned*)((const char*)(gbase) + (voff)[_i]), (PG8_LAS unsigned*)(lds + (bufoff) + ldsw + _i * 8192), 16, 0, 0); } while (0)
; #define PG8_LDA(dst, b, h) do { _Pragma("unroll") for (int m = 0; m < 4; ++m) _Pragma("unroll") for (int k = 0; k < 2; ++k) dst[m][k] = *(const PG8_LAS bf16x8*)(lds + PG8_SA(b, h) + aoff + m * 2048 + k * 1024); } while (0)
; #define PG8_LDB(dst, b, h) do { _Pragma("unroll") for (int n = 0; n < 2; ++n) _Pragma("unroll") for (int k = 0; k < 2; ++k) dst[n][k] = *(const PG8_LAS bf16x8*)(lds + PG8_SB(b, h) + boff + n * 2048 + k * 1024); } while (0)
; #define PG8_MMA(ai, bj, At, Bt) do { __builtin_amdgcn_s_setprio(1); _Pragma("unroll") for (int m = 0; m < 4; ++m) _Pragma("unroll") for (int n = 0; n < 2; ++n) _Pragma("unroll") for (int k = 0; k < 2; ++k) \
;         acc[ai][bj][m][n] = __builtin_amdgcn_mfma_f32_16x16x32_bf16(Bt[n][k], At[m][k], acc[ai][bj][m][n], 0, 0, 0); __builtin_amdgcn_s_setprio(0); } while (0)
; #define PG8_BAR __builtin_amdgcn_s_barrier()
; template <class Epi, class Sched, bool ALIGN_EPI = false, bool SP2 = false>
; __device__ __forceinline__ void gemm_phase(PG8_LAS unsigned char* lds, const Gemm g, const Sched& S, const Epi& E) {
;     ...
;         const bool has_next = S.next(ui + 1, nxt);
;         const char* nA = has_next ? (const char*)g.A + (size_t)nxt.pm * tstep : cA; const char* nB = has_next ? (const char*)g.Bt + (size_t)nxt.pn * tstep : cB;
;         for (int t = 0; t < nt; t += 2) {
;             const bool last = (t == nt - 2);
;             const char* a1 = cA + (size_t)(t + 1) * kstep;
;             const char* a2 = last ? nA : cA + (size_t)(t + 2) * kstep; const char* b2 = last ? nB : cB + (size_t)(t + 2) * kstep;
;             const char* a3 = a2 + kstep; const char* b3 = b2 + kstep;
;             if (last && has_next) S.a_ready(nxt);
;             if constexpr (SP2) {
;             PG8_LDB(B0, 0, 0); PG8_LDB(B1, 0, 1); PG8_SCHED; PG8_LDA(At, 0, 0); PG8_STAGE(PG8_SA(1, 1), a1 + hstep, voffA);
;             PG8_WAIT_V(8); PG8_WAIT_L(0); PG8_BAR; PG8_MMA(0, 0, At, B0); PG8_MMA(0, 1, At, B1); PG8_BAR; PG8_SCHED;
;             PG8_LDA(At, 0, 1); PG8_STAGE(PG8_SB(0, 0), b2, voffB); PG8_STAGE(PG8_SB(0, 1), b2 + hstep, voffB); PG8_STAGE(PG8_SA(0, 0), a2, voffA);
.LBB0_490:
	s_ashr_i32 s21, s20, 31
	s_lshl_b64 s[0:1], s[20:21], 20
	v_readlane_b32 s24, v254, 51
	v_readlane_b32 s25, v254, 52
	s_add_u32 s24, s24, s0
	s_addc_u32 s25, s25, s1
	s_and_b64 s[0:1], s[22:23], exec
	s_cselect_b32 s5, s25, s31
	s_cselect_b32 s21, s24, s30
	s_ashr_i32 s19, s18, 31
	s_lshl_b64 s[0:1], s[18:19], 20
	v_readlane_b32 s26, v254, 22
	v_readlane_b32 s27, v254, 23
	s_add_u32 s26, s26, s0
	s_addc_u32 s27, s27, s1
	s_and_b64 s[0:1], s[22:23], exec
	s_cselect_b32 s19, s27, s29
	s_cselect_b32 s33, s26, s28
	s_add_u32 s0, s30, 0x80080
	s_addc_u32 s1, s31, 0
	s_add_u32 s44, s28, 0x100
	s_addc_u32 s45, s29, 0
	s_mov_b32 s48, -2
	v_add_u32_e32 v140, s68, v163
	v_add_u32_e32 v152, s69, v163
	ds_read_b128 v[128:131], v140
	ds_read_b128 v[132:135], v140 offset:1024
	ds_read_b128 v[136:139], v140 offset:2048
	ds_read_b128 v[140:143], v140 offset:3072
	ds_read_b128 v[184:187], v152
	ds_read_b128 v[218:221], v152 offset:1024
	ds_read_b128 v[222:225], v152 offset:2048
	ds_read_b128 v[226:229], v152 offset:3072
	s_add_u32 s28, s0, 0xfff80080
	s_addc_u32 s29, s1, -1
	s_cmp_eq_u32 s48, 28
	s_cselect_b32 s31, s5, s29
	s_cselect_b32 s30, s21, s28
	s_cselect_b32 s29, s19, s45
	s_cselect_b32 s28, s33, s44
	s_add_i32 m0, s17, 0xc000
	ds_read_b128 v[230:233], v214
	ds_read_b128 v[234:237], v214 offset:1024
	ds_read_b128 v[238:241], v214 offset:2048
	ds_read_b128 v[242:245], v214 offset:3072
	ds_read_b128 v[246:249], v214 offset:4096
	ds_read_b128 v[250:253], v214 offset:5120
	ds_read_b128 v[206:209], v214 offset:6144
	ds_read_b128 v[210:213], v214 offset:7168
	global_load_lds_dwordx4 v156, s[0:1]
	s_add_i32 m0, s17, 0xe000
	s_nop 0
	global_load_lds_dwordx4 v158, s[0:1]
	s_waitcnt lgkmcnt(0)
	s_setprio 1
	s_barrier
	v_mfma_f32_16x16x32_bf16 v[124:127], v[128:131], v[230:233], 0
	v_mfma_f32_16x16x32_bf16 v[120:123], v[136:139], v[230:233], 0
	v_mfma_f32_16x16x32_bf16 v[116:119], v[128:131], v[238:241], 0
	v_mfma_f32_16x16x32_bf16 v[108:111], v[136:139], v[238:241], 0
	v_mfma_f32_16x16x32_bf16 v[100:103], v[128:131], v[246:249], 0
	v_mfma_f32_16x16x32_bf16 v[92:95], v[136:139], v[246:249], 0
	v_mfma_f32_16x16x32_bf16 v[84:87], v[128:131], v[206:209], 0
	v_mfma_f32_16x16x32_bf16 v[76:79], v[136:139], v[206:209], 0
	v_mfma_f32_16x16x32_bf16 v[124:127], v[132:135], v[234:237], v[124:127]
	v_mfma_f32_16x16x32_bf16 v[120:123], v[140:143], v[234:237], v[120:123]
	v_mfma_f32_16x16x32_bf16 v[116:119], v[132:135], v[242:245], v[116:119]
	v_mfma_f32_16x16x32_bf16 v[108:111], v[140:143], v[242:245], v[108:111]
	v_mfma_f32_16x16x32_bf16 v[100:103], v[132:135], v[250:253], v[100:103]
	v_mfma_f32_16x16x32_bf16 v[92:95], v[140:143], v[250:253], v[92:95]
	v_mfma_f32_16x16x32_bf16 v[84:87], v[132:135], v[210:213], v[84:87]
	v_mfma_f32_16x16x32_bf16 v[76:79], v[140:143], v[210:213], v[76:79]
	v_mfma_f32_16x16x32_bf16 v[112:115], v[184:187], v[230:233], 0
	v_mfma_f32_16x16x32_bf16 v[104:107], v[222:225], v[230:233], 0
	v_mfma_f32_16x16x32_bf16 v[96:99], v[184:187], v[238:241], 0
	v_mfma_f32_16x16x32_bf16 v[88:91], v[222:225], v[238:241], 0
	v_mfma_f32_16x16x32_bf16 v[80:83], v[184:187], v[246:249], 0
	v_mfma_f32_16x16x32_bf16 v[72:75], v[222:225], v[246:249], 0
	v_mfma_f32_16x16x32_bf16 v[68:71], v[184:187], v[206:209], 0
	v_mfma_f32_16x16x32_bf16 v[64:67], v[222:225], v[206:209], 0
	v_mfma_f32_16x16x32_bf16 v[112:115], v[218:221], v[234:237], v[112:115]
	v_mfma_f32_16x16x32_bf16 v[104:107], v[226:229], v[234:237], v[104:107]
	v_mfma_f32_16x16x32_bf16 v[96:99], v[218:221], v[242:245], v[96:99]
	v_mfma_f32_16x16x32_bf16 v[88:91], v[226:229], v[242:245], v[88:91]
	v_mfma_f32_16x16x32_bf16 v[80:83], v[218:221], v[250:253], v[80:83]
	v_mfma_f32_16x16x32_bf16 v[72:75], v[226:229], v[250:253], v[72:75]
	v_mfma_f32_16x16x32_bf16 v[68:71], v[218:221], v[210:213], v[68:71]
	v_mfma_f32_16x16x32_bf16 v[64:67], v[226:229], v[210:213], v[64:67]
	s_barrier
	s_setprio 0
	s_add_i32 s49, s68, s34
	v_lshl_add_u64 v[172:173], s[28:29], 0, v[146:147]
	s_mov_b32 m0, s49
	ds_read_b128 v[206:209], v214 offset:16384
	ds_read_b128 v[210:213], v214 offset:17408
	ds_read_b128 v[230:233], v214 offset:18432
	ds_read_b128 v[234:237], v214 offset:19456
	ds_read_b128 v[238:241], v214 offset:20480
	ds_read_b128 v[242:245], v214 offset:21504
	ds_read_b128 v[246:249], v214 offset:22528
	ds_read_b128 v[250:253], v214 offset:23552
	global_load_lds_dwordx4 v[172:173], off
	s_add_i32 m0, s49, 0x2000
	s_add_u32 s50, s28, 0x80000
	v_lshl_add_u64 v[176:177], s[28:29], 0, v[150:151]
	s_addc_u32 s51, s29, 0
	s_add_i32 s49, s69, s34
	global_load_lds_dwordx4 v[176:177], off
	s_mov_b32 m0, s49
	v_lshl_add_u64 v[188:189], s[30:31], 0, v[148:149]
	global_load_lds_dwordx4 v146, s[50:51]
	s_add_i32 m0, s49, 0x2000
	s_nop 0
	global_load_lds_dwordx4 v150, s[50:51]
	s_mov_b32 m0, s17
	v_lshl_add_u64 v[180:181], s[30:31], 0, v[144:145]
	global_load_lds_dwordx4 v[180:181], off
	s_mov_b32 m0, s35
	s_nop 0
	global_load_lds_dwordx4 v[188:189], off
	s_waitcnt lgkmcnt(0)
	s_setprio 1
	s_barrier
; #define PG8_STAGE(bufoff, gbase, voff) do { _Pragma("unroll") for (int _i = 0; _i < 2; ++_i) \
;         __builtin_amdgcn_global_load_lds((const unsigned*)((const char*)(gbase) + (voff)[_i]), (PG8_LAS unsigned*)(lds + (bufoff) + ldsw + _i * 8192), 16, 0, 0); } while (0)
; #define PG8_LDA(dst, b, h) do { _Pragma("unroll") for (int m = 0; m < 4; ++m) _Pragma("unroll") for (int k = 0; k < 2; ++k) dst[m][k] = *(const PG8_LAS bf16x8*)(lds + PG8_SA(b, h) + aoff + m * 2048 + k * 1024); } while (0)
; #define PG8_LDB(dst, b, h) do { _Pragma("unroll") for (int n = 0; n < 2; ++n) _Pragma("unroll") for (int k = 0; k < 2; ++k) dst[n][k] = *(const PG8_LAS bf16x8*)(lds + PG8_SB(b, h) + boff + n * 2048 + k * 1024); } while (0)
; #define PG8_MMA(ai, bj, At, Bt) do { __builtin_amdgcn_s_setprio(1); _Pragma("unroll") for (int m = 0; m < 4; ++m) _Pragma("unroll") for (int n = 0; n < 2; ++n) _Pragma("unroll") for (int k = 0; k < 2; ++k) \
;         acc[ai][bj][m][n] = __builtin_amdgcn_mfma_f32_16x16x32_bf16(Bt[n][k], At[m][k], acc[ai][bj][m][n], 0, 0, 0); __builtin_amdgcn_s_setprio(0); } while (0)
; #define PG8_WAIT_V(n) asm volatile("s_waitcnt vmcnt(" #n ")" ::: "memory")
; #define PG8_WAIT_L(n) asm volatile("s_waitcnt lgkmcnt(" #n ")" ::: "memory")
; #define PG8_BAR __builtin_amdgcn_s_barrier()
; #define PG8_SCHED __builtin_amdgcn_sched_barrier(0)
; template <class Epi, class Sched, bool ALIGN_EPI = false, bool SP2 = false>
; __device__ __forceinline__ void gemm_phase(PG8_LAS unsigned char* lds, const Gemm g, const Sched& S, const Epi& E) {
;     ...
;             PG8_WAIT_V(8); PG8_WAIT_L(0); PG8_BAR; PG8_MMA(1, 0, At, B0); PG8_MMA(1, 1, At, B1); PG8_BAR; PG8_SCHED;
;             PG8_LDB(B0, 1, 0); PG8_LDB(B1, 1, 1); PG8_SCHED; PG8_LDA(At, 1, 0); PG8_STAGE(PG8_SA(0, 1), a2 + hstep, voffA);
;             PG8_WAIT_V(8); PG8_WAIT_L(0); PG8_BAR; PG8_MMA(0, 0, At, B0); PG8_MMA(0, 1, At, B1); PG8_BAR; PG8_SCHED;
	v_mfma_f32_16x16x32_bf16 v[60:63], v[128:131], v[206:209], 0
	v_mfma_f32_16x16x32_bf16 v[56:59], v[136:139], v[206:209], 0
	v_mfma_f32_16x16x32_bf16 v[52:55], v[128:131], v[230:233], 0
	v_mfma_f32_16x16x32_bf16 v[44:47], v[136:139], v[230:233], 0
	v_mfma_f32_16x16x32_bf16 v[36:39], v[128:131], v[238:241], 0
	v_mfma_f32_16x16x32_bf16 v[28:31], v[136:139], v[238:241], 0
	v_mfma_f32_16x16x32_bf16 v[20:23], v[128:131], v[246:249], 0
	v_mfma_f32_16x16x32_bf16 v[12:15], v[136:139], v[246:249], 0
	v_mfma_f32_16x16x32_bf16 v[60:63], v[132:135], v[210:213], v[60:63]
	v_mfma_f32_16x16x32_bf16 v[56:59], v[140:143], v[210:213], v[56:59]
	v_mfma_f32_16x16x32_bf16 v[52:55], v[132:135], v[234:237], v[52:55]
	v_mfma_f32_16x16x32_bf16 v[44:47], v[140:143], v[234:237], v[44:47]
	v_mfma_f32_16x16x32_bf16 v[36:39], v[132:135], v[242:245], v[36:39]
	v_mfma_f32_16x16x32_bf16 v[28:31], v[140:143], v[242:245], v[28:31]
	v_mfma_f32_16x16x32_bf16 v[20:23], v[132:135], v[250:253], v[20:23]
	v_mfma_f32_16x16x32_bf16 v[12:15], v[140:143], v[250:253], v[12:15]
	v_mfma_f32_16x16x32_bf16 v[48:51], v[184:187], v[206:209], 0
	v_mfma_f32_16x16x32_bf16 v[40:43], v[222:225], v[206:209], 0
	v_mfma_f32_16x16x32_bf16 v[32:35], v[184:187], v[230:233], 0
	v_mfma_f32_16x16x32_bf16 v[24:27], v[222:225], v[230:233], 0
	v_mfma_f32_16x16x32_bf16 v[16:19], v[184:187], v[238:241], 0
	v_mfma_f32_16x16x32_bf16 v[8:11], v[222:225], v[238:241], 0
	v_mfma_f32_16x16x32_bf16 v[4:7], v[184:187], v[246:249], 0
	v_mfma_f32_16x16x32_bf16 v[0:3], v[222:225], v[246:249], 0
	v_mfma_f32_16x16x32_bf16 v[48:51], v[218:221], v[210:213], v[48:51]
	v_mfma_f32_16x16x32_bf16 v[40:43], v[226:229], v[210:213], v[40:43]
	v_mfma_f32_16x16x32_bf16 v[32:35], v[218:221], v[234:237], v[32:35]
	v_mfma_f32_16x16x32_bf16 v[24:27], v[226:229], v[234:237], v[24:27]
	v_mfma_f32_16x16x32_bf16 v[16:19], v[218:221], v[242:245], v[16:19]
	v_mfma_f32_16x16x32_bf16 v[8:11], v[226:229], v[242:245], v[8:11]
	v_mfma_f32_16x16x32_bf16 v[4:7], v[218:221], v[250:253], v[4:7]
	v_mfma_f32_16x16x32_bf16 v[0:3], v[226:229], v[250:253], v[0:3]
	s_barrier
	s_setprio 0
	s_add_i32 s49, 0, 0x18000
	s_add_i32 s50, 0, 0x1c000
	v_add_u32_e32 v140, s49, v163
	v_add_u32_e32 v152, s50, v163
	ds_read_b128 v[128:131], v140
	ds_read_b128 v[132:135], v140 offset:1024
	ds_read_b128 v[136:139], v140 offset:2048
	ds_read_b128 v[140:143], v140 offset:3072
	ds_read_b128 v[184:187], v152
	ds_read_b128 v[206:209], v152 offset:1024
	ds_read_b128 v[210:213], v152 offset:2048
	ds_read_b128 v[218:221], v152 offset:3072
	s_add_u32 s30, s30, 0x80000
	s_addc_u32 s31, s31, 0
	s_mov_b32 m0, s37
	ds_read_b128 v[222:225], v214 offset:32768
	ds_read_b128 v[226:229], v214 offset:33792
	ds_read_b128 v[230:233], v214 offset:34816
	ds_read_b128 v[234:237], v214 offset:35840
	ds_read_b128 v[238:241], v214 offset:36864
	ds_read_b128 v[242:245], v214 offset:37888
	ds_read_b128 v[246:249], v214 offset:38912
	ds_read_b128 v[250:253], v214 offset:39936
	global_load_lds_dwordx4 v144, s[30:31]
	s_mov_b32 m0, s39
	v_lshl_add_u64 v[216:217], s[30:31], 0, v[148:149]
	global_load_lds_dwordx4 v[216:217], off
	s_waitcnt vmcnt(8) lgkmcnt(0)
	s_setprio 1
	s_barrier
	v_mfma_f32_16x16x32_bf16 v[124:127], v[128:131], v[222:225], v[124:127]
	v_mfma_f32_16x16x32_bf16 v[120:123], v[136:139], v[222:225], v[120:123]
	v_mfma_f32_16x16x32_bf16 v[116:119], v[128:131], v[230:233], v[116:119]
	v_mfma_f32_16x16x32_bf16 v[108:111], v[136:139], v[230:233], v[108:111]
	v_mfma_f32_16x16x32_bf16 v[100:103], v[128:131], v[238:241], v[100:103]
	v_mfma_f32_16x16x32_bf16 v[92:95], v[136:139], v[238:241], v[92:95]
	v_mfma_f32_16x16x32_bf16 v[84:87], v[128:131], v[246:249], v[84:87]
	v_mfma_f32_16x16x32_bf16 v[76:79], v[136:139], v[246:249], v[76:79]
	v_mfma_f32_16x16x32_bf16 v[124:127], v[132:135], v[226:229], v[124:127]
	v_mfma_f32_16x16x32_bf16 v[120:123], v[140:143], v[226:229], v[120:123]
	v_mfma_f32_16x16x32_bf16 v[116:119], v[132:135], v[234:237], v[116:119]
	v_mfma_f32_16x16x32_bf16 v[108:111], v[140:143], v[234:237], v[108:111]
	v_mfma_f32_16x16x32_bf16 v[100:103], v[132:135], v[242:245], v[100:103]
	v_mfma_f32_16x16x32_bf16 v[92:95], v[140:143], v[242:245], v[92:95]
	v_mfma_f32_16x16x32_bf16 v[84:87], v[132:135], v[250:253], v[84:87]
	v_mfma_f32_16x16x32_bf16 v[76:79], v[140:143], v[250:253], v[76:79]
	v_mfma_f32_16x16x32_bf16 v[112:115], v[184:187], v[222:225], v[112:115]
	v_mfma_f32_16x16x32_bf16 v[104:107], v[210:213], v[222:225], v[104:107]
	v_mfma_f32_16x16x32_bf16 v[96:99], v[184:187], v[230:233], v[96:99]
	v_mfma_f32_16x16x32_bf16 v[88:91], v[210:213], v[230:233], v[88:91]
	v_mfma_f32_16x16x32_bf16 v[80:83], v[184:187], v[238:241], v[80:83]
	v_mfma_f32_16x16x32_bf16 v[72:75], v[210:213], v[238:241], v[72:75]
	v_mfma_f32_16x16x32_bf16 v[68:71], v[184:187], v[246:249], v[68:71]
	v_mfma_f32_16x16x32_bf16 v[64:67], v[210:213], v[246:249], v[64:67]
	v_mfma_f32_16x16x32_bf16 v[112:115], v[206:209], v[226:229], v[112:115]
	v_mfma_f32_16x16x32_bf16 v[104:107], v[218:221], v[226:229], v[104:107]
	v_mfma_f32_16x16x32_bf16 v[96:99], v[206:209], v[234:237], v[96:99]
	v_mfma_f32_16x16x32_bf16 v[88:91], v[218:221], v[234:237], v[88:91]
	v_mfma_f32_16x16x32_bf16 v[80:83], v[206:209], v[242:245], v[80:83]
	v_mfma_f32_16x16x32_bf16 v[72:75], v[218:221], v[242:245], v[72:75]
	v_mfma_f32_16x16x32_bf16 v[68:71], v[206:209], v[250:253], v[68:71]
	v_mfma_f32_16x16x32_bf16 v[64:67], v[218:221], v[250:253], v[64:67]
	s_barrier
; #define PG8_STAGE(bufoff, gbase, voff) do { _Pragma("unroll") for (int _i = 0; _i < 2; ++_i) \
;         __builtin_amdgcn_global_load_lds((const unsigned*)((const char*)(gbase) + (voff)[_i]), (PG8_LAS unsigned*)(lds + (bufoff) + ldsw + _i * 8192), 16, 0, 0); } while (0)
; #define PG8_LDA(dst, b, h) do { _Pragma("unroll") for (int m = 0; m < 4; ++m) _Pragma("unroll") for (int k = 0; k < 2; ++k) dst[m][k] = *(const PG8_LAS bf16x8*)(lds + PG8_SA(b, h) + aoff + m * 2048 + k * 1024); } while (0)
; #define PG8_MMA(ai, bj, At, Bt) do { __builtin_amdgcn_s_setprio(1); _Pragma("unroll") for (int m = 0; m < 4; ++m) _Pragma("unroll") for (int n = 0; n < 2; ++n) _Pragma("unroll") for (int k = 0; k < 2; ++k) \
;         acc[ai][bj][m][n] = __builtin_amdgcn_mfma_f32_16x16x32_bf16(Bt[n][k], At[m][k], acc[ai][bj][m][n], 0, 0, 0); __builtin_amdgcn_s_setprio(0); } while (0)
; #define PG8_WAIT_V(n) asm volatile("s_waitcnt vmcnt(" #n ")" ::: "memory")
; #define PG8_WAIT_L(n) asm volatile("s_waitcnt lgkmcnt(" #n ")" ::: "memory")
; #define PG8_BAR __builtin_amdgcn_s_barrier()
; #define PG8_SCHED __builtin_amdgcn_sched_barrier(0)
; template <class Epi, class Sched, bool ALIGN_EPI = false, bool SP2 = false>
; __device__ __forceinline__ void gemm_phase(PG8_LAS unsigned char* lds, const Gemm g, const Sched& S, const Epi& E) {
;     ...
;         for (int t = 0; t < nt; t += 2) {
;     ...
;             PG8_LDA(At, 1, 1); PG8_STAGE(PG8_SB(1, 0), b3, voffB); PG8_STAGE(PG8_SB(1, 1), b3 + hstep, voffB); PG8_STAGE(PG8_SA(1, 0), a3, voffA);
;             PG8_WAIT_V(8); PG8_WAIT_L(0); PG8_BAR; PG8_MMA(1, 0, At, B0); PG8_MMA(1, 1, At, B1); PG8_BAR; PG8_SCHED;
	s_setprio 0
	s_add_i32 s30, s49, s34
	v_lshl_add_u64 v[172:173], v[172:173], 0, s[10:11]
	s_mov_b32 m0, s30
	ds_read_b128 v[222:225], v214 offset:49152
	ds_read_b128 v[226:229], v214 offset:50176
	ds_read_b128 v[230:233], v214 offset:51200
	ds_read_b128 v[234:237], v214 offset:52224
	ds_read_b128 v[238:241], v214 offset:53248
	ds_read_b128 v[242:245], v214 offset:54272
	ds_read_b128 v[246:249], v214 offset:55296
	ds_read_b128 v[250:253], v214 offset:56320
	global_load_lds_dwordx4 v[172:173], off
	s_add_i32 m0, s30, 0x2000
	s_add_u32 s28, s28, 0x80080
	v_lshl_add_u64 v[172:173], v[176:177], 0, s[10:11]
	s_addc_u32 s29, s29, 0
	s_add_i32 s30, s50, s34
	global_load_lds_dwordx4 v[172:173], off
	s_mov_b32 m0, s30
	s_nop 0
	global_load_lds_dwordx4 v146, s[28:29]
	s_add_i32 m0, s30, 0x2000
	v_lshl_add_u64 v[172:173], s[28:29], 0, v[150:151]
	global_load_lds_dwordx4 v[172:173], off
	s_mov_b32 m0, s43
	v_lshl_add_u64 v[172:173], v[180:181], 0, s[10:11]
	global_load_lds_dwordx4 v[172:173], off
	s_mov_b32 m0, s46
	v_lshl_add_u64 v[172:173], v[188:189], 0, s[10:11]
	global_load_lds_dwordx4 v[172:173], off
	s_waitcnt vmcnt(8) lgkmcnt(0)
	s_setprio 1
	s_barrier
	v_mfma_f32_16x16x32_bf16 v[60:63], v[128:131], v[222:225], v[60:63]
	v_mfma_f32_16x16x32_bf16 v[56:59], v[136:139], v[222:225], v[56:59]
	v_mfma_f32_16x16x32_bf16 v[52:55], v[128:131], v[230:233], v[52:55]
	v_mfma_f32_16x16x32_bf16 v[44:47], v[136:139], v[230:233], v[44:47]
	v_mfma_f32_16x16x32_bf16 v[36:39], v[128:131], v[238:241], v[36:39]
	v_mfma_f32_16x16x32_bf16 v[28:31], v[136:139], v[238:241], v[28:31]
	v_mfma_f32_16x16x32_bf16 v[20:23], v[128:131], v[246:249], v[20:23]
	v_mfma_f32_16x16x32_bf16 v[12:15], v[136:139], v[246:249], v[12:15]
	v_mfma_f32_16x16x32_bf16 v[60:63], v[132:135], v[226:229], v[60:63]
	v_mfma_f32_16x16x32_bf16 v[56:59], v[140:143], v[226:229], v[56:59]
	v_mfma_f32_16x16x32_bf16 v[52:55], v[132:135], v[234:237], v[52:55]
	v_mfma_f32_16x16x32_bf16 v[44:47], v[140:143], v[234:237], v[44:47]
	v_mfma_f32_16x16x32_bf16 v[36:39], v[132:135], v[242:245], v[36:39]
	v_mfma_f32_16x16x32_bf16 v[28:31], v[140:143], v[242:245], v[28:31]
	v_mfma_f32_16x16x32_bf16 v[20:23], v[132:135], v[250:253], v[20:23]
	v_mfma_f32_16x16x32_bf16 v[12:15], v[140:143], v[250:253], v[12:15]
	v_mfma_f32_16x16x32_bf16 v[48:51], v[184:187], v[222:225], v[48:51]
	v_mfma_f32_16x16x32_bf16 v[40:43], v[210:213], v[222:225], v[40:43]
	v_mfma_f32_16x16x32_bf16 v[32:35], v[184:187], v[230:233], v[32:35]
	v_mfma_f32_16x16x32_bf16 v[24:27], v[210:213], v[230:233], v[24:27]
	v_mfma_f32_16x16x32_bf16 v[16:19], v[184:187], v[238:241], v[16:19]
	v_mfma_f32_16x16x32_bf16 v[8:11], v[210:213], v[238:241], v[8:11]
	v_mfma_f32_16x16x32_bf16 v[4:7], v[184:187], v[246:249], v[4:7]
	v_mfma_f32_16x16x32_bf16 v[0:3], v[210:213], v[246:249], v[0:3]
	v_mfma_f32_16x16x32_bf16 v[48:51], v[206:209], v[226:229], v[48:51]
	v_mfma_f32_16x16x32_bf16 v[40:43], v[218:221], v[226:229], v[40:43]
	v_mfma_f32_16x16x32_bf16 v[32:35], v[206:209], v[234:237], v[32:35]
	v_mfma_f32_16x16x32_bf16 v[24:27], v[218:221], v[234:237], v[24:27]
	v_mfma_f32_16x16x32_bf16 v[16:19], v[206:209], v[242:245], v[16:19]
	v_mfma_f32_16x16x32_bf16 v[8:11], v[218:221], v[242:245], v[8:11]
	v_mfma_f32_16x16x32_bf16 v[4:7], v[206:209], v[250:253], v[4:7]
	v_mfma_f32_16x16x32_bf16 v[0:3], v[218:221], v[250:253], v[0:3]
	s_barrier
	s_setprio 0
	s_add_i32 s48, s48, 2
	s_add_u32 s0, s0, 0x100
	s_addc_u32 s1, s1, 0
	s_add_u32 s44, s44, 0x100
	s_addc_u32 s45, s45, 0
	.p2align	6

; #define PG8_STAGE(bufoff, gbase, voff) do { _Pragma("unroll") for (int _i = 0; _i < 2; ++_i) \
;         __builtin_amdgcn_global_load_lds((const unsigned*)((const char*)(gbase) + (voff)[_i]), (PG8_LAS unsigned*)(lds + (bufoff) + ldsw + _i * 8192), 16, 0, 0); } while (0)
; #define PG8_LDA(dst, b, h) do { _Pragma("unroll") for (int m = 0; m < 4; ++m) _Pragma("unroll") for (int k = 0; k < 2; ++k) dst[m][k] = *(const PG8_LAS bf16x8*)(lds + PG8_SA(b, h) + aoff + m * 2048 + k * 1024); } while (0)
; #define PG8_LDB(dst, b, h) do { _Pragma("unroll") for (int n = 0; n < 2; ++n) _Pragma("unroll") for (int k = 0; k < 2; ++k) dst[n][k] = *(const PG8_LAS bf16x8*)(lds + PG8_SB(b, h) + boff + n * 2048 + k * 1024); } while (0)
; #define PG8_MMA(ai, bj, At, Bt) do { __builtin_amdgcn_s_setprio(1); _Pragma("unroll") for (int m = 0; m < 4; ++m) _Pragma("unroll") for (int n = 0; n < 2; ++n) _Pragma("unroll") for (int k = 0; k < 2; ++k) \
;         acc[ai][bj][m][n] = __builtin_amdgcn_mfma_f32_16x16x32_bf16(Bt[n][k], At[m][k], acc[ai][bj][m][n], 0, 0, 0); __builtin_amdgcn_s_setprio(0); } while (0)
; #define PG8_BAR __builtin_amdgcn_s_barrier()
; template <class Epi, class Sched, bool ALIGN_EPI = false, bool SP2 = false>
; __device__ __forceinline__ void gemm_phase(PG8_LAS unsigned char* lds, const Gemm g, const Sched& S, const Epi& E) {
;     ...
;         const bool has_next = S.next(ui + 1, nxt);
;         const char* nA = has_next ? (const char*)g.A + (size_t)nxt.pm * tstep : cA; const char* nB = has_next ? (const char*)g.Bt + (size_t)nxt.pn * tstep : cB;
;         for (int t = 0; t < nt; t += 2) {
;             const bool last = (t == nt - 2);
;             const char* a1 = cA + (size_t)(t + 1) * kstep;
;             const char* a2 = last ? nA : cA + (size_t)(t + 2) * kstep; const char* b2 = last ? nB : cB + (size_t)(t + 2) * kstep;
;             const char* a3 = a2 + kstep; const char* b3 = b2 + kstep;
;             if (last && has_next) S.a_ready(nxt);
;             if constexpr (SP2) {
;             PG8_LDB(B0, 0, 0); PG8_LDB(B1, 0, 1); PG8_SCHED; PG8_LDA(At, 0, 0); PG8_STAGE(PG8_SA(1, 1), a1 + hstep, voffA);
;             PG8_WAIT_V(8); PG8_WAIT_L(0); PG8_BAR; PG8_MMA(0, 0, At, B0); PG8_MMA(0, 1, At, B1); PG8_BAR; PG8_SCHED;
;             PG8_LDA(At, 0, 1); PG8_STAGE(PG8_SB(0, 0), b2, voffB); PG8_STAGE(PG8_SB(0, 1), b2 + hstep, voffB); PG8_STAGE(PG8_SA(0, 0), a2, voffA);
.LBB0_762:
	s_ashr_i32 s21, s20, 31
	s_lshl_b64 s[22:23], s[20:21], 21
	s_add_u32 s22, s60, s22
	s_addc_u32 s23, s61, s23
	s_and_b64 s[24:25], s[4:5], exec
	s_cselect_b32 s7, s23, s27
	s_cselect_b32 s21, s22, s26
	s_ashr_i32 s19, s18, 31
	s_lshl_b64 s[24:25], s[18:19], 21
	v_readlane_b32 s30, v254, 32
	v_readlane_b32 s31, v254, 33
	s_add_u32 s24, s30, s24
	s_addc_u32 s25, s31, s25
	s_and_b64 s[30:31], s[4:5], exec
	s_cselect_b32 s19, s25, s29
	s_cselect_b32 s48, s24, s28
	s_add_u32 s26, s26, 0x100080
	s_addc_u32 s27, s27, 0
	s_add_u32 s49, s28, 0x100
	s_addc_u32 s52, s29, 0
	s_mov_b32 s53, -2
	s_waitcnt lgkmcnt(0)
	ds_read_b128 v[128:131], v181
	ds_read_b128 v[132:135], v181 offset:1024
	ds_read_b128 v[136:139], v181 offset:2048
	ds_read_b128 v[140:143], v181 offset:3072
	ds_read_b128 v[144:147], v182
	ds_read_b128 v[148:151], v182 offset:1024
	ds_read_b128 v[168:171], v182 offset:2048
	ds_read_b128 v[172:175], v182 offset:3072
	s_add_u32 s28, s26, 0xfff00080
	s_addc_u32 s29, s27, -1
	s_cmp_eq_u32 s53, 60
	s_cselect_b32 s31, s7, s29
	s_cselect_b32 s30, s21, s28
	s_cselect_b32 s29, s19, s52
	s_cselect_b32 s28, s48, s49
	s_add_i32 m0, s35, 0xc000
	ds_read_b128 v[186:189], v183
	ds_read_b128 v[190:193], v183 offset:1024
	ds_read_b128 v[198:201], v183 offset:2048
	ds_read_b128 v[202:205], v183 offset:3072
	ds_read_b128 v[206:209], v183 offset:4096
	ds_read_b128 v[210:213], v183 offset:5120
	ds_read_b128 v[214:217], v183 offset:6144
	ds_read_b128 v[218:221], v183 offset:7168
	global_load_lds_dwordx4 v160, s[26:27]
	s_add_i32 m0, s35, 0xe000
	s_nop 0
	global_load_lds_dwordx4 v162, s[26:27]
	s_waitcnt lgkmcnt(0)
	s_setprio 1
	s_barrier
	v_mfma_f32_16x16x32_bf16 v[124:127], v[128:131], v[186:189], 0
	v_mfma_f32_16x16x32_bf16 v[120:123], v[136:139], v[186:189], 0
	v_mfma_f32_16x16x32_bf16 v[104:107], v[128:131], v[198:201], 0
	v_mfma_f32_16x16x32_bf16 v[108:111], v[136:139], v[198:201], 0
	v_mfma_f32_16x16x32_bf16 v[88:91], v[128:131], v[206:209], 0
	v_mfma_f32_16x16x32_bf16 v[92:95], v[136:139], v[206:209], 0
	v_mfma_f32_16x16x32_bf16 v[72:75], v[128:131], v[214:217], 0
	v_mfma_f32_16x16x32_bf16 v[76:79], v[136:139], v[214:217], 0
	v_mfma_f32_16x16x32_bf16 v[124:127], v[132:135], v[190:193], v[124:127]
	v_mfma_f32_16x16x32_bf16 v[120:123], v[140:143], v[190:193], v[120:123]
	v_mfma_f32_16x16x32_bf16 v[104:107], v[132:135], v[202:205], v[104:107]
	v_mfma_f32_16x16x32_bf16 v[108:111], v[140:143], v[202:205], v[108:111]
	v_mfma_f32_16x16x32_bf16 v[88:91], v[132:135], v[210:213], v[88:91]
	v_mfma_f32_16x16x32_bf16 v[92:95], v[140:143], v[210:213], v[92:95]
	v_mfma_f32_16x16x32_bf16 v[72:75], v[132:135], v[218:221], v[72:75]
	v_mfma_f32_16x16x32_bf16 v[76:79], v[140:143], v[218:221], v[76:79]
	v_mfma_f32_16x16x32_bf16 v[116:119], v[144:147], v[186:189], 0
	v_mfma_f32_16x16x32_bf16 v[112:115], v[168:171], v[186:189], 0
	v_mfma_f32_16x16x32_bf16 v[100:103], v[144:147], v[198:201], 0
	v_mfma_f32_16x16x32_bf16 v[96:99], v[168:171], v[198:201], 0
	v_mfma_f32_16x16x32_bf16 v[84:87], v[144:147], v[206:209], 0
	v_mfma_f32_16x16x32_bf16 v[80:83], v[168:171], v[206:209], 0
	v_mfma_f32_16x16x32_bf16 v[68:71], v[144:147], v[214:217], 0
	v_mfma_f32_16x16x32_bf16 v[64:67], v[168:171], v[214:217], 0
	v_mfma_f32_16x16x32_bf16 v[116:119], v[148:151], v[190:193], v[116:119]
	v_mfma_f32_16x16x32_bf16 v[112:115], v[172:175], v[190:193], v[112:115]
	v_mfma_f32_16x16x32_bf16 v[100:103], v[148:151], v[202:205], v[100:103]
	v_mfma_f32_16x16x32_bf16 v[96:99], v[172:175], v[202:205], v[96:99]
	v_mfma_f32_16x16x32_bf16 v[84:87], v[148:151], v[210:213], v[84:87]
	v_mfma_f32_16x16x32_bf16 v[80:83], v[172:175], v[210:213], v[80:83]
	v_mfma_f32_16x16x32_bf16 v[68:71], v[148:151], v[218:221], v[68:71]
	v_mfma_f32_16x16x32_bf16 v[64:67], v[172:175], v[218:221], v[64:67]
	s_barrier
	s_setprio 0
	s_add_i32 s54, s47, s34
	v_lshl_add_u64 v[176:177], s[28:29], 0, v[154:155]
	s_mov_b32 m0, s54
	ds_read_b128 v[186:189], v183 offset:16384
	ds_read_b128 v[190:193], v183 offset:17408
	ds_read_b128 v[198:201], v183 offset:18432
	ds_read_b128 v[202:205], v183 offset:19456
	ds_read_b128 v[206:209], v183 offset:20480
	ds_read_b128 v[210:213], v183 offset:21504
	ds_read_b128 v[214:217], v183 offset:22528
	ds_read_b128 v[218:221], v183 offset:23552
	global_load_lds_dwordx4 v[176:177], off
	s_add_i32 m0, s54, 0x2000
	s_add_u32 s54, s28, 0x100000
	v_lshl_add_u64 v[194:195], s[28:29], 0, v[158:159]
	s_addc_u32 s55, s29, 0
	s_add_i32 s56, s50, s34
	global_load_lds_dwordx4 v[194:195], off
	s_mov_b32 m0, s56
	v_lshl_add_u64 v[224:225], s[30:31], 0, v[156:157]
	global_load_lds_dwordx4 v154, s[54:55]
	s_add_i32 m0, s56, 0x2000
	s_nop 0
	global_load_lds_dwordx4 v158, s[54:55]
	s_mov_b32 m0, s35
	v_lshl_add_u64 v[222:223], s[30:31], 0, v[152:153]
	global_load_lds_dwordx4 v[222:223], off
	s_mov_b32 m0, s33
	s_nop 0
	global_load_lds_dwordx4 v[224:225], off
	s_waitcnt lgkmcnt(0)
	s_setprio 1
	s_barrier
; #define PG8_STAGE(bufoff, gbase, voff) do { _Pragma("unroll") for (int _i = 0; _i < 2; ++_i) \
;         __builtin_amdgcn_global_load_lds((const unsigned*)((const char*)(gbase) + (voff)[_i]), (PG8_LAS unsigned*)(lds + (bufoff) + ldsw + _i * 8192), 16, 0, 0); } while (0)
; #define PG8_LDA(dst, b, h) do { _Pragma("unroll") for (int m = 0; m < 4; ++m) _Pragma("unroll") for (int k = 0; k < 2; ++k) dst[m][k] = *(const PG8_LAS bf16x8*)(lds + PG8_SA(b, h) + aoff + m * 2048 + k * 1024); } while (0)
; #define PG8_LDB(dst, b, h) do { _Pragma("unroll") for (int n = 0; n < 2; ++n) _Pragma("unroll") for (int k = 0; k < 2; ++k) dst[n][k] = *(const PG8_LAS bf16x8*)(lds + PG8_SB(b, h) + boff + n * 2048 + k * 1024); } while (0)
; #define PG8_MMA(ai, bj, At, Bt) do { __builtin_amdgcn_s_setprio(1); _Pragma("unroll") for (int m = 0; m < 4; ++m) _Pragma("unroll") for (int n = 0; n < 2; ++n) _Pragma("unroll") for (int k = 0; k < 2; ++k) \
;         acc[ai][bj][m][n] = __builtin_amdgcn_mfma_f32_16x16x32_bf16(Bt[n][k], At[m][k], acc[ai][bj][m][n], 0, 0, 0); __builtin_amdgcn_s_setprio(0); } while (0)
; #define PG8_WAIT_V(n) asm volatile("s_waitcnt vmcnt(" #n ")" ::: "memory")
; #define PG8_WAIT_L(n) asm volatile("s_waitcnt lgkmcnt(" #n ")" ::: "memory")
; #define PG8_BAR __builtin_amdgcn_s_barrier()
; #define PG8_SCHED __builtin_amdgcn_sched_barrier(0)
; template <class Epi, class Sched, bool ALIGN_EPI = false, bool SP2 = false>
; __device__ __forceinline__ void gemm_phase(PG8_LAS unsigned char* lds, const Gemm g, const Sched& S, const Epi& E) {
;     ...
;             PG8_WAIT_V(8); PG8_WAIT_L(0); PG8_BAR; PG8_MMA(1, 0, At, B0); PG8_MMA(1, 1, At, B1); PG8_BAR; PG8_SCHED;
;             PG8_LDB(B0, 1, 0); PG8_LDB(B1, 1, 1); PG8_SCHED; PG8_LDA(At, 1, 0); PG8_STAGE(PG8_SA(0, 1), a2 + hstep, voffA);
;             PG8_WAIT_V(8); PG8_WAIT_L(0); PG8_BAR; PG8_MMA(0, 0, At, B0); PG8_MMA(0, 1, At, B1); PG8_BAR; PG8_SCHED;
	v_mfma_f32_16x16x32_bf16 v[56:59], v[128:131], v[186:189], 0
	v_mfma_f32_16x16x32_bf16 v[60:63], v[136:139], v[186:189], 0
	v_mfma_f32_16x16x32_bf16 v[40:43], v[128:131], v[198:201], 0
	v_mfma_f32_16x16x32_bf16 v[44:47], v[136:139], v[198:201], 0
	v_mfma_f32_16x16x32_bf16 v[24:27], v[128:131], v[206:209], 0
	v_mfma_f32_16x16x32_bf16 v[28:31], v[136:139], v[206:209], 0
	v_mfma_f32_16x16x32_bf16 v[8:11], v[128:131], v[214:217], 0
	v_mfma_f32_16x16x32_bf16 v[12:15], v[136:139], v[214:217], 0
	v_mfma_f32_16x16x32_bf16 v[56:59], v[132:135], v[190:193], v[56:59]
	v_mfma_f32_16x16x32_bf16 v[60:63], v[140:143], v[190:193], v[60:63]
	v_mfma_f32_16x16x32_bf16 v[40:43], v[132:135], v[202:205], v[40:43]
	v_mfma_f32_16x16x32_bf16 v[44:47], v[140:143], v[202:205], v[44:47]
	v_mfma_f32_16x16x32_bf16 v[24:27], v[132:135], v[210:213], v[24:27]
	v_mfma_f32_16x16x32_bf16 v[28:31], v[140:143], v[210:213], v[28:31]
	v_mfma_f32_16x16x32_bf16 v[8:11], v[132:135], v[218:221], v[8:11]
	v_mfma_f32_16x16x32_bf16 v[12:15], v[140:143], v[218:221], v[12:15]
	v_mfma_f32_16x16x32_bf16 v[52:55], v[144:147], v[186:189], 0
	v_mfma_f32_16x16x32_bf16 v[48:51], v[168:171], v[186:189], 0
	v_mfma_f32_16x16x32_bf16 v[36:39], v[144:147], v[198:201], 0
	v_mfma_f32_16x16x32_bf16 v[32:35], v[168:171], v[198:201], 0
	v_mfma_f32_16x16x32_bf16 v[20:23], v[144:147], v[206:209], 0
	v_mfma_f32_16x16x32_bf16 v[16:19], v[168:171], v[206:209], 0
	v_mfma_f32_16x16x32_bf16 v[4:7], v[144:147], v[214:217], 0
	v_mfma_f32_16x16x32_bf16 v[0:3], v[168:171], v[214:217], 0
	v_mfma_f32_16x16x32_bf16 v[52:55], v[148:151], v[190:193], v[52:55]
	v_mfma_f32_16x16x32_bf16 v[48:51], v[172:175], v[190:193], v[48:51]
	v_mfma_f32_16x16x32_bf16 v[36:39], v[148:151], v[202:205], v[36:39]
	v_mfma_f32_16x16x32_bf16 v[32:35], v[172:175], v[202:205], v[32:35]
	v_mfma_f32_16x16x32_bf16 v[20:23], v[148:151], v[210:213], v[20:23]
	v_mfma_f32_16x16x32_bf16 v[16:19], v[172:175], v[210:213], v[16:19]
	v_mfma_f32_16x16x32_bf16 v[4:7], v[148:151], v[218:221], v[4:7]
	v_mfma_f32_16x16x32_bf16 v[0:3], v[172:175], v[218:221], v[0:3]
	s_barrier
	s_setprio 0
	s_add_i32 s54, 0, 0x18000
	s_add_i32 s55, 0, 0x1c000
	v_add_u32_e32 v140, s54, v179
	v_add_u32_e32 v172, s55, v179
	ds_read_b128 v[128:131], v140
	ds_read_b128 v[132:135], v140 offset:1024
	ds_read_b128 v[136:139], v140 offset:2048
	ds_read_b128 v[140:143], v140 offset:3072
	ds_read_b128 v[144:147], v172
	ds_read_b128 v[148:151], v172 offset:1024
	ds_read_b128 v[168:171], v172 offset:2048
	ds_read_b128 v[172:175], v172 offset:3072
	s_add_u32 s30, s30, 0x100000
	s_addc_u32 s31, s31, 0
	s_mov_b32 m0, s37
	ds_read_b128 v[186:189], v183 offset:32768
	ds_read_b128 v[190:193], v183 offset:33792
	ds_read_b128 v[198:201], v183 offset:34816
	ds_read_b128 v[202:205], v183 offset:35840
	ds_read_b128 v[206:209], v183 offset:36864
	ds_read_b128 v[210:213], v183 offset:37888
	ds_read_b128 v[214:217], v183 offset:38912
	ds_read_b128 v[218:221], v183 offset:39936
	global_load_lds_dwordx4 v152, s[30:31]
	s_mov_b32 m0, s39
	v_lshl_add_u64 v[226:227], s[30:31], 0, v[156:157]
	global_load_lds_dwordx4 v[226:227], off
	s_waitcnt vmcnt(8) lgkmcnt(0)
	s_setprio 1
	s_barrier
	v_mfma_f32_16x16x32_bf16 v[124:127], v[128:131], v[186:189], v[124:127]
	v_mfma_f32_16x16x32_bf16 v[120:123], v[136:139], v[186:189], v[120:123]
	v_mfma_f32_16x16x32_bf16 v[104:107], v[128:131], v[198:201], v[104:107]
	v_mfma_f32_16x16x32_bf16 v[108:111], v[136:139], v[198:201], v[108:111]
	v_mfma_f32_16x16x32_bf16 v[88:91], v[128:131], v[206:209], v[88:91]
	v_mfma_f32_16x16x32_bf16 v[92:95], v[136:139], v[206:209], v[92:95]
	v_mfma_f32_16x16x32_bf16 v[72:75], v[128:131], v[214:217], v[72:75]
	v_mfma_f32_16x16x32_bf16 v[76:79], v[136:139], v[214:217], v[76:79]
	v_mfma_f32_16x16x32_bf16 v[124:127], v[132:135], v[190:193], v[124:127]
	v_mfma_f32_16x16x32_bf16 v[120:123], v[140:143], v[190:193], v[120:123]
	v_mfma_f32_16x16x32_bf16 v[104:107], v[132:135], v[202:205], v[104:107]
	v_mfma_f32_16x16x32_bf16 v[108:111], v[140:143], v[202:205], v[108:111]
	v_mfma_f32_16x16x32_bf16 v[88:91], v[132:135], v[210:213], v[88:91]
	v_mfma_f32_16x16x32_bf16 v[92:95], v[140:143], v[210:213], v[92:95]
	v_mfma_f32_16x16x32_bf16 v[72:75], v[132:135], v[218:221], v[72:75]
	v_mfma_f32_16x16x32_bf16 v[76:79], v[140:143], v[218:221], v[76:79]
	v_mfma_f32_16x16x32_bf16 v[116:119], v[144:147], v[186:189], v[116:119]
	v_mfma_f32_16x16x32_bf16 v[112:115], v[168:171], v[186:189], v[112:115]
	v_mfma_f32_16x16x32_bf16 v[100:103], v[144:147], v[198:201], v[100:103]
	v_mfma_f32_16x16x32_bf16 v[96:99], v[168:171], v[198:201], v[96:99]
	v_mfma_f32_16x16x32_bf16 v[84:87], v[144:147], v[206:209], v[84:87]
	v_mfma_f32_16x16x32_bf16 v[80:83], v[168:171], v[206:209], v[80:83]
	v_mfma_f32_16x16x32_bf16 v[68:71], v[144:147], v[214:217], v[68:71]
	v_mfma_f32_16x16x32_bf16 v[64:67], v[168:171], v[214:217], v[64:67]
	v_mfma_f32_16x16x32_bf16 v[116:119], v[148:151], v[190:193], v[116:119]
	v_mfma_f32_16x16x32_bf16 v[112:115], v[172:175], v[190:193], v[112:115]
	v_mfma_f32_16x16x32_bf16 v[100:103], v[148:151], v[202:205], v[100:103]
	v_mfma_f32_16x16x32_bf16 v[96:99], v[172:175], v[202:205], v[96:99]
	v_mfma_f32_16x16x32_bf16 v[84:87], v[148:151], v[210:213], v[84:87]
	v_mfma_f32_16x16x32_bf16 v[80:83], v[172:175], v[210:213], v[80:83]
	v_mfma_f32_16x16x32_bf16 v[68:71], v[148:151], v[218:221], v[68:71]
	v_mfma_f32_16x16x32_bf16 v[64:67], v[172:175], v[218:221], v[64:67]
	s_barrier
; #define PG8_STAGE(bufoff, gbase, voff) do { _Pragma("unroll") for (int _i = 0; _i < 2; ++_i) \
;         __builtin_amdgcn_global_load_lds((const unsigned*)((const char*)(gbase) + (voff)[_i]), (PG8_LAS unsigned*)(lds + (bufoff) + ldsw + _i * 8192), 16, 0, 0); } while (0)
; #define PG8_LDA(dst, b, h) do { _Pragma("unroll") for (int m = 0; m < 4; ++m) _Pragma("unroll") for (int k = 0; k < 2; ++k) dst[m][k] = *(const PG8_LAS bf16x8*)(lds + PG8_SA(b, h) + aoff + m * 2048 + k * 1024); } while (0)
; #define PG8_MMA(ai, bj, At, Bt) do { __builtin_amdgcn_s_setprio(1); _Pragma("unroll") for (int m = 0; m < 4; ++m) _Pragma("unroll") for (int n = 0; n < 2; ++n) _Pragma("unroll") for (int k = 0; k < 2; ++k) \
;         acc[ai][bj][m][n] = __builtin_amdgcn_mfma_f32_16x16x32_bf16(Bt[n][k], At[m][k], acc[ai][bj][m][n], 0, 0, 0); __builtin_amdgcn_s_setprio(0); } while (0)
; #define PG8_WAIT_V(n) asm volatile("s_waitcnt vmcnt(" #n ")" ::: "memory")
; #define PG8_WAIT_L(n) asm volatile("s_waitcnt lgkmcnt(" #n ")" ::: "memory")
; #define PG8_BAR __builtin_amdgcn_s_barrier()
; #define PG8_SCHED __builtin_amdgcn_sched_barrier(0)
; template <class Epi, class Sched, bool ALIGN_EPI = false, bool SP2 = false>
; __device__ __forceinline__ void gemm_phase(PG8_LAS unsigned char* lds, const Gemm g, const Sched& S, const Epi& E) {
;     ...
;         for (int t = 0; t < nt; t += 2) {
;     ...
;             PG8_LDA(At, 1, 1); PG8_STAGE(PG8_SB(1, 0), b3, voffB); PG8_STAGE(PG8_SB(1, 1), b3 + hstep, voffB); PG8_STAGE(PG8_SA(1, 0), a3, voffA);
;             PG8_WAIT_V(8); PG8_WAIT_L(0); PG8_BAR; PG8_MMA(1, 0, At, B0); PG8_MMA(1, 1, At, B1); PG8_BAR; PG8_SCHED;
	s_setprio 0
	s_add_i32 s30, s54, s34
	v_lshl_add_u64 v[176:177], v[176:177], 0, s[12:13]
	s_mov_b32 m0, s30
	ds_read_b128 v[186:189], v183 offset:49152
	ds_read_b128 v[190:193], v183 offset:50176
	ds_read_b128 v[198:201], v183 offset:51200
	ds_read_b128 v[202:205], v183 offset:52224
	ds_read_b128 v[206:209], v183 offset:53248
	ds_read_b128 v[210:213], v183 offset:54272
	ds_read_b128 v[214:217], v183 offset:55296
	ds_read_b128 v[218:221], v183 offset:56320
	global_load_lds_dwordx4 v[176:177], off
	s_add_i32 m0, s30, 0x2000
	s_add_u32 s28, s28, 0x100080
	v_lshl_add_u64 v[176:177], v[194:195], 0, s[12:13]
	s_addc_u32 s29, s29, 0
	s_add_i32 s30, s55, s34
	global_load_lds_dwordx4 v[176:177], off
	s_mov_b32 m0, s30
	s_nop 0
	global_load_lds_dwordx4 v154, s[28:29]
	s_add_i32 m0, s30, 0x2000
	v_lshl_add_u64 v[176:177], s[28:29], 0, v[158:159]
	global_load_lds_dwordx4 v[176:177], off
	s_mov_b32 m0, s43
	v_lshl_add_u64 v[176:177], v[222:223], 0, s[12:13]
	global_load_lds_dwordx4 v[176:177], off
	s_mov_b32 m0, s44
	v_lshl_add_u64 v[176:177], v[224:225], 0, s[12:13]
	global_load_lds_dwordx4 v[176:177], off
	s_waitcnt vmcnt(8) lgkmcnt(0)
	s_setprio 1
	s_barrier
	v_mfma_f32_16x16x32_bf16 v[56:59], v[128:131], v[186:189], v[56:59]
	v_mfma_f32_16x16x32_bf16 v[60:63], v[136:139], v[186:189], v[60:63]
	v_mfma_f32_16x16x32_bf16 v[40:43], v[128:131], v[198:201], v[40:43]
	v_mfma_f32_16x16x32_bf16 v[44:47], v[136:139], v[198:201], v[44:47]
	v_mfma_f32_16x16x32_bf16 v[24:27], v[128:131], v[206:209], v[24:27]
	v_mfma_f32_16x16x32_bf16 v[28:31], v[136:139], v[206:209], v[28:31]
	v_mfma_f32_16x16x32_bf16 v[8:11], v[128:131], v[214:217], v[8:11]
	v_mfma_f32_16x16x32_bf16 v[12:15], v[136:139], v[214:217], v[12:15]
	v_mfma_f32_16x16x32_bf16 v[56:59], v[132:135], v[190:193], v[56:59]
	v_mfma_f32_16x16x32_bf16 v[60:63], v[140:143], v[190:193], v[60:63]
	v_mfma_f32_16x16x32_bf16 v[40:43], v[132:135], v[202:205], v[40:43]
	v_mfma_f32_16x16x32_bf16 v[44:47], v[140:143], v[202:205], v[44:47]
	v_mfma_f32_16x16x32_bf16 v[24:27], v[132:135], v[210:213], v[24:27]
	v_mfma_f32_16x16x32_bf16 v[28:31], v[140:143], v[210:213], v[28:31]
	v_mfma_f32_16x16x32_bf16 v[8:11], v[132:135], v[218:221], v[8:11]
	v_mfma_f32_16x16x32_bf16 v[12:15], v[140:143], v[218:221], v[12:15]
	v_mfma_f32_16x16x32_bf16 v[52:55], v[144:147], v[186:189], v[52:55]
	v_mfma_f32_16x16x32_bf16 v[48:51], v[168:171], v[186:189], v[48:51]
	v_mfma_f32_16x16x32_bf16 v[36:39], v[144:147], v[198:201], v[36:39]
	v_mfma_f32_16x16x32_bf16 v[32:35], v[168:171], v[198:201], v[32:35]
	v_mfma_f32_16x16x32_bf16 v[20:23], v[144:147], v[206:209], v[20:23]
	v_mfma_f32_16x16x32_bf16 v[16:19], v[168:171], v[206:209], v[16:19]
	v_mfma_f32_16x16x32_bf16 v[4:7], v[144:147], v[214:217], v[4:7]
	v_mfma_f32_16x16x32_bf16 v[0:3], v[168:171], v[214:217], v[0:3]
	v_mfma_f32_16x16x32_bf16 v[52:55], v[148:151], v[190:193], v[52:55]
	v_mfma_f32_16x16x32_bf16 v[48:51], v[172:175], v[190:193], v[48:51]
	v_mfma_f32_16x16x32_bf16 v[36:39], v[148:151], v[202:205], v[36:39]
	v_mfma_f32_16x16x32_bf16 v[32:35], v[172:175], v[202:205], v[32:35]
	v_mfma_f32_16x16x32_bf16 v[20:23], v[148:151], v[210:213], v[20:23]
	v_mfma_f32_16x16x32_bf16 v[16:19], v[172:175], v[210:213], v[16:19]
	v_mfma_f32_16x16x32_bf16 v[4:7], v[148:151], v[218:221], v[4:7]
	v_mfma_f32_16x16x32_bf16 v[0:3], v[172:175], v[218:221], v[0:3]
	s_barrier
	s_setprio 0
	s_add_i32 s53, s53, 2
	s_add_u32 s26, s26, 0x100
	s_addc_u32 s27, s27, 0
	s_add_u32 s49, s49, 0x100
	s_addc_u32 s52, s52, 0
	.p2align	6

; #define PG8_STAGE(bufoff, gbase, voff) do { _Pragma("unroll") for (int _i = 0; _i < 2; ++_i) \
;         __builtin_amdgcn_global_load_lds((const unsigned*)((const char*)(gbase) + (voff)[_i]), (PG8_LAS unsigned*)(lds + (bufoff) + ldsw + _i * 8192), 16, 0, 0); } while (0)
; #define PG8_LDA(dst, b, h) do { _Pragma("unroll") for (int m = 0; m < 4; ++m) _Pragma("unroll") for (int k = 0; k < 2; ++k) dst[m][k] = *(const PG8_LAS bf16x8*)(lds + PG8_SA(b, h) + aoff + m * 2048 + k * 1024); } while (0)
; #define PG8_LDB(dst, b, h) do { _Pragma("unroll") for (int n = 0; n < 2; ++n) _Pragma("unroll") for (int k = 0; k < 2; ++k) dst[n][k] = *(const PG8_LAS bf16x8*)(lds + PG8_SB(b, h) + boff + n * 2048 + k * 1024); } while (0)
; #define PG8_MMA(ai, bj, At, Bt) do { __builtin_amdgcn_s_setprio(1); _Pragma("unroll") for (int m = 0; m < 4; ++m) _Pragma("unroll") for (int n = 0; n < 2; ++n) _Pragma("unroll") for (int k = 0; k < 2; ++k) \
;         acc[ai][bj][m][n] = __builtin_amdgcn_mfma_f32_16x16x32_bf16(Bt[n][k], At[m][k], acc[ai][bj][m][n], 0, 0, 0); __builtin_amdgcn_s_setprio(0); } while (0)
; #define PG8_BAR __builtin_amdgcn_s_barrier()
; template <class Epi, class Sched, bool ALIGN_EPI = false, bool SP2 = false>
; __device__ __forceinline__ void gemm_phase(PG8_LAS unsigned char* lds, const Gemm g, const Sched& S, const Epi& E) {
;     ...
;         const bool has_next = S.next(ui + 1, nxt);
;         const char* nA = has_next ? (const char*)g.A + (size_t)nxt.pm * tstep : cA; const char* nB = has_next ? (const char*)g.Bt + (size_t)nxt.pn * tstep : cB;
;         for (int t = 0; t < nt; t += 2) {
;             const bool last = (t == nt - 2);
;             const char* a1 = cA + (size_t)(t + 1) * kstep;
;             const char* a2 = last ? nA : cA + (size_t)(t + 2) * kstep; const char* b2 = last ? nB : cB + (size_t)(t + 2) * kstep;
;             const char* a3 = a2 + kstep; const char* b3 = b2 + kstep;
;             if (last && has_next) S.a_ready(nxt);
;             if constexpr (SP2) {
;             PG8_LDB(B0, 0, 0); PG8_LDB(B1, 0, 1); PG8_SCHED; PG8_LDA(At, 0, 0); PG8_STAGE(PG8_SA(1, 1), a1 + hstep, voffA);
;             PG8_WAIT_V(8); PG8_WAIT_L(0); PG8_BAR; PG8_MMA(0, 0, At, B0); PG8_MMA(0, 1, At, B1); PG8_BAR; PG8_SCHED;
;             PG8_LDA(At, 0, 1); PG8_STAGE(PG8_SB(0, 0), b2, voffB); PG8_STAGE(PG8_SB(0, 1), b2 + hstep, voffB); PG8_STAGE(PG8_SA(0, 0), a2, voffA);
.LBB0_954:
	s_ashr_i32 s53, s52, 31
	s_lshl_b64 s[22:23], s[52:53], 20
	s_add_u32 s54, s74, s22
	s_addc_u32 s55, s75, s23
	s_and_b64 s[24:25], s[62:63], exec
	s_cselect_b32 s1, s55, s27
	s_cselect_b32 s5, s54, s26
	s_ashr_i32 s41, s40, 31
	s_lshl_b64 s[24:25], s[40:41], 20
	s_add_u32 s56, s94, s24
	s_addc_u32 s57, s95, s25
	s_and_b64 s[30:31], s[62:63], exec
	s_cselect_b32 s17, s57, s29
	s_cselect_b32 s19, s56, s28
	s_add_u32 s26, s26, 0x80080
	s_addc_u32 s27, s27, 0
	s_add_u32 s33, s28, 0x100
	s_addc_u32 s44, s29, 0
	s_mov_b32 s45, -2
	s_waitcnt vmcnt(0)
	ds_read_b128 v[128:131], v209
	ds_read_b128 v[132:135], v209 offset:1024
	ds_read_b128 v[136:139], v209 offset:2048
	ds_read_b128 v[178:181], v209 offset:3072
	ds_read_b128 v[182:185], v210
	ds_read_b128 v[186:189], v210 offset:1024
	ds_read_b128 v[190:193], v210 offset:2048
	ds_read_b128 v[222:225], v210 offset:3072
	s_add_u32 s28, s26, 0xfff80080
	s_addc_u32 s29, s27, -1
	s_cmp_eq_u32 s45, 28
	s_cselect_b32 s31, s1, s29
	s_cselect_b32 s30, s5, s28
	s_cselect_b32 s29, s17, s44
	s_cselect_b32 s28, s19, s33
	s_add_i32 m0, s35, 0xc000
	ds_read_b128 v[226:229], v211
	ds_read_b128 v[230:233], v211 offset:1024
	ds_read_b128 v[234:237], v211 offset:2048
	ds_read_b128 v[238:241], v211 offset:3072
	ds_read_b128 v[242:245], v211 offset:4096
	ds_read_b128 v[246:249], v211 offset:5120
	ds_read_b128 v[250:253], v211 offset:6144
	ds_read_b128 v[160:163], v211 offset:7168
	global_load_lds_dwordx4 v150, s[26:27]
	s_add_i32 m0, s35, 0xe000
	s_nop 0
	global_load_lds_dwordx4 v152, s[26:27]
	s_waitcnt lgkmcnt(0)
	s_setprio 1
	s_barrier
	v_mfma_f32_16x16x32_bf16 v[124:127], v[128:131], v[226:229], 0
	v_mfma_f32_16x16x32_bf16 v[120:123], v[136:139], v[226:229], 0
	v_mfma_f32_16x16x32_bf16 v[116:119], v[128:131], v[234:237], 0
	v_mfma_f32_16x16x32_bf16 v[108:111], v[136:139], v[234:237], 0
	v_mfma_f32_16x16x32_bf16 v[100:103], v[128:131], v[242:245], 0
	v_mfma_f32_16x16x32_bf16 v[92:95], v[136:139], v[242:245], 0
	v_mfma_f32_16x16x32_bf16 v[84:87], v[128:131], v[250:253], 0
	v_mfma_f32_16x16x32_bf16 v[76:79], v[136:139], v[250:253], 0
	v_mfma_f32_16x16x32_bf16 v[124:127], v[132:135], v[230:233], v[124:127]
	v_mfma_f32_16x16x32_bf16 v[120:123], v[178:181], v[230:233], v[120:123]
	v_mfma_f32_16x16x32_bf16 v[116:119], v[132:135], v[238:241], v[116:119]
	v_mfma_f32_16x16x32_bf16 v[108:111], v[178:181], v[238:241], v[108:111]
	v_mfma_f32_16x16x32_bf16 v[100:103], v[132:135], v[246:249], v[100:103]
	v_mfma_f32_16x16x32_bf16 v[92:95], v[178:181], v[246:249], v[92:95]
	v_mfma_f32_16x16x32_bf16 v[84:87], v[132:135], v[160:163], v[84:87]
	v_mfma_f32_16x16x32_bf16 v[76:79], v[178:181], v[160:163], v[76:79]
	v_mfma_f32_16x16x32_bf16 v[112:115], v[182:185], v[226:229], 0
	v_mfma_f32_16x16x32_bf16 v[104:107], v[190:193], v[226:229], 0
	v_mfma_f32_16x16x32_bf16 v[96:99], v[182:185], v[234:237], 0
	v_mfma_f32_16x16x32_bf16 v[88:91], v[190:193], v[234:237], 0
	v_mfma_f32_16x16x32_bf16 v[80:83], v[182:185], v[242:245], 0
	v_mfma_f32_16x16x32_bf16 v[72:75], v[190:193], v[242:245], 0
	v_mfma_f32_16x16x32_bf16 v[68:71], v[182:185], v[250:253], 0
	v_mfma_f32_16x16x32_bf16 v[64:67], v[190:193], v[250:253], 0
	v_mfma_f32_16x16x32_bf16 v[112:115], v[186:189], v[230:233], v[112:115]
	v_mfma_f32_16x16x32_bf16 v[104:107], v[222:225], v[230:233], v[104:107]
	v_mfma_f32_16x16x32_bf16 v[96:99], v[186:189], v[238:241], v[96:99]
	v_mfma_f32_16x16x32_bf16 v[88:91], v[222:225], v[238:241], v[88:91]
	v_mfma_f32_16x16x32_bf16 v[80:83], v[186:189], v[246:249], v[80:83]
	v_mfma_f32_16x16x32_bf16 v[72:75], v[222:225], v[246:249], v[72:75]
	v_mfma_f32_16x16x32_bf16 v[68:71], v[186:189], v[160:163], v[68:71]
	v_mfma_f32_16x16x32_bf16 v[64:67], v[222:225], v[160:163], v[64:67]
	s_barrier
	s_setprio 0
	s_add_i32 s48, s69, s34
	v_lshl_add_u64 v[166:167], s[28:29], 0, v[142:143]
	s_mov_b32 m0, s48
	ds_read_b128 v[160:163], v211 offset:16384
	ds_read_b128 v[226:229], v211 offset:17408
	ds_read_b128 v[230:233], v211 offset:18432
	ds_read_b128 v[234:237], v211 offset:19456
	ds_read_b128 v[238:241], v211 offset:20480
	ds_read_b128 v[242:245], v211 offset:21504
	ds_read_b128 v[246:249], v211 offset:22528
	ds_read_b128 v[250:253], v211 offset:23552
	global_load_lds_dwordx4 v[166:167], off
	s_add_i32 m0, s48, 0x2000
	s_add_u32 s48, s28, 0x80000
	v_lshl_add_u64 v[170:171], s[28:29], 0, v[146:147]
	s_addc_u32 s49, s29, 0
	s_add_i32 s50, s70, s34
	global_load_lds_dwordx4 v[170:171], off
	s_mov_b32 m0, s50
	v_lshl_add_u64 v[194:195], s[30:31], 0, v[144:145]
	global_load_lds_dwordx4 v142, s[48:49]
	s_add_i32 m0, s50, 0x2000
	s_nop 0
	global_load_lds_dwordx4 v146, s[48:49]
	s_mov_b32 m0, s35
	v_lshl_add_u64 v[174:175], s[30:31], 0, v[140:141]
	global_load_lds_dwordx4 v[174:175], off
	s_mov_b32 m0, s37
	s_nop 0
	global_load_lds_dwordx4 v[194:195], off
	s_waitcnt lgkmcnt(0)
	s_setprio 1
	s_barrier
; #define PG8_STAGE(bufoff, gbase, voff) do { _Pragma("unroll") for (int _i = 0; _i < 2; ++_i) \
;         __builtin_amdgcn_global_load_lds((const unsigned*)((const char*)(gbase) + (voff)[_i]), (PG8_LAS unsigned*)(lds + (bufoff) + ldsw + _i * 8192), 16, 0, 0); } while (0)
; #define PG8_LDA(dst, b, h) do { _Pragma("unroll") for (int m = 0; m < 4; ++m) _Pragma("unroll") for (int k = 0; k < 2; ++k) dst[m][k] = *(const PG8_LAS bf16x8*)(lds + PG8_SA(b, h) + aoff + m * 2048 + k * 1024); } while (0)
; #define PG8_LDB(dst, b, h) do { _Pragma("unroll") for (int n = 0; n < 2; ++n) _Pragma("unroll") for (int k = 0; k < 2; ++k) dst[n][k] = *(const PG8_LAS bf16x8*)(lds + PG8_SB(b, h) + boff + n * 2048 + k * 1024); } while (0)
; #define PG8_MMA(ai, bj, At, Bt) do { __builtin_amdgcn_s_setprio(1); _Pragma("unroll") for (int m = 0; m < 4; ++m) _Pragma("unroll") for (int n = 0; n < 2; ++n) _Pragma("unroll") for (int k = 0; k < 2; ++k) \
;         acc[ai][bj][m][n] = __builtin_amdgcn_mfma_f32_16x16x32_bf16(Bt[n][k], At[m][k], acc[ai][bj][m][n], 0, 0, 0); __builtin_amdgcn_s_setprio(0); } while (0)
; #define PG8_WAIT_V(n) asm volatile("s_waitcnt vmcnt(" #n ")" ::: "memory")
; #define PG8_WAIT_L(n) asm volatile("s_waitcnt lgkmcnt(" #n ")" ::: "memory")
; #define PG8_BAR __builtin_amdgcn_s_barrier()
; #define PG8_SCHED __builtin_amdgcn_sched_barrier(0)
; template <class Epi, class Sched, bool ALIGN_EPI = false, bool SP2 = false>
; __device__ __forceinline__ void gemm_phase(PG8_LAS unsigned char* lds, const Gemm g, const Sched& S, const Epi& E) {
;     ...
;             PG8_WAIT_V(8); PG8_WAIT_L(0); PG8_BAR; PG8_MMA(1, 0, At, B0); PG8_MMA(1, 1, At, B1); PG8_BAR; PG8_SCHED;
;             PG8_LDB(B0, 1, 0); PG8_LDB(B1, 1, 1); PG8_SCHED; PG8_LDA(At, 1, 0); PG8_STAGE(PG8_SA(0, 1), a2 + hstep, voffA);
;             PG8_WAIT_V(8); PG8_WAIT_L(0); PG8_BAR; PG8_MMA(0, 0, At, B0); PG8_MMA(0, 1, At, B1); PG8_BAR; PG8_SCHED;
	v_mfma_f32_16x16x32_bf16 v[60:63], v[128:131], v[160:163], 0
	v_mfma_f32_16x16x32_bf16 v[56:59], v[136:139], v[160:163], 0
	v_mfma_f32_16x16x32_bf16 v[52:55], v[128:131], v[230:233], 0
	v_mfma_f32_16x16x32_bf16 v[44:47], v[136:139], v[230:233], 0
	v_mfma_f32_16x16x32_bf16 v[36:39], v[128:131], v[238:241], 0
	v_mfma_f32_16x16x32_bf16 v[28:31], v[136:139], v[238:241], 0
	v_mfma_f32_16x16x32_bf16 v[20:23], v[128:131], v[246:249], 0
	v_mfma_f32_16x16x32_bf16 v[12:15], v[136:139], v[246:249], 0
	v_mfma_f32_16x16x32_bf16 v[60:63], v[132:135], v[226:229], v[60:63]
	v_mfma_f32_16x16x32_bf16 v[56:59], v[178:181], v[226:229], v[56:59]
	v_mfma_f32_16x16x32_bf16 v[52:55], v[132:135], v[234:237], v[52:55]
	v_mfma_f32_16x16x32_bf16 v[44:47], v[178:181], v[234:237], v[44:47]
	v_mfma_f32_16x16x32_bf16 v[36:39], v[132:135], v[242:245], v[36:39]
	v_mfma_f32_16x16x32_bf16 v[28:31], v[178:181], v[242:245], v[28:31]
	v_mfma_f32_16x16x32_bf16 v[20:23], v[132:135], v[250:253], v[20:23]
	v_mfma_f32_16x16x32_bf16 v[12:15], v[178:181], v[250:253], v[12:15]
	v_mfma_f32_16x16x32_bf16 v[48:51], v[182:185], v[160:163], 0
	v_mfma_f32_16x16x32_bf16 v[40:43], v[190:193], v[160:163], 0
	v_mfma_f32_16x16x32_bf16 v[32:35], v[182:185], v[230:233], 0
	v_mfma_f32_16x16x32_bf16 v[24:27], v[190:193], v[230:233], 0
	v_mfma_f32_16x16x32_bf16 v[16:19], v[182:185], v[238:241], 0
	v_mfma_f32_16x16x32_bf16 v[8:11], v[190:193], v[238:241], 0
	v_mfma_f32_16x16x32_bf16 v[4:7], v[182:185], v[246:249], 0
	v_mfma_f32_16x16x32_bf16 v[0:3], v[190:193], v[246:249], 0
	v_mfma_f32_16x16x32_bf16 v[48:51], v[186:189], v[226:229], v[48:51]
	v_mfma_f32_16x16x32_bf16 v[40:43], v[222:225], v[226:229], v[40:43]
	v_mfma_f32_16x16x32_bf16 v[32:35], v[186:189], v[234:237], v[32:35]
	v_mfma_f32_16x16x32_bf16 v[24:27], v[222:225], v[234:237], v[24:27]
	v_mfma_f32_16x16x32_bf16 v[16:19], v[186:189], v[242:245], v[16:19]
	v_mfma_f32_16x16x32_bf16 v[8:11], v[222:225], v[242:245], v[8:11]
	v_mfma_f32_16x16x32_bf16 v[4:7], v[186:189], v[250:253], v[4:7]
	v_mfma_f32_16x16x32_bf16 v[0:3], v[222:225], v[250:253], v[0:3]
	s_barrier
	s_setprio 0
	s_add_i32 s48, 0, 0x18000
	v_add_u32_e32 v148, s48, v159
	s_add_i32 s49, 0, 0x1c000
	ds_read_b128 v[128:131], v148
	ds_read_b128 v[132:135], v148 offset:1024
	ds_read_b128 v[136:139], v148 offset:2048
	ds_read_b128 v[160:163], v148 offset:3072
	v_add_u32_e32 v148, s49, v159
	ds_read_b128 v[178:181], v148
	ds_read_b128 v[182:185], v148 offset:1024
	ds_read_b128 v[186:189], v148 offset:2048
	ds_read_b128 v[190:193], v148 offset:3072
	s_add_u32 s30, s30, 0x80000
	s_addc_u32 s31, s31, 0
	s_mov_b32 m0, s39
	ds_read_b128 v[222:225], v211 offset:32768
	ds_read_b128 v[226:229], v211 offset:33792
	ds_read_b128 v[230:233], v211 offset:34816
	ds_read_b128 v[234:237], v211 offset:35840
	ds_read_b128 v[238:241], v211 offset:36864
	ds_read_b128 v[242:245], v211 offset:37888
	ds_read_b128 v[246:249], v211 offset:38912
	ds_read_b128 v[250:253], v211 offset:39936
	global_load_lds_dwordx4 v140, s[30:31]
	s_mov_b32 m0, s42
	v_lshl_add_u64 v[154:155], s[30:31], 0, v[144:145]
	global_load_lds_dwordx4 v[154:155], off
	s_waitcnt vmcnt(8) lgkmcnt(0)
	s_setprio 1
	s_barrier
	v_mfma_f32_16x16x32_bf16 v[124:127], v[128:131], v[222:225], v[124:127]
	v_mfma_f32_16x16x32_bf16 v[120:123], v[136:139], v[222:225], v[120:123]
	v_mfma_f32_16x16x32_bf16 v[116:119], v[128:131], v[230:233], v[116:119]
	v_mfma_f32_16x16x32_bf16 v[108:111], v[136:139], v[230:233], v[108:111]
	v_mfma_f32_16x16x32_bf16 v[100:103], v[128:131], v[238:241], v[100:103]
	v_mfma_f32_16x16x32_bf16 v[92:95], v[136:139], v[238:241], v[92:95]
	v_mfma_f32_16x16x32_bf16 v[84:87], v[128:131], v[246:249], v[84:87]
	v_mfma_f32_16x16x32_bf16 v[76:79], v[136:139], v[246:249], v[76:79]
	v_mfma_f32_16x16x32_bf16 v[124:127], v[132:135], v[226:229], v[124:127]
	v_mfma_f32_16x16x32_bf16 v[120:123], v[160:163], v[226:229], v[120:123]
	v_mfma_f32_16x16x32_bf16 v[116:119], v[132:135], v[234:237], v[116:119]
	v_mfma_f32_16x16x32_bf16 v[108:111], v[160:163], v[234:237], v[108:111]
	v_mfma_f32_16x16x32_bf16 v[100:103], v[132:135], v[242:245], v[100:103]
	v_mfma_f32_16x16x32_bf16 v[92:95], v[160:163], v[242:245], v[92:95]
	v_mfma_f32_16x16x32_bf16 v[84:87], v[132:135], v[250:253], v[84:87]
	v_mfma_f32_16x16x32_bf16 v[76:79], v[160:163], v[250:253], v[76:79]
	v_mfma_f32_16x16x32_bf16 v[112:115], v[178:181], v[222:225], v[112:115]
	v_mfma_f32_16x16x32_bf16 v[104:107], v[186:189], v[222:225], v[104:107]
	v_mfma_f32_16x16x32_bf16 v[96:99], v[178:181], v[230:233], v[96:99]
	v_mfma_f32_16x16x32_bf16 v[88:91], v[186:189], v[230:233], v[88:91]
	v_mfma_f32_16x16x32_bf16 v[80:83], v[178:181], v[238:241], v[80:83]
	v_mfma_f32_16x16x32_bf16 v[72:75], v[186:189], v[238:241], v[72:75]
	v_mfma_f32_16x16x32_bf16 v[68:71], v[178:181], v[246:249], v[68:71]
	v_mfma_f32_16x16x32_bf16 v[64:67], v[186:189], v[246:249], v[64:67]
	v_mfma_f32_16x16x32_bf16 v[112:115], v[182:185], v[226:229], v[112:115]
	v_mfma_f32_16x16x32_bf16 v[104:107], v[190:193], v[226:229], v[104:107]
	v_mfma_f32_16x16x32_bf16 v[96:99], v[182:185], v[234:237], v[96:99]
	v_mfma_f32_16x16x32_bf16 v[88:91], v[190:193], v[234:237], v[88:91]
	v_mfma_f32_16x16x32_bf16 v[80:83], v[182:185], v[242:245], v[80:83]
	v_mfma_f32_16x16x32_bf16 v[72:75], v[190:193], v[242:245], v[72:75]
	v_mfma_f32_16x16x32_bf16 v[68:71], v[182:185], v[250:253], v[68:71]
	v_mfma_f32_16x16x32_bf16 v[64:67], v[190:193], v[250:253], v[64:67]
	s_barrier
; #define PG8_STAGE(bufoff, gbase, voff) do { _Pragma("unroll") for (int _i = 0; _i < 2; ++_i) \
;         __builtin_amdgcn_global_load_lds((const unsigned*)((const char*)(gbase) + (voff)[_i]), (PG8_LAS unsigned*)(lds + (bufoff) + ldsw + _i * 8192), 16, 0, 0); } while (0)
; #define PG8_LDA(dst, b, h) do { _Pragma("unroll") for (int m = 0; m < 4; ++m) _Pragma("unroll") for (int k = 0; k < 2; ++k) dst[m][k] = *(const PG8_LAS bf16x8*)(lds + PG8_SA(b, h) + aoff + m * 2048 + k * 1024); } while (0)
; #define PG8_MMA(ai, bj, At, Bt) do { __builtin_amdgcn_s_setprio(1); _Pragma("unroll") for (int m = 0; m < 4; ++m) _Pragma("unroll") for (int n = 0; n < 2; ++n) _Pragma("unroll") for (int k = 0; k < 2; ++k) \
;         acc[ai][bj][m][n] = __builtin_amdgcn_mfma_f32_16x16x32_bf16(Bt[n][k], At[m][k], acc[ai][bj][m][n], 0, 0, 0); __builtin_amdgcn_s_setprio(0); } while (0)
; #define PG8_WAIT_V(n) asm volatile("s_waitcnt vmcnt(" #n ")" ::: "memory")
; #define PG8_WAIT_L(n) asm volatile("s_waitcnt lgkmcnt(" #n ")" ::: "memory")
; #define PG8_BAR __builtin_amdgcn_s_barrier()
; #define PG8_SCHED __builtin_amdgcn_sched_barrier(0)
; template <class Epi, class Sched, bool ALIGN_EPI = false, bool SP2 = false>
; __device__ __forceinline__ void gemm_phase(PG8_LAS unsigned char* lds, const Gemm g, const Sched& S, const Epi& E) {
;     ...
;         for (int t = 0; t < nt; t += 2) {
;     ...
;             PG8_LDA(At, 1, 1); PG8_STAGE(PG8_SB(1, 0), b3, voffB); PG8_STAGE(PG8_SB(1, 1), b3 + hstep, voffB); PG8_STAGE(PG8_SA(1, 0), a3, voffA);
;             PG8_WAIT_V(8); PG8_WAIT_L(0); PG8_BAR; PG8_MMA(1, 0, At, B0); PG8_MMA(1, 1, At, B1); PG8_BAR; PG8_SCHED;
	s_setprio 0
	s_add_i32 s30, s48, s34
	v_lshl_add_u64 v[154:155], v[166:167], 0, s[10:11]
	s_mov_b32 m0, s30
	ds_read_b128 v[222:225], v211 offset:49152
	ds_read_b128 v[226:229], v211 offset:50176
	ds_read_b128 v[230:233], v211 offset:51200
	ds_read_b128 v[234:237], v211 offset:52224
	ds_read_b128 v[238:241], v211 offset:53248
	ds_read_b128 v[242:245], v211 offset:54272
	ds_read_b128 v[246:249], v211 offset:55296
	ds_read_b128 v[250:253], v211 offset:56320
	global_load_lds_dwordx4 v[154:155], off
	s_add_i32 m0, s30, 0x2000
	s_add_u32 s28, s28, 0x80080
	v_lshl_add_u64 v[154:155], v[170:171], 0, s[10:11]
	s_addc_u32 s29, s29, 0
	s_add_i32 s30, s49, s34
	global_load_lds_dwordx4 v[154:155], off
	s_mov_b32 m0, s30
	s_nop 0
	global_load_lds_dwordx4 v142, s[28:29]
	s_add_i32 m0, s30, 0x2000
	v_lshl_add_u64 v[154:155], s[28:29], 0, v[146:147]
	global_load_lds_dwordx4 v[154:155], off
	s_mov_b32 m0, s46
	v_lshl_add_u64 v[154:155], v[174:175], 0, s[10:11]
	global_load_lds_dwordx4 v[154:155], off
	s_mov_b32 m0, s47
	v_lshl_add_u64 v[154:155], v[194:195], 0, s[10:11]
	global_load_lds_dwordx4 v[154:155], off
	s_waitcnt vmcnt(8) lgkmcnt(0)
	s_setprio 1
	s_barrier
	v_mfma_f32_16x16x32_bf16 v[60:63], v[128:131], v[222:225], v[60:63]
	v_mfma_f32_16x16x32_bf16 v[56:59], v[136:139], v[222:225], v[56:59]
	v_mfma_f32_16x16x32_bf16 v[52:55], v[128:131], v[230:233], v[52:55]
	v_mfma_f32_16x16x32_bf16 v[44:47], v[136:139], v[230:233], v[44:47]
	v_mfma_f32_16x16x32_bf16 v[36:39], v[128:131], v[238:241], v[36:39]
	v_mfma_f32_16x16x32_bf16 v[28:31], v[136:139], v[238:241], v[28:31]
	v_mfma_f32_16x16x32_bf16 v[20:23], v[128:131], v[246:249], v[20:23]
	v_mfma_f32_16x16x32_bf16 v[12:15], v[136:139], v[246:249], v[12:15]
	v_mfma_f32_16x16x32_bf16 v[60:63], v[132:135], v[226:229], v[60:63]
	v_mfma_f32_16x16x32_bf16 v[56:59], v[160:163], v[226:229], v[56:59]
	v_mfma_f32_16x16x32_bf16 v[52:55], v[132:135], v[234:237], v[52:55]
	v_mfma_f32_16x16x32_bf16 v[44:47], v[160:163], v[234:237], v[44:47]
	v_mfma_f32_16x16x32_bf16 v[36:39], v[132:135], v[242:245], v[36:39]
	v_mfma_f32_16x16x32_bf16 v[28:31], v[160:163], v[242:245], v[28:31]
	v_mfma_f32_16x16x32_bf16 v[20:23], v[132:135], v[250:253], v[20:23]
	v_mfma_f32_16x16x32_bf16 v[12:15], v[160:163], v[250:253], v[12:15]
	v_mfma_f32_16x16x32_bf16 v[48:51], v[178:181], v[222:225], v[48:51]
	v_mfma_f32_16x16x32_bf16 v[40:43], v[186:189], v[222:225], v[40:43]
	v_mfma_f32_16x16x32_bf16 v[32:35], v[178:181], v[230:233], v[32:35]
	v_mfma_f32_16x16x32_bf16 v[24:27], v[186:189], v[230:233], v[24:27]
	v_mfma_f32_16x16x32_bf16 v[16:19], v[178:181], v[238:241], v[16:19]
	v_mfma_f32_16x16x32_bf16 v[8:11], v[186:189], v[238:241], v[8:11]
	v_mfma_f32_16x16x32_bf16 v[4:7], v[178:181], v[246:249], v[4:7]
	v_mfma_f32_16x16x32_bf16 v[0:3], v[186:189], v[246:249], v[0:3]
	v_mfma_f32_16x16x32_bf16 v[48:51], v[182:185], v[226:229], v[48:51]
	v_mfma_f32_16x16x32_bf16 v[40:43], v[190:193], v[226:229], v[40:43]
	v_mfma_f32_16x16x32_bf16 v[32:35], v[182:185], v[234:237], v[32:35]
	v_mfma_f32_16x16x32_bf16 v[24:27], v[190:193], v[234:237], v[24:27]
	v_mfma_f32_16x16x32_bf16 v[16:19], v[182:185], v[242:245], v[16:19]
	v_mfma_f32_16x16x32_bf16 v[8:11], v[190:193], v[242:245], v[8:11]
	v_mfma_f32_16x16x32_bf16 v[4:7], v[182:185], v[250:253], v[4:7]
	v_mfma_f32_16x16x32_bf16 v[0:3], v[190:193], v[250:253], v[0:3]
	s_barrier
	s_setprio 0
	s_add_i32 s45, s45, 2
	s_add_u32 s26, s26, 0x100
	s_addc_u32 s27, s27, 0
	s_add_u32 s33, s33, 0x100
	s_addc_u32 s44, s44, 0
	.p2align	6

; #define PG8_STAGE(bufoff, gbase, voff) do { _Pragma("unroll") for (int _i = 0; _i < 2; ++_i) \
;         __builtin_amdgcn_global_load_lds((const unsigned*)((const char*)(gbase) + (voff)[_i]), (PG8_LAS unsigned*)(lds + (bufoff) + ldsw + _i * 8192), 16, 0, 0); } while (0)
; #define PG8_LDA(dst, b, h) do { _Pragma("unroll") for (int m = 0; m < 4; ++m) _Pragma("unroll") for (int k = 0; k < 2; ++k) dst[m][k] = *(const PG8_LAS bf16x8*)(lds + PG8_SA(b, h) + aoff + m * 2048 + k * 1024); } while (0)
; #define PG8_LDB(dst, b, h) do { _Pragma("unroll") for (int n = 0; n < 2; ++n) _Pragma("unroll") for (int k = 0; k < 2; ++k) dst[n][k] = *(const PG8_LAS bf16x8*)(lds + PG8_SB(b, h) + boff + n * 2048 + k * 1024); } while (0)
; #define PG8_MMA(ai, bj, At, Bt) do { __builtin_amdgcn_s_setprio(1); _Pragma("unroll") for (int m = 0; m < 4; ++m) _Pragma("unroll") for (int n = 0; n < 2; ++n) _Pragma("unroll") for (int k = 0; k < 2; ++k) \
;         acc[ai][bj][m][n] = __builtin_amdgcn_mfma_f32_16x16x32_bf16(Bt[n][k], At[m][k], acc[ai][bj][m][n], 0, 0, 0); __builtin_amdgcn_s_setprio(0); } while (0)
; #define PG8_BAR __builtin_amdgcn_s_barrier()
; template <class Epi, class Sched, bool ALIGN_EPI = false, bool SP2 = false>
; __device__ __forceinline__ void gemm_phase(PG8_LAS unsigned char* lds, const Gemm g, const Sched& S, const Epi& E) {
;     ...
;         const bool has_next = S.next(ui + 1, nxt);
;         const char* nA = has_next ? (const char*)g.A + (size_t)nxt.pm * tstep : cA; const char* nB = has_next ? (const char*)g.Bt + (size_t)nxt.pn * tstep : cB;
;         for (int t = 0; t < nt; t += 2) {
;             const bool last = (t == nt - 2);
;             const char* a1 = cA + (size_t)(t + 1) * kstep;
;             const char* a2 = last ? nA : cA + (size_t)(t + 2) * kstep; const char* b2 = last ? nB : cB + (size_t)(t + 2) * kstep;
;             const char* a3 = a2 + kstep; const char* b3 = b2 + kstep;
;             if (last && has_next) S.a_ready(nxt);
;             if constexpr (SP2) {
;             PG8_LDB(B0, 0, 0); PG8_LDB(B1, 0, 1); PG8_SCHED; PG8_LDA(At, 0, 0); PG8_STAGE(PG8_SA(1, 1), a1 + hstep, voffA);
;             PG8_WAIT_V(8); PG8_WAIT_L(0); PG8_BAR; PG8_MMA(0, 0, At, B0); PG8_MMA(0, 1, At, B1); PG8_BAR; PG8_SCHED;
;             PG8_LDA(At, 0, 1); PG8_STAGE(PG8_SB(0, 0), b2, voffB); PG8_STAGE(PG8_SB(0, 1), b2 + hstep, voffB); PG8_STAGE(PG8_SA(0, 0), a2, voffA);
.LBB0_1179:
	s_ashr_i32 s21, s20, 31
	s_lshl_b64 s[22:23], s[20:21], 20
	s_add_u32 s22, s56, s22
	s_addc_u32 s23, s57, s23
	s_and_b64 s[24:25], s[4:5], exec
	s_cselect_b32 s7, s23, s27
	s_cselect_b32 s21, s22, s26
	s_ashr_i32 s19, s18, 31
	s_lshl_b64 s[24:25], s[18:19], 20
	s_add_u32 s24, s68, s24
	s_addc_u32 s25, s69, s25
	s_and_b64 s[30:31], s[4:5], exec
	s_cselect_b32 s19, s25, s29
	s_cselect_b32 s46, s24, s28
	s_add_u32 s26, s26, 0x80080
	s_addc_u32 s27, s27, 0
	s_add_u32 s47, s28, 0x100
	s_addc_u32 s48, s29, 0
	s_mov_b32 s49, -2
	s_waitcnt lgkmcnt(0)
	ds_read_b128 v[128:131], v181
	ds_read_b128 v[132:135], v181 offset:1024
	ds_read_b128 v[136:139], v181 offset:2048
	ds_read_b128 v[140:143], v181 offset:3072
	ds_read_b128 v[144:147], v182
	ds_read_b128 v[148:151], v182 offset:1024
	ds_read_b128 v[168:171], v182 offset:2048
	ds_read_b128 v[172:175], v182 offset:3072
	s_add_u32 s28, s26, 0xfff80080
	s_addc_u32 s29, s27, -1
	s_cmp_eq_u32 s49, 28
	s_cselect_b32 s31, s7, s29
	s_cselect_b32 s30, s21, s28
	s_cselect_b32 s29, s19, s48
	s_cselect_b32 s28, s46, s47
	s_add_i32 m0, s35, 0xc000
	ds_read_b128 v[186:189], v183
	ds_read_b128 v[190:193], v183 offset:1024
	ds_read_b128 v[198:201], v183 offset:2048
	ds_read_b128 v[202:205], v183 offset:3072
	ds_read_b128 v[206:209], v183 offset:4096
	ds_read_b128 v[210:213], v183 offset:5120
	ds_read_b128 v[214:217], v183 offset:6144
	ds_read_b128 v[218:221], v183 offset:7168
	global_load_lds_dwordx4 v160, s[26:27]
	s_add_i32 m0, s35, 0xe000
	s_nop 0
	global_load_lds_dwordx4 v162, s[26:27]
	s_waitcnt lgkmcnt(0)
	s_setprio 1
	s_barrier
	v_mfma_f32_16x16x32_bf16 v[124:127], v[128:131], v[186:189], 0
	v_mfma_f32_16x16x32_bf16 v[120:123], v[136:139], v[186:189], 0
	v_mfma_f32_16x16x32_bf16 v[104:107], v[128:131], v[198:201], 0
	v_mfma_f32_16x16x32_bf16 v[108:111], v[136:139], v[198:201], 0
	v_mfma_f32_16x16x32_bf16 v[88:91], v[128:131], v[206:209], 0
	v_mfma_f32_16x16x32_bf16 v[92:95], v[136:139], v[206:209], 0
	v_mfma_f32_16x16x32_bf16 v[72:75], v[128:131], v[214:217], 0
	v_mfma_f32_16x16x32_bf16 v[76:79], v[136:139], v[214:217], 0
	v_mfma_f32_16x16x32_bf16 v[124:127], v[132:135], v[190:193], v[124:127]
	v_mfma_f32_16x16x32_bf16 v[120:123], v[140:143], v[190:193], v[120:123]
	v_mfma_f32_16x16x32_bf16 v[104:107], v[132:135], v[202:205], v[104:107]
	v_mfma_f32_16x16x32_bf16 v[108:111], v[140:143], v[202:205], v[108:111]
	v_mfma_f32_16x16x32_bf16 v[88:91], v[132:135], v[210:213], v[88:91]
	v_mfma_f32_16x16x32_bf16 v[92:95], v[140:143], v[210:213], v[92:95]
	v_mfma_f32_16x16x32_bf16 v[72:75], v[132:135], v[218:221], v[72:75]
	v_mfma_f32_16x16x32_bf16 v[76:79], v[140:143], v[218:221], v[76:79]
	v_mfma_f32_16x16x32_bf16 v[116:119], v[144:147], v[186:189], 0
	v_mfma_f32_16x16x32_bf16 v[112:115], v[168:171], v[186:189], 0
	v_mfma_f32_16x16x32_bf16 v[100:103], v[144:147], v[198:201], 0
	v_mfma_f32_16x16x32_bf16 v[96:99], v[168:171], v[198:201], 0
	v_mfma_f32_16x16x32_bf16 v[84:87], v[144:147], v[206:209], 0
	v_mfma_f32_16x16x32_bf16 v[80:83], v[168:171], v[206:209], 0
	v_mfma_f32_16x16x32_bf16 v[68:71], v[144:147], v[214:217], 0
	v_mfma_f32_16x16x32_bf16 v[64:67], v[168:171], v[214:217], 0
	v_mfma_f32_16x16x32_bf16 v[116:119], v[148:151], v[190:193], v[116:119]
	v_mfma_f32_16x16x32_bf16 v[112:115], v[172:175], v[190:193], v[112:115]
	v_mfma_f32_16x16x32_bf16 v[100:103], v[148:151], v[202:205], v[100:103]
	v_mfma_f32_16x16x32_bf16 v[96:99], v[172:175], v[202:205], v[96:99]
	v_mfma_f32_16x16x32_bf16 v[84:87], v[148:151], v[210:213], v[84:87]
	v_mfma_f32_16x16x32_bf16 v[80:83], v[172:175], v[210:213], v[80:83]
	v_mfma_f32_16x16x32_bf16 v[68:71], v[148:151], v[218:221], v[68:71]
	v_mfma_f32_16x16x32_bf16 v[64:67], v[172:175], v[218:221], v[64:67]
	s_barrier
	s_setprio 0
	s_add_i32 s50, s43, s34
	v_lshl_add_u64 v[176:177], s[28:29], 0, v[154:155]
	s_mov_b32 m0, s50
	ds_read_b128 v[186:189], v183 offset:16384
	ds_read_b128 v[190:193], v183 offset:17408
	ds_read_b128 v[198:201], v183 offset:18432
	ds_read_b128 v[202:205], v183 offset:19456
	ds_read_b128 v[206:209], v183 offset:20480
	ds_read_b128 v[210:213], v183 offset:21504
	ds_read_b128 v[214:217], v183 offset:22528
	ds_read_b128 v[218:221], v183 offset:23552
	global_load_lds_dwordx4 v[176:177], off
	s_add_i32 m0, s50, 0x2000
	s_add_u32 s50, s28, 0x80000
	v_lshl_add_u64 v[194:195], s[28:29], 0, v[158:159]
	s_addc_u32 s51, s29, 0
	s_add_i32 s52, s44, s34
	global_load_lds_dwordx4 v[194:195], off
	s_mov_b32 m0, s52
	v_lshl_add_u64 v[224:225], s[30:31], 0, v[156:157]
	global_load_lds_dwordx4 v154, s[50:51]
	s_add_i32 m0, s52, 0x2000
	s_nop 0
	global_load_lds_dwordx4 v158, s[50:51]
	s_mov_b32 m0, s35
	v_lshl_add_u64 v[222:223], s[30:31], 0, v[152:153]
	global_load_lds_dwordx4 v[222:223], off
	s_mov_b32 m0, s33
	s_nop 0
	global_load_lds_dwordx4 v[224:225], off
	s_waitcnt lgkmcnt(0)
	s_setprio 1
	s_barrier
; #define PG8_STAGE(bufoff, gbase, voff) do { _Pragma("unroll") for (int _i = 0; _i < 2; ++_i) \
;         __builtin_amdgcn_global_load_lds((const unsigned*)((const char*)(gbase) + (voff)[_i]), (PG8_LAS unsigned*)(lds + (bufoff) + ldsw + _i * 8192), 16, 0, 0); } while (0)
; #define PG8_LDA(dst, b, h) do { _Pragma("unroll") for (int m = 0; m < 4; ++m) _Pragma("unroll") for (int k = 0; k < 2; ++k) dst[m][k] = *(const PG8_LAS bf16x8*)(lds + PG8_SA(b, h) + aoff + m * 2048 + k * 1024); } while (0)
; #define PG8_LDB(dst, b, h) do { _Pragma("unroll") for (int n = 0; n < 2; ++n) _Pragma("unroll") for (int k = 0; k < 2; ++k) dst[n][k] = *(const PG8_LAS bf16x8*)(lds + PG8_SB(b, h) + boff + n * 2048 + k * 1024); } while (0)
; #define PG8_MMA(ai, bj, At, Bt) do { __builtin_amdgcn_s_setprio(1); _Pragma("unroll") for (int m = 0; m < 4; ++m) _Pragma("unroll") for (int n = 0; n < 2; ++n) _Pragma("unroll") for (int k = 0; k < 2; ++k) \
;         acc[ai][bj][m][n] = __builtin_amdgcn_mfma_f32_16x16x32_bf16(Bt[n][k], At[m][k], acc[ai][bj][m][n], 0, 0, 0); __builtin_amdgcn_s_setprio(0); } while (0)
; #define PG8_WAIT_V(n) asm volatile("s_waitcnt vmcnt(" #n ")" ::: "memory")
; #define PG8_WAIT_L(n) asm volatile("s_waitcnt lgkmcnt(" #n ")" ::: "memory")
; #define PG8_BAR __builtin_amdgcn_s_barrier()
; #define PG8_SCHED __builtin_amdgcn_sched_barrier(0)
; template <class Epi, class Sched, bool ALIGN_EPI = false, bool SP2 = false>
; __device__ __forceinline__ void gemm_phase(PG8_LAS unsigned char* lds, const Gemm g, const Sched& S, const Epi& E) {
;     ...
;             PG8_WAIT_V(8); PG8_WAIT_L(0); PG8_BAR; PG8_MMA(1, 0, At, B0); PG8_MMA(1, 1, At, B1); PG8_BAR; PG8_SCHED;
;             PG8_LDB(B0, 1, 0); PG8_LDB(B1, 1, 1); PG8_SCHED; PG8_LDA(At, 1, 0); PG8_STAGE(PG8_SA(0, 1), a2 + hstep, voffA);
;             PG8_WAIT_V(8); PG8_WAIT_L(0); PG8_BAR; PG8_MMA(0, 0, At, B0); PG8_MMA(0, 1, At, B1); PG8_BAR; PG8_SCHED;
	v_mfma_f32_16x16x32_bf16 v[56:59], v[128:131], v[186:189], 0
	v_mfma_f32_16x16x32_bf16 v[60:63], v[136:139], v[186:189], 0
	v_mfma_f32_16x16x32_bf16 v[40:43], v[128:131], v[198:201], 0
	v_mfma_f32_16x16x32_bf16 v[44:47], v[136:139], v[198:201], 0
	v_mfma_f32_16x16x32_bf16 v[24:27], v[128:131], v[206:209], 0
	v_mfma_f32_16x16x32_bf16 v[28:31], v[136:139], v[206:209], 0
	v_mfma_f32_16x16x32_bf16 v[8:11], v[128:131], v[214:217], 0
	v_mfma_f32_16x16x32_bf16 v[12:15], v[136:139], v[214:217], 0
	v_mfma_f32_16x16x32_bf16 v[56:59], v[132:135], v[190:193], v[56:59]
	v_mfma_f32_16x16x32_bf16 v[60:63], v[140:143], v[190:193], v[60:63]
	v_mfma_f32_16x16x32_bf16 v[40:43], v[132:135], v[202:205], v[40:43]
	v_mfma_f32_16x16x32_bf16 v[44:47], v[140:143], v[202:205], v[44:47]
	v_mfma_f32_16x16x32_bf16 v[24:27], v[132:135], v[210:213], v[24:27]
	v_mfma_f32_16x16x32_bf16 v[28:31], v[140:143], v[210:213], v[28:31]
	v_mfma_f32_16x16x32_bf16 v[8:11], v[132:135], v[218:221], v[8:11]
	v_mfma_f32_16x16x32_bf16 v[12:15], v[140:143], v[218:221], v[12:15]
	v_mfma_f32_16x16x32_bf16 v[52:55], v[144:147], v[186:189], 0
	v_mfma_f32_16x16x32_bf16 v[48:51], v[168:171], v[186:189], 0
	v_mfma_f32_16x16x32_bf16 v[36:39], v[144:147], v[198:201], 0
	v_mfma_f32_16x16x32_bf16 v[32:35], v[168:171], v[198:201], 0
	v_mfma_f32_16x16x32_bf16 v[20:23], v[144:147], v[206:209], 0
	v_mfma_f32_16x16x32_bf16 v[16:19], v[168:171], v[206:209], 0
	v_mfma_f32_16x16x32_bf16 v[4:7], v[144:147], v[214:217], 0
	v_mfma_f32_16x16x32_bf16 v[0:3], v[168:171], v[214:217], 0
	v_mfma_f32_16x16x32_bf16 v[52:55], v[148:151], v[190:193], v[52:55]
	v_mfma_f32_16x16x32_bf16 v[48:51], v[172:175], v[190:193], v[48:51]
	v_mfma_f32_16x16x32_bf16 v[36:39], v[148:151], v[202:205], v[36:39]
	v_mfma_f32_16x16x32_bf16 v[32:35], v[172:175], v[202:205], v[32:35]
	v_mfma_f32_16x16x32_bf16 v[20:23], v[148:151], v[210:213], v[20:23]
	v_mfma_f32_16x16x32_bf16 v[16:19], v[172:175], v[210:213], v[16:19]
	v_mfma_f32_16x16x32_bf16 v[4:7], v[148:151], v[218:221], v[4:7]
	v_mfma_f32_16x16x32_bf16 v[0:3], v[172:175], v[218:221], v[0:3]
	s_barrier
	s_setprio 0
	s_add_i32 s50, 0, 0x18000
	s_add_i32 s51, 0, 0x1c000
	v_add_u32_e32 v140, s50, v179
	v_add_u32_e32 v172, s51, v179
	ds_read_b128 v[128:131], v140
	ds_read_b128 v[132:135], v140 offset:1024
	ds_read_b128 v[136:139], v140 offset:2048
	ds_read_b128 v[140:143], v140 offset:3072
	ds_read_b128 v[144:147], v172
	ds_read_b128 v[148:151], v172 offset:1024
	ds_read_b128 v[168:171], v172 offset:2048
	ds_read_b128 v[172:175], v172 offset:3072
	s_add_u32 s30, s30, 0x80000
	s_addc_u32 s31, s31, 0
	s_mov_b32 m0, s36
	ds_read_b128 v[186:189], v183 offset:32768
	ds_read_b128 v[190:193], v183 offset:33792
	ds_read_b128 v[198:201], v183 offset:34816
	ds_read_b128 v[202:205], v183 offset:35840
	ds_read_b128 v[206:209], v183 offset:36864
	ds_read_b128 v[210:213], v183 offset:37888
	ds_read_b128 v[214:217], v183 offset:38912
	ds_read_b128 v[218:221], v183 offset:39936
	global_load_lds_dwordx4 v152, s[30:31]
	s_mov_b32 m0, s37
	v_lshl_add_u64 v[226:227], s[30:31], 0, v[156:157]
	global_load_lds_dwordx4 v[226:227], off
	s_waitcnt vmcnt(8) lgkmcnt(0)
	s_setprio 1
	s_barrier
	v_mfma_f32_16x16x32_bf16 v[124:127], v[128:131], v[186:189], v[124:127]
	v_mfma_f32_16x16x32_bf16 v[120:123], v[136:139], v[186:189], v[120:123]
	v_mfma_f32_16x16x32_bf16 v[104:107], v[128:131], v[198:201], v[104:107]
	v_mfma_f32_16x16x32_bf16 v[108:111], v[136:139], v[198:201], v[108:111]
	v_mfma_f32_16x16x32_bf16 v[88:91], v[128:131], v[206:209], v[88:91]
	v_mfma_f32_16x16x32_bf16 v[92:95], v[136:139], v[206:209], v[92:95]
	v_mfma_f32_16x16x32_bf16 v[72:75], v[128:131], v[214:217], v[72:75]
	v_mfma_f32_16x16x32_bf16 v[76:79], v[136:139], v[214:217], v[76:79]
	v_mfma_f32_16x16x32_bf16 v[124:127], v[132:135], v[190:193], v[124:127]
	v_mfma_f32_16x16x32_bf16 v[120:123], v[140:143], v[190:193], v[120:123]
	v_mfma_f32_16x16x32_bf16 v[104:107], v[132:135], v[202:205], v[104:107]
	v_mfma_f32_16x16x32_bf16 v[108:111], v[140:143], v[202:205], v[108:111]
	v_mfma_f32_16x16x32_bf16 v[88:91], v[132:135], v[210:213], v[88:91]
	v_mfma_f32_16x16x32_bf16 v[92:95], v[140:143], v[210:213], v[92:95]
	v_mfma_f32_16x16x32_bf16 v[72:75], v[132:135], v[218:221], v[72:75]
	v_mfma_f32_16x16x32_bf16 v[76:79], v[140:143], v[218:221], v[76:79]
	v_mfma_f32_16x16x32_bf16 v[116:119], v[144:147], v[186:189], v[116:119]
	v_mfma_f32_16x16x32_bf16 v[112:115], v[168:171], v[186:189], v[112:115]
	v_mfma_f32_16x16x32_bf16 v[100:103], v[144:147], v[198:201], v[100:103]
	v_mfma_f32_16x16x32_bf16 v[96:99], v[168:171], v[198:201], v[96:99]
	v_mfma_f32_16x16x32_bf16 v[84:87], v[144:147], v[206:209], v[84:87]
	v_mfma_f32_16x16x32_bf16 v[80:83], v[168:171], v[206:209], v[80:83]
	v_mfma_f32_16x16x32_bf16 v[68:71], v[144:147], v[214:217], v[68:71]
	v_mfma_f32_16x16x32_bf16 v[64:67], v[168:171], v[214:217], v[64:67]
	v_mfma_f32_16x16x32_bf16 v[116:119], v[148:151], v[190:193], v[116:119]
	v_mfma_f32_16x16x32_bf16 v[112:115], v[172:175], v[190:193], v[112:115]
	v_mfma_f32_16x16x32_bf16 v[100:103], v[148:151], v[202:205], v[100:103]
	v_mfma_f32_16x16x32_bf16 v[96:99], v[172:175], v[202:205], v[96:99]
	v_mfma_f32_16x16x32_bf16 v[84:87], v[148:151], v[210:213], v[84:87]
	v_mfma_f32_16x16x32_bf16 v[80:83], v[172:175], v[210:213], v[80:83]
	v_mfma_f32_16x16x32_bf16 v[68:71], v[148:151], v[218:221], v[68:71]
	v_mfma_f32_16x16x32_bf16 v[64:67], v[172:175], v[218:221], v[64:67]
	s_barrier
; #define PG8_STAGE(bufoff, gbase, voff) do { _Pragma("unroll") for (int _i = 0; _i < 2; ++_i) \
;         __builtin_amdgcn_global_load_lds((const unsigned*)((const char*)(gbase) + (voff)[_i]), (PG8_LAS unsigned*)(lds + (bufoff) + ldsw + _i * 8192), 16, 0, 0); } while (0)
; #define PG8_LDA(dst, b, h) do { _Pragma("unroll") for (int m = 0; m < 4; ++m) _Pragma("unroll") for (int k = 0; k < 2; ++k) dst[m][k] = *(const PG8_LAS bf16x8*)(lds + PG8_SA(b, h) + aoff + m * 2048 + k * 1024); } while (0)
; #define PG8_MMA(ai, bj, At, Bt) do { __builtin_amdgcn_s_setprio(1); _Pragma("unroll") for (int m = 0; m < 4; ++m) _Pragma("unroll") for (int n = 0; n < 2; ++n) _Pragma("unroll") for (int k = 0; k < 2; ++k) \
;         acc[ai][bj][m][n] = __builtin_amdgcn_mfma_f32_16x16x32_bf16(Bt[n][k], At[m][k], acc[ai][bj][m][n], 0, 0, 0); __builtin_amdgcn_s_setprio(0); } while (0)
; #define PG8_WAIT_V(n) asm volatile("s_waitcnt vmcnt(" #n ")" ::: "memory")
; #define PG8_WAIT_L(n) asm volatile("s_waitcnt lgkmcnt(" #n ")" ::: "memory")
; #define PG8_BAR __builtin_amdgcn_s_barrier()
; #define PG8_SCHED __builtin_amdgcn_sched_barrier(0)
; template <class Epi, class Sched, bool ALIGN_EPI = false, bool SP2 = false>
; __device__ __forceinline__ void gemm_phase(PG8_LAS unsigned char* lds, const Gemm g, const Sched& S, const Epi& E) {
;     ...
;         for (int t = 0; t < nt; t += 2) {
;     ...
;             PG8_LDA(At, 1, 1); PG8_STAGE(PG8_SB(1, 0), b3, voffB); PG8_STAGE(PG8_SB(1, 1), b3 + hstep, voffB); PG8_STAGE(PG8_SA(1, 0), a3, voffA);
;             PG8_WAIT_V(8); PG8_WAIT_L(0); PG8_BAR; PG8_MMA(1, 0, At, B0); PG8_MMA(1, 1, At, B1); PG8_BAR; PG8_SCHED;
	s_setprio 0
	s_add_i32 s30, s50, s34
	v_lshl_add_u64 v[176:177], v[176:177], 0, s[12:13]
	s_mov_b32 m0, s30
	ds_read_b128 v[186:189], v183 offset:49152
	ds_read_b128 v[190:193], v183 offset:50176
	ds_read_b128 v[198:201], v183 offset:51200
	ds_read_b128 v[202:205], v183 offset:52224
	ds_read_b128 v[206:209], v183 offset:53248
	ds_read_b128 v[210:213], v183 offset:54272
	ds_read_b128 v[214:217], v183 offset:55296
	ds_read_b128 v[218:221], v183 offset:56320
	global_load_lds_dwordx4 v[176:177], off
	s_add_i32 m0, s30, 0x2000
	s_add_u32 s28, s28, 0x80080
	v_lshl_add_u64 v[176:177], v[194:195], 0, s[12:13]
	s_addc_u32 s29, s29, 0
	s_add_i32 s30, s51, s34
	global_load_lds_dwordx4 v[176:177], off
	s_mov_b32 m0, s30
	s_nop 0
	global_load_lds_dwordx4 v154, s[28:29]
	s_add_i32 m0, s30, 0x2000
	v_lshl_add_u64 v[176:177], s[28:29], 0, v[158:159]
	global_load_lds_dwordx4 v[176:177], off
	s_mov_b32 m0, s39
	v_lshl_add_u64 v[176:177], v[222:223], 0, s[12:13]
	global_load_lds_dwordx4 v[176:177], off
	s_mov_b32 m0, s40
	v_lshl_add_u64 v[176:177], v[224:225], 0, s[12:13]
	global_load_lds_dwordx4 v[176:177], off
	s_waitcnt vmcnt(8) lgkmcnt(0)
	s_setprio 1
	s_barrier
	v_mfma_f32_16x16x32_bf16 v[56:59], v[128:131], v[186:189], v[56:59]
	v_mfma_f32_16x16x32_bf16 v[60:63], v[136:139], v[186:189], v[60:63]
	v_mfma_f32_16x16x32_bf16 v[40:43], v[128:131], v[198:201], v[40:43]
	v_mfma_f32_16x16x32_bf16 v[44:47], v[136:139], v[198:201], v[44:47]
	v_mfma_f32_16x16x32_bf16 v[24:27], v[128:131], v[206:209], v[24:27]
	v_mfma_f32_16x16x32_bf16 v[28:31], v[136:139], v[206:209], v[28:31]
	v_mfma_f32_16x16x32_bf16 v[8:11], v[128:131], v[214:217], v[8:11]
	v_mfma_f32_16x16x32_bf16 v[12:15], v[136:139], v[214:217], v[12:15]
	v_mfma_f32_16x16x32_bf16 v[56:59], v[132:135], v[190:193], v[56:59]
	v_mfma_f32_16x16x32_bf16 v[60:63], v[140:143], v[190:193], v[60:63]
	v_mfma_f32_16x16x32_bf16 v[40:43], v[132:135], v[202:205], v[40:43]
	v_mfma_f32_16x16x32_bf16 v[44:47], v[140:143], v[202:205], v[44:47]
	v_mfma_f32_16x16x32_bf16 v[24:27], v[132:135], v[210:213], v[24:27]
	v_mfma_f32_16x16x32_bf16 v[28:31], v[140:143], v[210:213], v[28:31]
	v_mfma_f32_16x16x32_bf16 v[8:11], v[132:135], v[218:221], v[8:11]
	v_mfma_f32_16x16x32_bf16 v[12:15], v[140:143], v[218:221], v[12:15]
	v_mfma_f32_16x16x32_bf16 v[52:55], v[144:147], v[186:189], v[52:55]
	v_mfma_f32_16x16x32_bf16 v[48:51], v[168:171], v[186:189], v[48:51]
	v_mfma_f32_16x16x32_bf16 v[36:39], v[144:147], v[198:201], v[36:39]
	v_mfma_f32_16x16x32_bf16 v[32:35], v[168:171], v[198:201], v[32:35]
	v_mfma_f32_16x16x32_bf16 v[20:23], v[144:147], v[206:209], v[20:23]
	v_mfma_f32_16x16x32_bf16 v[16:19], v[168:171], v[206:209], v[16:19]
	v_mfma_f32_16x16x32_bf16 v[4:7], v[144:147], v[214:217], v[4:7]
	v_mfma_f32_16x16x32_bf16 v[0:3], v[168:171], v[214:217], v[0:3]
	v_mfma_f32_16x16x32_bf16 v[52:55], v[148:151], v[190:193], v[52:55]
	v_mfma_f32_16x16x32_bf16 v[48:51], v[172:175], v[190:193], v[48:51]
	v_mfma_f32_16x16x32_bf16 v[36:39], v[148:151], v[202:205], v[36:39]
	v_mfma_f32_16x16x32_bf16 v[32:35], v[172:175], v[202:205], v[32:35]
	v_mfma_f32_16x16x32_bf16 v[20:23], v[148:151], v[210:213], v[20:23]
	v_mfma_f32_16x16x32_bf16 v[16:19], v[172:175], v[210:213], v[16:19]
	v_mfma_f32_16x16x32_bf16 v[4:7], v[148:151], v[218:221], v[4:7]
	v_mfma_f32_16x16x32_bf16 v[0:3], v[172:175], v[218:221], v[0:3]
	s_barrier
	s_setprio 0
	s_add_i32 s49, s49, 2
	s_add_u32 s26, s26, 0x100
	s_addc_u32 s27, s27, 0
	s_add_u32 s47, s47, 0x100
	s_addc_u32 s48, s48, 0
	.p2align	6

; #define PG8_STAGE(bufoff, gbase, voff) do { _Pragma("unroll") for (int _i = 0; _i < 2; ++_i) \
;         __builtin_amdgcn_global_load_lds((const unsigned*)((const char*)(gbase) + (voff)[_i]), (PG8_LAS unsigned*)(lds + (bufoff) + ldsw + _i * 8192), 16, 0, 0); } while (0)
; #define PG8_LDA(dst, b, h) do { _Pragma("unroll") for (int m = 0; m < 4; ++m) _Pragma("unroll") for (int k = 0; k < 2; ++k) dst[m][k] = *(const PG8_LAS bf16x8*)(lds + PG8_SA(b, h) + aoff + m * 2048 + k * 1024); } while (0)
; #define PG8_LDB(dst, b, h) do { _Pragma("unroll") for (int n = 0; n < 2; ++n) _Pragma("unroll") for (int k = 0; k < 2; ++k) dst[n][k] = *(const PG8_LAS bf16x8*)(lds + PG8_SB(b, h) + boff + n * 2048 + k * 1024); } while (0)
; #define PG8_MMA(ai, bj, At, Bt) do { __builtin_amdgcn_s_setprio(1); _Pragma("unroll") for (int m = 0; m < 4; ++m) _Pragma("unroll") for (int n = 0; n < 2; ++n) _Pragma("unroll") for (int k = 0; k < 2; ++k) \
;         acc[ai][bj][m][n] = __builtin_amdgcn_mfma_f32_16x16x32_bf16(Bt[n][k], At[m][k], acc[ai][bj][m][n], 0, 0, 0); __builtin_amdgcn_s_setprio(0); } while (0)
; #define PG8_BAR __builtin_amdgcn_s_barrier()
; template <class Epi, class Sched, bool ALIGN_EPI = false, bool SP2 = false>
; __device__ __forceinline__ void gemm_phase(PG8_LAS unsigned char* lds, const Gemm g, const Sched& S, const Epi& E) {
;     ...
;         const bool has_next = S.next(ui + 1, nxt);
;         const char* nA = has_next ? (const char*)g.A + (size_t)nxt.pm * tstep : cA; const char* nB = has_next ? (const char*)g.Bt + (size_t)nxt.pn * tstep : cB;
;         for (int t = 0; t < nt; t += 2) {
;             const bool last = (t == nt - 2);
;             const char* a1 = cA + (size_t)(t + 1) * kstep;
;             const char* a2 = last ? nA : cA + (size_t)(t + 2) * kstep; const char* b2 = last ? nB : cB + (size_t)(t + 2) * kstep;
;             const char* a3 = a2 + kstep; const char* b3 = b2 + kstep;
;             if (last && has_next) S.a_ready(nxt);
;             if constexpr (SP2) {
;             PG8_LDB(B0, 0, 0); PG8_LDB(B1, 0, 1); PG8_SCHED; PG8_LDA(At, 0, 0); PG8_STAGE(PG8_SA(1, 1), a1 + hstep, voffA);
;             PG8_WAIT_V(8); PG8_WAIT_L(0); PG8_BAR; PG8_MMA(0, 0, At, B0); PG8_MMA(0, 1, At, B1); PG8_BAR; PG8_SCHED;
;             PG8_LDA(At, 0, 1); PG8_STAGE(PG8_SB(0, 0), b2, voffB); PG8_STAGE(PG8_SB(0, 1), b2 + hstep, voffB); PG8_STAGE(PG8_SA(0, 0), a2, voffA);
.LBB0_1372:
	s_ashr_i32 s29, s28, 31
	s_lshl_b64 s[34:35], s[28:29], 20
	s_add_u32 s34, s74, s34
	s_addc_u32 s35, s75, s35
	s_and_b64 s[36:37], s[30:31], exec
	s_cselect_b32 s29, s35, s9
	s_cselect_b32 s39, s34, s8
	s_ashr_i32 s27, s26, 31
	s_lshl_b64 s[36:37], s[26:27], 20
	v_readlane_b32 s44, v254, 22
	v_readlane_b32 s45, v254, 23
	s_add_u32 s36, s44, s36
	s_addc_u32 s37, s45, s37
	s_and_b64 s[44:45], s[30:31], exec
	s_cselect_b32 s27, s37, s43
	s_cselect_b32 s41, s36, s42
	s_add_u32 s8, s8, 0x80080
	s_addc_u32 s9, s9, 0
	s_add_u32 s48, s42, 0x100
	s_addc_u32 s49, s43, 0
	s_mov_b32 s66, -2
	ds_read_b128 v[108:111], v173
	ds_read_b128 v[112:115], v173 offset:1024
	ds_read_b128 v[116:119], v173 offset:2048
	ds_read_b128 v[120:123], v173 offset:3072
	ds_read_b128 v[178:181], v175
	ds_read_b128 v[182:185], v175 offset:1024
	ds_read_b128 v[186:189], v175 offset:2048
	ds_read_b128 v[190:193], v175 offset:3072
	s_add_u32 s42, s8, 0xfff80080
	s_addc_u32 s43, s9, -1
	s_cmp_eq_u32 s66, 28
	s_cselect_b32 s45, s29, s43
	s_cselect_b32 s44, s39, s42
	s_cselect_b32 s43, s27, s49
	s_cselect_b32 s42, s41, s48
	s_add_i32 m0, s50, 0xc000
	ds_read_b128 v[198:201], v177
	ds_read_b128 v[202:205], v177 offset:1024
	ds_read_b128 v[206:209], v177 offset:2048
	ds_read_b128 v[210:213], v177 offset:3072
	ds_read_b128 v[214:217], v177 offset:4096
	ds_read_b128 v[218:221], v177 offset:5120
	ds_read_b128 v[222:225], v177 offset:6144
	ds_read_b128 v[226:229], v177 offset:7168
	global_load_lds_dwordx4 v154, s[8:9]
	s_add_i32 m0, s50, 0xe000
	s_nop 0
	global_load_lds_dwordx4 v156, s[8:9]
	s_waitcnt lgkmcnt(0)
	s_setprio 1
	s_barrier
	v_mfma_f32_16x16x32_bf16 v[140:143], v[108:111], v[198:201], 0
	v_mfma_f32_16x16x32_bf16 v[136:139], v[116:119], v[198:201], 0
	v_mfma_f32_16x16x32_bf16 v[100:103], v[108:111], v[206:209], 0
	v_mfma_f32_16x16x32_bf16 v[124:127], v[116:119], v[206:209], 0
	v_mfma_f32_16x16x32_bf16 v[84:87], v[108:111], v[214:217], 0
	v_mfma_f32_16x16x32_bf16 v[92:95], v[116:119], v[214:217], 0
	v_mfma_f32_16x16x32_bf16 v[68:71], v[108:111], v[222:225], 0
	v_mfma_f32_16x16x32_bf16 v[76:79], v[116:119], v[222:225], 0
	v_mfma_f32_16x16x32_bf16 v[140:143], v[112:115], v[202:205], v[140:143]
	v_mfma_f32_16x16x32_bf16 v[136:139], v[120:123], v[202:205], v[136:139]
	v_mfma_f32_16x16x32_bf16 v[100:103], v[112:115], v[210:213], v[100:103]
	v_mfma_f32_16x16x32_bf16 v[124:127], v[120:123], v[210:213], v[124:127]
	v_mfma_f32_16x16x32_bf16 v[84:87], v[112:115], v[218:221], v[84:87]
	v_mfma_f32_16x16x32_bf16 v[92:95], v[120:123], v[218:221], v[92:95]
	v_mfma_f32_16x16x32_bf16 v[68:71], v[112:115], v[226:229], v[68:71]
	v_mfma_f32_16x16x32_bf16 v[76:79], v[120:123], v[226:229], v[76:79]
	v_mfma_f32_16x16x32_bf16 v[128:131], v[178:181], v[198:201], 0
	v_mfma_f32_16x16x32_bf16 v[132:135], v[186:189], v[198:201], 0
	v_mfma_f32_16x16x32_bf16 v[104:107], v[178:181], v[206:209], 0
	v_mfma_f32_16x16x32_bf16 v[96:99], v[186:189], v[206:209], 0
	v_mfma_f32_16x16x32_bf16 v[88:91], v[178:181], v[214:217], 0
	v_mfma_f32_16x16x32_bf16 v[80:83], v[186:189], v[214:217], 0
	v_mfma_f32_16x16x32_bf16 v[72:75], v[178:181], v[222:225], 0
	v_mfma_f32_16x16x32_bf16 v[64:67], v[186:189], v[222:225], 0
	v_mfma_f32_16x16x32_bf16 v[128:131], v[182:185], v[202:205], v[128:131]
	v_mfma_f32_16x16x32_bf16 v[132:135], v[190:193], v[202:205], v[132:135]
	v_mfma_f32_16x16x32_bf16 v[104:107], v[182:185], v[210:213], v[104:107]
	v_mfma_f32_16x16x32_bf16 v[96:99], v[190:193], v[210:213], v[96:99]
	v_mfma_f32_16x16x32_bf16 v[88:91], v[182:185], v[218:221], v[88:91]
	v_mfma_f32_16x16x32_bf16 v[80:83], v[190:193], v[218:221], v[80:83]
	v_mfma_f32_16x16x32_bf16 v[72:75], v[182:185], v[226:229], v[72:75]
	v_mfma_f32_16x16x32_bf16 v[64:67], v[190:193], v[226:229], v[64:67]
	s_barrier
	s_setprio 0
	s_add_i32 s67, s62, s47
	v_lshl_add_u64 v[160:161], s[42:43], 0, v[144:145]
	s_mov_b32 m0, s67
	ds_read_b128 v[198:201], v177 offset:16384
	ds_read_b128 v[202:205], v177 offset:17408
	ds_read_b128 v[206:209], v177 offset:18432
	ds_read_b128 v[210:213], v177 offset:19456
	ds_read_b128 v[214:217], v177 offset:20480
	ds_read_b128 v[218:221], v177 offset:21504
	ds_read_b128 v[222:225], v177 offset:22528
	ds_read_b128 v[226:229], v177 offset:23552
	global_load_lds_dwordx4 v[160:161], off
	s_add_i32 m0, s67, 0x2000
	s_add_u32 s68, s42, 0x80000
	v_lshl_add_u64 v[164:165], s[42:43], 0, v[146:147]
	s_addc_u32 s69, s43, 0
	s_add_i32 s67, s63, s47
	global_load_lds_dwordx4 v[164:165], off
	s_mov_b32 m0, s67
	v_lshl_add_u64 v[194:195], s[44:45], 0, v[146:147]
	global_load_lds_dwordx4 v144, s[68:69]
	s_add_i32 m0, s67, 0x2000
	s_nop 0
	global_load_lds_dwordx4 v146, s[68:69]
	s_mov_b32 m0, s50
	v_lshl_add_u64 v[170:171], s[44:45], 0, v[144:145]
	global_load_lds_dwordx4 v[170:171], off
	s_mov_b32 m0, s51
	s_nop 0
	global_load_lds_dwordx4 v[194:195], off
	s_waitcnt lgkmcnt(0)
	s_setprio 1
	s_barrier
; #define PG8_STAGE(bufoff, gbase, voff) do { _Pragma("unroll") for (int _i = 0; _i < 2; ++_i) \
;         __builtin_amdgcn_global_load_lds((const unsigned*)((const char*)(gbase) + (voff)[_i]), (PG8_LAS unsigned*)(lds + (bufoff) + ldsw + _i * 8192), 16, 0, 0); } while (0)
; #define PG8_LDA(dst, b, h) do { _Pragma("unroll") for (int m = 0; m < 4; ++m) _Pragma("unroll") for (int k = 0; k < 2; ++k) dst[m][k] = *(const PG8_LAS bf16x8*)(lds + PG8_SA(b, h) + aoff + m * 2048 + k * 1024); } while (0)
; #define PG8_LDB(dst, b, h) do { _Pragma("unroll") for (int n = 0; n < 2; ++n) _Pragma("unroll") for (int k = 0; k < 2; ++k) dst[n][k] = *(const PG8_LAS bf16x8*)(lds + PG8_SB(b, h) + boff + n * 2048 + k * 1024); } while (0)
; #define PG8_MMA(ai, bj, At, Bt) do { __builtin_amdgcn_s_setprio(1); _Pragma("unroll") for (int m = 0; m < 4; ++m) _Pragma("unroll") for (int n = 0; n < 2; ++n) _Pragma("unroll") for (int k = 0; k < 2; ++k) \
;         acc[ai][bj][m][n] = __builtin_amdgcn_mfma_f32_16x16x32_bf16(Bt[n][k], At[m][k], acc[ai][bj][m][n], 0, 0, 0); __builtin_amdgcn_s_setprio(0); } while (0)
; #define PG8_WAIT_V(n) asm volatile("s_waitcnt vmcnt(" #n ")" ::: "memory")
; #define PG8_WAIT_L(n) asm volatile("s_waitcnt lgkmcnt(" #n ")" ::: "memory")
; #define PG8_BAR __builtin_amdgcn_s_barrier()
; #define PG8_SCHED __builtin_amdgcn_sched_barrier(0)
; template <class Epi, class Sched, bool ALIGN_EPI = false, bool SP2 = false>
; __device__ __forceinline__ void gemm_phase(PG8_LAS unsigned char* lds, const Gemm g, const Sched& S, const Epi& E) {
;     ...
;             PG8_WAIT_V(8); PG8_WAIT_L(0); PG8_BAR; PG8_MMA(1, 0, At, B0); PG8_MMA(1, 1, At, B1); PG8_BAR; PG8_SCHED;
;             PG8_LDB(B0, 1, 0); PG8_LDB(B1, 1, 1); PG8_SCHED; PG8_LDA(At, 1, 0); PG8_STAGE(PG8_SA(0, 1), a2 + hstep, voffA);
;             PG8_WAIT_V(8); PG8_WAIT_L(0); PG8_BAR; PG8_MMA(0, 0, At, B0); PG8_MMA(0, 1, At, B1); PG8_BAR; PG8_SCHED;
	v_mfma_f32_16x16x32_bf16 v[60:63], v[108:111], v[198:201], 0
	v_mfma_f32_16x16x32_bf16 v[56:59], v[116:119], v[198:201], 0
	v_mfma_f32_16x16x32_bf16 v[36:39], v[108:111], v[206:209], 0
	v_mfma_f32_16x16x32_bf16 v[44:47], v[116:119], v[206:209], 0
	v_mfma_f32_16x16x32_bf16 v[20:23], v[108:111], v[214:217], 0
	v_mfma_f32_16x16x32_bf16 v[28:31], v[116:119], v[214:217], 0
	v_mfma_f32_16x16x32_bf16 v[4:7], v[108:111], v[222:225], 0
	v_mfma_f32_16x16x32_bf16 v[12:15], v[116:119], v[222:225], 0
	v_mfma_f32_16x16x32_bf16 v[60:63], v[112:115], v[202:205], v[60:63]
	v_mfma_f32_16x16x32_bf16 v[56:59], v[120:123], v[202:205], v[56:59]
	v_mfma_f32_16x16x32_bf16 v[36:39], v[112:115], v[210:213], v[36:39]
	v_mfma_f32_16x16x32_bf16 v[44:47], v[120:123], v[210:213], v[44:47]
	v_mfma_f32_16x16x32_bf16 v[20:23], v[112:115], v[218:221], v[20:23]
	v_mfma_f32_16x16x32_bf16 v[28:31], v[120:123], v[218:221], v[28:31]
	v_mfma_f32_16x16x32_bf16 v[4:7], v[112:115], v[226:229], v[4:7]
	v_mfma_f32_16x16x32_bf16 v[12:15], v[120:123], v[226:229], v[12:15]
	v_mfma_f32_16x16x32_bf16 v[48:51], v[178:181], v[198:201], 0
	v_mfma_f32_16x16x32_bf16 v[52:55], v[186:189], v[198:201], 0
	v_mfma_f32_16x16x32_bf16 v[40:43], v[178:181], v[206:209], 0
	v_mfma_f32_16x16x32_bf16 v[32:35], v[186:189], v[206:209], 0
	v_mfma_f32_16x16x32_bf16 v[24:27], v[178:181], v[214:217], 0
	v_mfma_f32_16x16x32_bf16 v[16:19], v[186:189], v[214:217], 0
	v_mfma_f32_16x16x32_bf16 v[8:11], v[178:181], v[222:225], 0
	v_mfma_f32_16x16x32_bf16 v[0:3], v[186:189], v[222:225], 0
	v_mfma_f32_16x16x32_bf16 v[48:51], v[182:185], v[202:205], v[48:51]
	v_mfma_f32_16x16x32_bf16 v[52:55], v[190:193], v[202:205], v[52:55]
	v_mfma_f32_16x16x32_bf16 v[40:43], v[182:185], v[210:213], v[40:43]
	v_mfma_f32_16x16x32_bf16 v[32:35], v[190:193], v[210:213], v[32:35]
	v_mfma_f32_16x16x32_bf16 v[24:27], v[182:185], v[218:221], v[24:27]
	v_mfma_f32_16x16x32_bf16 v[16:19], v[190:193], v[218:221], v[16:19]
	v_mfma_f32_16x16x32_bf16 v[8:11], v[182:185], v[226:229], v[8:11]
	v_mfma_f32_16x16x32_bf16 v[0:3], v[190:193], v[226:229], v[0:3]
	s_barrier
	s_setprio 0
	s_add_i32 s67, 0, 0x18000
	s_add_i32 s68, 0, 0x1c000
	v_add_u32_e32 v120, s67, v167
	v_add_u32_e32 v162, s68, v167
	ds_read_b128 v[108:111], v120
	ds_read_b128 v[112:115], v120 offset:1024
	ds_read_b128 v[116:119], v120 offset:2048
	ds_read_b128 v[120:123], v120 offset:3072
	ds_read_b128 v[178:181], v162
	ds_read_b128 v[182:185], v162 offset:1024
	ds_read_b128 v[186:189], v162 offset:2048
	ds_read_b128 v[190:193], v162 offset:3072
	s_add_u32 s44, s44, 0x80000
	s_addc_u32 s45, s45, 0
	s_mov_b32 m0, s52
	ds_read_b128 v[198:201], v177 offset:32768
	ds_read_b128 v[202:205], v177 offset:33792
	ds_read_b128 v[206:209], v177 offset:34816
	ds_read_b128 v[210:213], v177 offset:35840
	ds_read_b128 v[214:217], v177 offset:36864
	ds_read_b128 v[218:221], v177 offset:37888
	ds_read_b128 v[222:225], v177 offset:38912
	ds_read_b128 v[226:229], v177 offset:39936
	global_load_lds_dwordx4 v144, s[44:45]
	s_mov_b32 m0, s53
	v_lshl_add_u64 v[230:231], s[44:45], 0, v[146:147]
	global_load_lds_dwordx4 v[230:231], off
	s_waitcnt vmcnt(8) lgkmcnt(0)
	s_setprio 1
	s_barrier
	v_mfma_f32_16x16x32_bf16 v[140:143], v[108:111], v[198:201], v[140:143]
	v_mfma_f32_16x16x32_bf16 v[136:139], v[116:119], v[198:201], v[136:139]
	v_mfma_f32_16x16x32_bf16 v[100:103], v[108:111], v[206:209], v[100:103]
	v_mfma_f32_16x16x32_bf16 v[124:127], v[116:119], v[206:209], v[124:127]
	v_mfma_f32_16x16x32_bf16 v[84:87], v[108:111], v[214:217], v[84:87]
	v_mfma_f32_16x16x32_bf16 v[92:95], v[116:119], v[214:217], v[92:95]
	v_mfma_f32_16x16x32_bf16 v[68:71], v[108:111], v[222:225], v[68:71]
	v_mfma_f32_16x16x32_bf16 v[76:79], v[116:119], v[222:225], v[76:79]
	v_mfma_f32_16x16x32_bf16 v[140:143], v[112:115], v[202:205], v[140:143]
	v_mfma_f32_16x16x32_bf16 v[136:139], v[120:123], v[202:205], v[136:139]
	v_mfma_f32_16x16x32_bf16 v[100:103], v[112:115], v[210:213], v[100:103]
	v_mfma_f32_16x16x32_bf16 v[124:127], v[120:123], v[210:213], v[124:127]
	v_mfma_f32_16x16x32_bf16 v[84:87], v[112:115], v[218:221], v[84:87]
	v_mfma_f32_16x16x32_bf16 v[92:95], v[120:123], v[218:221], v[92:95]
	v_mfma_f32_16x16x32_bf16 v[68:71], v[112:115], v[226:229], v[68:71]
	v_mfma_f32_16x16x32_bf16 v[76:79], v[120:123], v[226:229], v[76:79]
	v_mfma_f32_16x16x32_bf16 v[128:131], v[178:181], v[198:201], v[128:131]
	v_mfma_f32_16x16x32_bf16 v[132:135], v[186:189], v[198:201], v[132:135]
	v_mfma_f32_16x16x32_bf16 v[104:107], v[178:181], v[206:209], v[104:107]
	v_mfma_f32_16x16x32_bf16 v[96:99], v[186:189], v[206:209], v[96:99]
	v_mfma_f32_16x16x32_bf16 v[88:91], v[178:181], v[214:217], v[88:91]
	v_mfma_f32_16x16x32_bf16 v[80:83], v[186:189], v[214:217], v[80:83]
	v_mfma_f32_16x16x32_bf16 v[72:75], v[178:181], v[222:225], v[72:75]
	v_mfma_f32_16x16x32_bf16 v[64:67], v[186:189], v[222:225], v[64:67]
	v_mfma_f32_16x16x32_bf16 v[128:131], v[182:185], v[202:205], v[128:131]
	v_mfma_f32_16x16x32_bf16 v[132:135], v[190:193], v[202:205], v[132:135]
	v_mfma_f32_16x16x32_bf16 v[104:107], v[182:185], v[210:213], v[104:107]
	v_mfma_f32_16x16x32_bf16 v[96:99], v[190:193], v[210:213], v[96:99]
	v_mfma_f32_16x16x32_bf16 v[88:91], v[182:185], v[218:221], v[88:91]
	v_mfma_f32_16x16x32_bf16 v[80:83], v[190:193], v[218:221], v[80:83]
	v_mfma_f32_16x16x32_bf16 v[72:75], v[182:185], v[226:229], v[72:75]
	v_mfma_f32_16x16x32_bf16 v[64:67], v[190:193], v[226:229], v[64:67]
	s_barrier
; #define PG8_STAGE(bufoff, gbase, voff) do { _Pragma("unroll") for (int _i = 0; _i < 2; ++_i) \
;         __builtin_amdgcn_global_load_lds((const unsigned*)((const char*)(gbase) + (voff)[_i]), (PG8_LAS unsigned*)(lds + (bufoff) + ldsw + _i * 8192), 16, 0, 0); } while (0)
; #define PG8_LDA(dst, b, h) do { _Pragma("unroll") for (int m = 0; m < 4; ++m) _Pragma("unroll") for (int k = 0; k < 2; ++k) dst[m][k] = *(const PG8_LAS bf16x8*)(lds + PG8_SA(b, h) + aoff + m * 2048 + k * 1024); } while (0)
; #define PG8_MMA(ai, bj, At, Bt) do { __builtin_amdgcn_s_setprio(1); _Pragma("unroll") for (int m = 0; m < 4; ++m) _Pragma("unroll") for (int n = 0; n < 2; ++n) _Pragma("unroll") for (int k = 0; k < 2; ++k) \
;         acc[ai][bj][m][n] = __builtin_amdgcn_mfma_f32_16x16x32_bf16(Bt[n][k], At[m][k], acc[ai][bj][m][n], 0, 0, 0); __builtin_amdgcn_s_setprio(0); } while (0)
; #define PG8_WAIT_V(n) asm volatile("s_waitcnt vmcnt(" #n ")" ::: "memory")
; #define PG8_WAIT_L(n) asm volatile("s_waitcnt lgkmcnt(" #n ")" ::: "memory")
; #define PG8_BAR __builtin_amdgcn_s_barrier()
; #define PG8_SCHED __builtin_amdgcn_sched_barrier(0)
; template <class Epi, class Sched, bool ALIGN_EPI = false, bool SP2 = false>
; __device__ __forceinline__ void gemm_phase(PG8_LAS unsigned char* lds, const Gemm g, const Sched& S, const Epi& E) {
;     ...
;         for (int t = 0; t < nt; t += 2) {
;     ...
;             PG8_LDA(At, 1, 1); PG8_STAGE(PG8_SB(1, 0), b3, voffB); PG8_STAGE(PG8_SB(1, 1), b3 + hstep, voffB); PG8_STAGE(PG8_SA(1, 0), a3, voffA);
;             PG8_WAIT_V(8); PG8_WAIT_L(0); PG8_BAR; PG8_MMA(1, 0, At, B0); PG8_MMA(1, 1, At, B1); PG8_BAR; PG8_SCHED;
	s_setprio 0
	s_add_i32 s44, s67, s47
	v_lshl_add_u64 v[160:161], v[160:161], 0, s[16:17]
	s_mov_b32 m0, s44
	ds_read_b128 v[198:201], v177 offset:49152
	ds_read_b128 v[202:205], v177 offset:50176
	ds_read_b128 v[206:209], v177 offset:51200
	ds_read_b128 v[210:213], v177 offset:52224
	ds_read_b128 v[214:217], v177 offset:53248
	ds_read_b128 v[218:221], v177 offset:54272
	ds_read_b128 v[222:225], v177 offset:55296
	ds_read_b128 v[226:229], v177 offset:56320
	global_load_lds_dwordx4 v[160:161], off
	s_add_i32 m0, s44, 0x2000
	s_add_u32 s42, s42, 0x80080
	v_lshl_add_u64 v[160:161], v[164:165], 0, s[16:17]
	s_addc_u32 s43, s43, 0
	s_add_i32 s44, s68, s47
	global_load_lds_dwordx4 v[160:161], off
	s_mov_b32 m0, s44
	s_nop 0
	global_load_lds_dwordx4 v144, s[42:43]
	s_add_i32 m0, s44, 0x2000
	v_lshl_add_u64 v[160:161], s[42:43], 0, v[146:147]
	global_load_lds_dwordx4 v[160:161], off
	s_mov_b32 m0, s55
	v_lshl_add_u64 v[160:161], v[170:171], 0, s[16:17]
	global_load_lds_dwordx4 v[160:161], off
	s_mov_b32 m0, s56
	v_lshl_add_u64 v[160:161], v[194:195], 0, s[16:17]
	global_load_lds_dwordx4 v[160:161], off
	s_waitcnt vmcnt(8) lgkmcnt(0)
	s_setprio 1
	s_barrier
	v_mfma_f32_16x16x32_bf16 v[60:63], v[108:111], v[198:201], v[60:63]
	v_mfma_f32_16x16x32_bf16 v[56:59], v[116:119], v[198:201], v[56:59]
	v_mfma_f32_16x16x32_bf16 v[36:39], v[108:111], v[206:209], v[36:39]
	v_mfma_f32_16x16x32_bf16 v[44:47], v[116:119], v[206:209], v[44:47]
	v_mfma_f32_16x16x32_bf16 v[20:23], v[108:111], v[214:217], v[20:23]
	v_mfma_f32_16x16x32_bf16 v[28:31], v[116:119], v[214:217], v[28:31]
	v_mfma_f32_16x16x32_bf16 v[4:7], v[108:111], v[222:225], v[4:7]
	v_mfma_f32_16x16x32_bf16 v[12:15], v[116:119], v[222:225], v[12:15]
	v_mfma_f32_16x16x32_bf16 v[60:63], v[112:115], v[202:205], v[60:63]
	v_mfma_f32_16x16x32_bf16 v[56:59], v[120:123], v[202:205], v[56:59]
	v_mfma_f32_16x16x32_bf16 v[36:39], v[112:115], v[210:213], v[36:39]
	v_mfma_f32_16x16x32_bf16 v[44:47], v[120:123], v[210:213], v[44:47]
	v_mfma_f32_16x16x32_bf16 v[20:23], v[112:115], v[218:221], v[20:23]
	v_mfma_f32_16x16x32_bf16 v[28:31], v[120:123], v[218:221], v[28:31]
	v_mfma_f32_16x16x32_bf16 v[4:7], v[112:115], v[226:229], v[4:7]
	v_mfma_f32_16x16x32_bf16 v[12:15], v[120:123], v[226:229], v[12:15]
	v_mfma_f32_16x16x32_bf16 v[48:51], v[178:181], v[198:201], v[48:51]
	v_mfma_f32_16x16x32_bf16 v[52:55], v[186:189], v[198:201], v[52:55]
	v_mfma_f32_16x16x32_bf16 v[40:43], v[178:181], v[206:209], v[40:43]
	v_mfma_f32_16x16x32_bf16 v[32:35], v[186:189], v[206:209], v[32:35]
	v_mfma_f32_16x16x32_bf16 v[24:27], v[178:181], v[214:217], v[24:27]
	v_mfma_f32_16x16x32_bf16 v[16:19], v[186:189], v[214:217], v[16:19]
	v_mfma_f32_16x16x32_bf16 v[8:11], v[178:181], v[222:225], v[8:11]
	v_mfma_f32_16x16x32_bf16 v[0:3], v[186:189], v[222:225], v[0:3]
	v_mfma_f32_16x16x32_bf16 v[48:51], v[182:185], v[202:205], v[48:51]
	v_mfma_f32_16x16x32_bf16 v[52:55], v[190:193], v[202:205], v[52:55]
	v_mfma_f32_16x16x32_bf16 v[40:43], v[182:185], v[210:213], v[40:43]
	v_mfma_f32_16x16x32_bf16 v[32:35], v[190:193], v[210:213], v[32:35]
	v_mfma_f32_16x16x32_bf16 v[24:27], v[182:185], v[218:221], v[24:27]
	v_mfma_f32_16x16x32_bf16 v[16:19], v[190:193], v[218:221], v[16:19]
	v_mfma_f32_16x16x32_bf16 v[8:11], v[182:185], v[226:229], v[8:11]
	v_mfma_f32_16x16x32_bf16 v[0:3], v[190:193], v[226:229], v[0:3]
	s_barrier
	s_setprio 0
	s_add_i32 s66, s66, 2
	s_add_u32 s8, s8, 0x100
	s_addc_u32 s9, s9, 0
	s_add_u32 s48, s48, 0x100
	s_addc_u32 s49, s49, 0
	.p2align	6

; #define PG8_STAGE(bufoff, gbase, voff) do { _Pragma("unroll") for (int _i = 0; _i < 2; ++_i) \
;         __builtin_amdgcn_global_load_lds((const unsigned*)((const char*)(gbase) + (voff)[_i]), (PG8_LAS unsigned*)(lds + (bufoff) + ldsw + _i * 8192), 16, 0, 0); } while (0)
; #define PG8_LDA(dst, b, h) do { _Pragma("unroll") for (int m = 0; m < 4; ++m) _Pragma("unroll") for (int k = 0; k < 2; ++k) dst[m][k] = *(const PG8_LAS bf16x8*)(lds + PG8_SA(b, h) + aoff + m * 2048 + k * 1024); } while (0)
; #define PG8_LDB(dst, b, h) do { _Pragma("unroll") for (int n = 0; n < 2; ++n) _Pragma("unroll") for (int k = 0; k < 2; ++k) dst[n][k] = *(const PG8_LAS bf16x8*)(lds + PG8_SB(b, h) + boff + n * 2048 + k * 1024); } while (0)
; #define PG8_MMA(ai, bj, At, Bt) do { __builtin_amdgcn_s_setprio(1); _Pragma("unroll") for (int m = 0; m < 4; ++m) _Pragma("unroll") for (int n = 0; n < 2; ++n) _Pragma("unroll") for (int k = 0; k < 2; ++k) \
;         acc[ai][bj][m][n] = __builtin_amdgcn_mfma_f32_16x16x32_bf16(Bt[n][k], At[m][k], acc[ai][bj][m][n], 0, 0, 0); __builtin_amdgcn_s_setprio(0); } while (0)
; #define PG8_BAR __builtin_amdgcn_s_barrier()
; template <class Epi, class Sched, bool ALIGN_EPI = false, bool SP2 = false>
; __device__ __forceinline__ void gemm_phase(PG8_LAS unsigned char* lds, const Gemm g, const Sched& S, const Epi& E) {
;     ...
;         const bool has_next = S.next(ui + 1, nxt);
;         const char* nA = has_next ? (const char*)g.A + (size_t)nxt.pm * tstep : cA; const char* nB = has_next ? (const char*)g.Bt + (size_t)nxt.pn * tstep : cB;
;         for (int t = 0; t < nt; t += 2) {
;             const bool last = (t == nt - 2);
;             const char* a1 = cA + (size_t)(t + 1) * kstep;
;             const char* a2 = last ? nA : cA + (size_t)(t + 2) * kstep; const char* b2 = last ? nB : cB + (size_t)(t + 2) * kstep;
;             const char* a3 = a2 + kstep; const char* b3 = b2 + kstep;
;             if (last && has_next) S.a_ready(nxt);
;             if constexpr (SP2) {
;             PG8_LDB(B0, 0, 0); PG8_LDB(B1, 0, 1); PG8_SCHED; PG8_LDA(At, 0, 0); PG8_STAGE(PG8_SA(1, 1), a1 + hstep, voffA);
;             PG8_WAIT_V(8); PG8_WAIT_L(0); PG8_BAR; PG8_MMA(0, 0, At, B0); PG8_MMA(0, 1, At, B1); PG8_BAR; PG8_SCHED;
;             PG8_LDA(At, 0, 1); PG8_STAGE(PG8_SB(0, 0), b2, voffB); PG8_STAGE(PG8_SB(0, 1), b2 + hstep, voffB); PG8_STAGE(PG8_SA(0, 0), a2, voffA);
.LBB0_1548:
	s_ashr_i32 s13, s12, 31
	s_lshl_b64 s[14:15], s[12:13], 20
	s_add_u32 s14, s60, s14
	s_addc_u32 s15, s61, s15
	s_and_b64 s[16:17], s[0:1], exec
	s_cselect_b32 s13, s15, s21
	s_cselect_b32 s39, s14, s20
	s_ashr_i32 s11, s10, 31
	s_lshl_b64 s[16:17], s[10:11], 20
	s_add_u32 s16, s72, s16
	s_addc_u32 s17, s73, s17
	s_and_b64 s[24:25], s[0:1], exec
	s_cselect_b32 s11, s17, s23
	s_cselect_b32 s40, s16, s22
	s_add_u32 s20, s20, 0x80080
	s_addc_u32 s21, s21, 0
	s_add_u32 s41, s22, 0x100
	s_addc_u32 s42, s23, 0
	s_mov_b32 s43, -2
	ds_read_b128 v[144:147], v155
	ds_read_b128 v[148:151], v155 offset:1024
	ds_read_b128 v[158:161], v155 offset:2048
	ds_read_b128 v[162:165], v155 offset:3072
	ds_read_b128 v[166:169], v156
	ds_read_b128 v[170:173], v156 offset:1024
	ds_read_b128 v[174:177], v156 offset:2048
	ds_read_b128 v[178:181], v156 offset:3072
	s_add_u32 s22, s20, 0xfff80080
	s_addc_u32 s23, s21, -1
	s_cmp_eq_u32 s43, 28
	s_cselect_b32 s25, s13, s23
	s_cselect_b32 s24, s39, s22
	s_cselect_b32 s23, s11, s42
	s_cselect_b32 s22, s40, s41
	s_add_i32 m0, s19, 0xc000
	ds_read_b128 v[182:185], v157
	ds_read_b128 v[186:189], v157 offset:1024
	ds_read_b128 v[190:193], v157 offset:2048
	ds_read_b128 v[194:197], v157 offset:3072
	ds_read_b128 v[198:201], v157 offset:4096
	ds_read_b128 v[202:205], v157 offset:5120
	ds_read_b128 v[206:209], v157 offset:6144
	ds_read_b128 v[210:213], v157 offset:7168
	global_load_lds_dwordx4 v136, s[20:21]
	s_add_i32 m0, s19, 0xe000
	s_nop 0
	global_load_lds_dwordx4 v138, s[20:21]
	s_waitcnt lgkmcnt(0)
	s_setprio 1
	s_barrier
	v_mfma_f32_16x16x32_bf16 v[124:127], v[144:147], v[182:185], 0
	v_mfma_f32_16x16x32_bf16 v[120:123], v[158:161], v[182:185], 0
	v_mfma_f32_16x16x32_bf16 v[108:111], v[144:147], v[190:193], 0
	v_mfma_f32_16x16x32_bf16 v[104:107], v[158:161], v[190:193], 0
	v_mfma_f32_16x16x32_bf16 v[88:91], v[144:147], v[198:201], 0
	v_mfma_f32_16x16x32_bf16 v[92:95], v[158:161], v[198:201], 0
	v_mfma_f32_16x16x32_bf16 v[72:75], v[144:147], v[206:209], 0
	v_mfma_f32_16x16x32_bf16 v[76:79], v[158:161], v[206:209], 0
	v_mfma_f32_16x16x32_bf16 v[124:127], v[148:151], v[186:189], v[124:127]
	v_mfma_f32_16x16x32_bf16 v[120:123], v[162:165], v[186:189], v[120:123]
	v_mfma_f32_16x16x32_bf16 v[108:111], v[148:151], v[194:197], v[108:111]
	v_mfma_f32_16x16x32_bf16 v[104:107], v[162:165], v[194:197], v[104:107]
	v_mfma_f32_16x16x32_bf16 v[88:91], v[148:151], v[202:205], v[88:91]
	v_mfma_f32_16x16x32_bf16 v[92:95], v[162:165], v[202:205], v[92:95]
	v_mfma_f32_16x16x32_bf16 v[72:75], v[148:151], v[210:213], v[72:75]
	v_mfma_f32_16x16x32_bf16 v[76:79], v[162:165], v[210:213], v[76:79]
	v_mfma_f32_16x16x32_bf16 v[116:119], v[166:169], v[182:185], 0
	v_mfma_f32_16x16x32_bf16 v[112:115], v[174:177], v[182:185], 0
	v_mfma_f32_16x16x32_bf16 v[96:99], v[166:169], v[190:193], 0
	v_mfma_f32_16x16x32_bf16 v[100:103], v[174:177], v[190:193], 0
	v_mfma_f32_16x16x32_bf16 v[80:83], v[166:169], v[198:201], 0
	v_mfma_f32_16x16x32_bf16 v[84:87], v[174:177], v[198:201], 0
	v_mfma_f32_16x16x32_bf16 v[64:67], v[166:169], v[206:209], 0
	v_mfma_f32_16x16x32_bf16 v[68:71], v[174:177], v[206:209], 0
	v_mfma_f32_16x16x32_bf16 v[116:119], v[170:173], v[186:189], v[116:119]
	v_mfma_f32_16x16x32_bf16 v[112:115], v[178:181], v[186:189], v[112:115]
	v_mfma_f32_16x16x32_bf16 v[96:99], v[170:173], v[194:197], v[96:99]
	v_mfma_f32_16x16x32_bf16 v[100:103], v[178:181], v[194:197], v[100:103]
	v_mfma_f32_16x16x32_bf16 v[80:83], v[170:173], v[202:205], v[80:83]
	v_mfma_f32_16x16x32_bf16 v[84:87], v[178:181], v[202:205], v[84:87]
	v_mfma_f32_16x16x32_bf16 v[64:67], v[170:173], v[210:213], v[64:67]
	v_mfma_f32_16x16x32_bf16 v[68:71], v[178:181], v[210:213], v[68:71]
	s_barrier
	s_setprio 0
	s_add_i32 s44, s36, s27
	v_lshl_add_u64 v[214:215], s[22:23], 0, v[130:131]
	s_mov_b32 m0, s44
	ds_read_b128 v[182:185], v157 offset:16384
	ds_read_b128 v[186:189], v157 offset:17408
	ds_read_b128 v[190:193], v157 offset:18432
	ds_read_b128 v[194:197], v157 offset:19456
	ds_read_b128 v[198:201], v157 offset:20480
	ds_read_b128 v[202:205], v157 offset:21504
	ds_read_b128 v[206:209], v157 offset:22528
	ds_read_b128 v[210:213], v157 offset:23552
	global_load_lds_dwordx4 v[214:215], off
	s_add_i32 m0, s44, 0x2000
	s_add_u32 s44, s22, 0x80000
	v_lshl_add_u64 v[216:217], s[22:23], 0, v[134:135]
	s_addc_u32 s45, s23, 0
	s_add_i32 s46, s37, s27
	global_load_lds_dwordx4 v[216:217], off
	s_mov_b32 m0, s46
	v_lshl_add_u64 v[220:221], s[24:25], 0, v[132:133]
	global_load_lds_dwordx4 v130, s[44:45]
	s_add_i32 m0, s46, 0x2000
	s_nop 0
	global_load_lds_dwordx4 v134, s[44:45]
	s_mov_b32 m0, s19
	v_lshl_add_u64 v[218:219], s[24:25], 0, v[128:129]
	global_load_lds_dwordx4 v[218:219], off
	s_mov_b32 m0, s28
	s_nop 0
	global_load_lds_dwordx4 v[220:221], off
	s_waitcnt lgkmcnt(0)
	s_setprio 1
	s_barrier
; #define PG8_STAGE(bufoff, gbase, voff) do { _Pragma("unroll") for (int _i = 0; _i < 2; ++_i) \
;         __builtin_amdgcn_global_load_lds((const unsigned*)((const char*)(gbase) + (voff)[_i]), (PG8_LAS unsigned*)(lds + (bufoff) + ldsw + _i * 8192), 16, 0, 0); } while (0)
; #define PG8_LDA(dst, b, h) do { _Pragma("unroll") for (int m = 0; m < 4; ++m) _Pragma("unroll") for (int k = 0; k < 2; ++k) dst[m][k] = *(const PG8_LAS bf16x8*)(lds + PG8_SA(b, h) + aoff + m * 2048 + k * 1024); } while (0)
; #define PG8_LDB(dst, b, h) do { _Pragma("unroll") for (int n = 0; n < 2; ++n) _Pragma("unroll") for (int k = 0; k < 2; ++k) dst[n][k] = *(const PG8_LAS bf16x8*)(lds + PG8_SB(b, h) + boff + n * 2048 + k * 1024); } while (0)
; #define PG8_MMA(ai, bj, At, Bt) do { __builtin_amdgcn_s_setprio(1); _Pragma("unroll") for (int m = 0; m < 4; ++m) _Pragma("unroll") for (int n = 0; n < 2; ++n) _Pragma("unroll") for (int k = 0; k < 2; ++k) \
;         acc[ai][bj][m][n] = __builtin_amdgcn_mfma_f32_16x16x32_bf16(Bt[n][k], At[m][k], acc[ai][bj][m][n], 0, 0, 0); __builtin_amdgcn_s_setprio(0); } while (0)
; #define PG8_WAIT_V(n) asm volatile("s_waitcnt vmcnt(" #n ")" ::: "memory")
; #define PG8_WAIT_L(n) asm volatile("s_waitcnt lgkmcnt(" #n ")" ::: "memory")
; #define PG8_BAR __builtin_amdgcn_s_barrier()
; #define PG8_SCHED __builtin_amdgcn_sched_barrier(0)
; template <class Epi, class Sched, bool ALIGN_EPI = false, bool SP2 = false>
; __device__ __forceinline__ void gemm_phase(PG8_LAS unsigned char* lds, const Gemm g, const Sched& S, const Epi& E) {
;     ...
;             PG8_WAIT_V(8); PG8_WAIT_L(0); PG8_BAR; PG8_MMA(1, 0, At, B0); PG8_MMA(1, 1, At, B1); PG8_BAR; PG8_SCHED;
;             PG8_LDB(B0, 1, 0); PG8_LDB(B1, 1, 1); PG8_SCHED; PG8_LDA(At, 1, 0); PG8_STAGE(PG8_SA(0, 1), a2 + hstep, voffA);
;             PG8_WAIT_V(8); PG8_WAIT_L(0); PG8_BAR; PG8_MMA(0, 0, At, B0); PG8_MMA(0, 1, At, B1); PG8_BAR; PG8_SCHED;
	v_mfma_f32_16x16x32_bf16 v[56:59], v[144:147], v[182:185], 0
	v_mfma_f32_16x16x32_bf16 v[60:63], v[158:161], v[182:185], 0
	v_mfma_f32_16x16x32_bf16 v[40:43], v[144:147], v[190:193], 0
	v_mfma_f32_16x16x32_bf16 v[44:47], v[158:161], v[190:193], 0
	v_mfma_f32_16x16x32_bf16 v[24:27], v[144:147], v[198:201], 0
	v_mfma_f32_16x16x32_bf16 v[28:31], v[158:161], v[198:201], 0
	v_mfma_f32_16x16x32_bf16 v[8:11], v[144:147], v[206:209], 0
	v_mfma_f32_16x16x32_bf16 v[12:15], v[158:161], v[206:209], 0
	v_mfma_f32_16x16x32_bf16 v[56:59], v[148:151], v[186:189], v[56:59]
	v_mfma_f32_16x16x32_bf16 v[60:63], v[162:165], v[186:189], v[60:63]
	v_mfma_f32_16x16x32_bf16 v[40:43], v[148:151], v[194:197], v[40:43]
	v_mfma_f32_16x16x32_bf16 v[44:47], v[162:165], v[194:197], v[44:47]
	v_mfma_f32_16x16x32_bf16 v[24:27], v[148:151], v[202:205], v[24:27]
	v_mfma_f32_16x16x32_bf16 v[28:31], v[162:165], v[202:205], v[28:31]
	v_mfma_f32_16x16x32_bf16 v[8:11], v[148:151], v[210:213], v[8:11]
	v_mfma_f32_16x16x32_bf16 v[12:15], v[162:165], v[210:213], v[12:15]
	v_mfma_f32_16x16x32_bf16 v[48:51], v[166:169], v[182:185], 0
	v_mfma_f32_16x16x32_bf16 v[52:55], v[174:177], v[182:185], 0
	v_mfma_f32_16x16x32_bf16 v[32:35], v[166:169], v[190:193], 0
	v_mfma_f32_16x16x32_bf16 v[36:39], v[174:177], v[190:193], 0
	v_mfma_f32_16x16x32_bf16 v[16:19], v[166:169], v[198:201], 0
	v_mfma_f32_16x16x32_bf16 v[20:23], v[174:177], v[198:201], 0
	v_mfma_f32_16x16x32_bf16 v[0:3], v[166:169], v[206:209], 0
	v_mfma_f32_16x16x32_bf16 v[4:7], v[174:177], v[206:209], 0
	v_mfma_f32_16x16x32_bf16 v[48:51], v[170:173], v[186:189], v[48:51]
	v_mfma_f32_16x16x32_bf16 v[52:55], v[178:181], v[186:189], v[52:55]
	v_mfma_f32_16x16x32_bf16 v[32:35], v[170:173], v[194:197], v[32:35]
	v_mfma_f32_16x16x32_bf16 v[36:39], v[178:181], v[194:197], v[36:39]
	v_mfma_f32_16x16x32_bf16 v[16:19], v[170:173], v[202:205], v[16:19]
	v_mfma_f32_16x16x32_bf16 v[20:23], v[178:181], v[202:205], v[20:23]
	v_mfma_f32_16x16x32_bf16 v[0:3], v[170:173], v[210:213], v[0:3]
	v_mfma_f32_16x16x32_bf16 v[4:7], v[178:181], v[210:213], v[4:7]
	s_barrier
	s_setprio 0
	s_add_i32 s44, 0, 0x18000
	s_add_i32 s45, 0, 0x1c000
	v_add_u32_e32 v162, s44, v153
	v_add_u32_e32 v178, s45, v153
	ds_read_b128 v[144:147], v162
	ds_read_b128 v[148:151], v162 offset:1024
	ds_read_b128 v[158:161], v162 offset:2048
	ds_read_b128 v[162:165], v162 offset:3072
	ds_read_b128 v[166:169], v178
	ds_read_b128 v[170:173], v178 offset:1024
	ds_read_b128 v[174:177], v178 offset:2048
	ds_read_b128 v[178:181], v178 offset:3072
	s_add_u32 s24, s24, 0x80000
	s_addc_u32 s25, s25, 0
	s_mov_b32 m0, s29
	ds_read_b128 v[182:185], v157 offset:32768
	ds_read_b128 v[186:189], v157 offset:33792
	ds_read_b128 v[190:193], v157 offset:34816
	ds_read_b128 v[194:197], v157 offset:35840
	ds_read_b128 v[198:201], v157 offset:36864
	ds_read_b128 v[202:205], v157 offset:37888
	ds_read_b128 v[206:209], v157 offset:38912
	ds_read_b128 v[210:213], v157 offset:39936
	global_load_lds_dwordx4 v128, s[24:25]
	s_mov_b32 m0, s30
	v_lshl_add_u64 v[222:223], s[24:25], 0, v[132:133]
	global_load_lds_dwordx4 v[222:223], off
	s_waitcnt vmcnt(8) lgkmcnt(0)
	s_setprio 1
	s_barrier
	v_mfma_f32_16x16x32_bf16 v[124:127], v[144:147], v[182:185], v[124:127]
	v_mfma_f32_16x16x32_bf16 v[120:123], v[158:161], v[182:185], v[120:123]
	v_mfma_f32_16x16x32_bf16 v[108:111], v[144:147], v[190:193], v[108:111]
	v_mfma_f32_16x16x32_bf16 v[104:107], v[158:161], v[190:193], v[104:107]
	v_mfma_f32_16x16x32_bf16 v[88:91], v[144:147], v[198:201], v[88:91]
	v_mfma_f32_16x16x32_bf16 v[92:95], v[158:161], v[198:201], v[92:95]
	v_mfma_f32_16x16x32_bf16 v[72:75], v[144:147], v[206:209], v[72:75]
	v_mfma_f32_16x16x32_bf16 v[76:79], v[158:161], v[206:209], v[76:79]
	v_mfma_f32_16x16x32_bf16 v[124:127], v[148:151], v[186:189], v[124:127]
	v_mfma_f32_16x16x32_bf16 v[120:123], v[162:165], v[186:189], v[120:123]
	v_mfma_f32_16x16x32_bf16 v[108:111], v[148:151], v[194:197], v[108:111]
	v_mfma_f32_16x16x32_bf16 v[104:107], v[162:165], v[194:197], v[104:107]
	v_mfma_f32_16x16x32_bf16 v[88:91], v[148:151], v[202:205], v[88:91]
	v_mfma_f32_16x16x32_bf16 v[92:95], v[162:165], v[202:205], v[92:95]
	v_mfma_f32_16x16x32_bf16 v[72:75], v[148:151], v[210:213], v[72:75]
	v_mfma_f32_16x16x32_bf16 v[76:79], v[162:165], v[210:213], v[76:79]
	v_mfma_f32_16x16x32_bf16 v[116:119], v[166:169], v[182:185], v[116:119]
	v_mfma_f32_16x16x32_bf16 v[112:115], v[174:177], v[182:185], v[112:115]
	v_mfma_f32_16x16x32_bf16 v[96:99], v[166:169], v[190:193], v[96:99]
	v_mfma_f32_16x16x32_bf16 v[100:103], v[174:177], v[190:193], v[100:103]
	v_mfma_f32_16x16x32_bf16 v[80:83], v[166:169], v[198:201], v[80:83]
	v_mfma_f32_16x16x32_bf16 v[84:87], v[174:177], v[198:201], v[84:87]
	v_mfma_f32_16x16x32_bf16 v[64:67], v[166:169], v[206:209], v[64:67]
	v_mfma_f32_16x16x32_bf16 v[68:71], v[174:177], v[206:209], v[68:71]
	v_mfma_f32_16x16x32_bf16 v[116:119], v[170:173], v[186:189], v[116:119]
	v_mfma_f32_16x16x32_bf16 v[112:115], v[178:181], v[186:189], v[112:115]
	v_mfma_f32_16x16x32_bf16 v[96:99], v[170:173], v[194:197], v[96:99]
	v_mfma_f32_16x16x32_bf16 v[100:103], v[178:181], v[194:197], v[100:103]
	v_mfma_f32_16x16x32_bf16 v[80:83], v[170:173], v[202:205], v[80:83]
	v_mfma_f32_16x16x32_bf16 v[84:87], v[178:181], v[202:205], v[84:87]
	v_mfma_f32_16x16x32_bf16 v[64:67], v[170:173], v[210:213], v[64:67]
	v_mfma_f32_16x16x32_bf16 v[68:71], v[178:181], v[210:213], v[68:71]
	s_barrier
; #define PG8_STAGE(bufoff, gbase, voff) do { _Pragma("unroll") for (int _i = 0; _i < 2; ++_i) \
;         __builtin_amdgcn_global_load_lds((const unsigned*)((const char*)(gbase) + (voff)[_i]), (PG8_LAS unsigned*)(lds + (bufoff) + ldsw + _i * 8192), 16, 0, 0); } while (0)
; #define PG8_LDA(dst, b, h) do { _Pragma("unroll") for (int m = 0; m < 4; ++m) _Pragma("unroll") for (int k = 0; k < 2; ++k) dst[m][k] = *(const PG8_LAS bf16x8*)(lds + PG8_SA(b, h) + aoff + m * 2048 + k * 1024); } while (0)
; #define PG8_MMA(ai, bj, At, Bt) do { __builtin_amdgcn_s_setprio(1); _Pragma("unroll") for (int m = 0; m < 4; ++m) _Pragma("unroll") for (int n = 0; n < 2; ++n) _Pragma("unroll") for (int k = 0; k < 2; ++k) \
;         acc[ai][bj][m][n] = __builtin_amdgcn_mfma_f32_16x16x32_bf16(Bt[n][k], At[m][k], acc[ai][bj][m][n], 0, 0, 0); __builtin_amdgcn_s_setprio(0); } while (0)
; #define PG8_WAIT_V(n) asm volatile("s_waitcnt vmcnt(" #n ")" ::: "memory")
; #define PG8_WAIT_L(n) asm volatile("s_waitcnt lgkmcnt(" #n ")" ::: "memory")
; #define PG8_BAR __builtin_amdgcn_s_barrier()
; #define PG8_SCHED __builtin_amdgcn_sched_barrier(0)
; template <class Epi, class Sched, bool ALIGN_EPI = false, bool SP2 = false>
; __device__ __forceinline__ void gemm_phase(PG8_LAS unsigned char* lds, const Gemm g, const Sched& S, const Epi& E) {
;     ...
;         for (int t = 0; t < nt; t += 2) {
;     ...
;             PG8_LDA(At, 1, 1); PG8_STAGE(PG8_SB(1, 0), b3, voffB); PG8_STAGE(PG8_SB(1, 1), b3 + hstep, voffB); PG8_STAGE(PG8_SA(1, 0), a3, voffA);
;             PG8_WAIT_V(8); PG8_WAIT_L(0); PG8_BAR; PG8_MMA(1, 0, At, B0); PG8_MMA(1, 1, At, B1); PG8_BAR; PG8_SCHED;
	s_setprio 0
	s_add_i32 s24, s44, s27
	v_lshl_add_u64 v[214:215], v[214:215], 0, s[4:5]
	s_mov_b32 m0, s24
	ds_read_b128 v[182:185], v157 offset:49152
	ds_read_b128 v[186:189], v157 offset:50176
	ds_read_b128 v[190:193], v157 offset:51200
	ds_read_b128 v[194:197], v157 offset:52224
	ds_read_b128 v[198:201], v157 offset:53248
	ds_read_b128 v[202:205], v157 offset:54272
	ds_read_b128 v[206:209], v157 offset:55296
	ds_read_b128 v[210:213], v157 offset:56320
	global_load_lds_dwordx4 v[214:215], off
	s_add_i32 m0, s24, 0x2000
	s_add_u32 s22, s22, 0x80080
	v_lshl_add_u64 v[214:215], v[216:217], 0, s[4:5]
	s_addc_u32 s23, s23, 0
	s_add_i32 s24, s45, s27
	global_load_lds_dwordx4 v[214:215], off
	s_mov_b32 m0, s24
	s_nop 0
	global_load_lds_dwordx4 v130, s[22:23]
	s_add_i32 m0, s24, 0x2000
	v_lshl_add_u64 v[214:215], s[22:23], 0, v[134:135]
	global_load_lds_dwordx4 v[214:215], off
	s_mov_b32 m0, s33
	v_lshl_add_u64 v[214:215], v[218:219], 0, s[4:5]
	global_load_lds_dwordx4 v[214:215], off
	s_mov_b32 m0, s34
	v_lshl_add_u64 v[214:215], v[220:221], 0, s[4:5]
	global_load_lds_dwordx4 v[214:215], off
	s_waitcnt vmcnt(8) lgkmcnt(0)
	s_setprio 1
	s_barrier
	v_mfma_f32_16x16x32_bf16 v[56:59], v[144:147], v[182:185], v[56:59]
	v_mfma_f32_16x16x32_bf16 v[60:63], v[158:161], v[182:185], v[60:63]
	v_mfma_f32_16x16x32_bf16 v[40:43], v[144:147], v[190:193], v[40:43]
	v_mfma_f32_16x16x32_bf16 v[44:47], v[158:161], v[190:193], v[44:47]
	v_mfma_f32_16x16x32_bf16 v[24:27], v[144:147], v[198:201], v[24:27]
	v_mfma_f32_16x16x32_bf16 v[28:31], v[158:161], v[198:201], v[28:31]
	v_mfma_f32_16x16x32_bf16 v[8:11], v[144:147], v[206:209], v[8:11]
	v_mfma_f32_16x16x32_bf16 v[12:15], v[158:161], v[206:209], v[12:15]
	v_mfma_f32_16x16x32_bf16 v[56:59], v[148:151], v[186:189], v[56:59]
	v_mfma_f32_16x16x32_bf16 v[60:63], v[162:165], v[186:189], v[60:63]
	v_mfma_f32_16x16x32_bf16 v[40:43], v[148:151], v[194:197], v[40:43]
	v_mfma_f32_16x16x32_bf16 v[44:47], v[162:165], v[194:197], v[44:47]
	v_mfma_f32_16x16x32_bf16 v[24:27], v[148:151], v[202:205], v[24:27]
	v_mfma_f32_16x16x32_bf16 v[28:31], v[162:165], v[202:205], v[28:31]
	v_mfma_f32_16x16x32_bf16 v[8:11], v[148:151], v[210:213], v[8:11]
	v_mfma_f32_16x16x32_bf16 v[12:15], v[162:165], v[210:213], v[12:15]
	v_mfma_f32_16x16x32_bf16 v[48:51], v[166:169], v[182:185], v[48:51]
	v_mfma_f32_16x16x32_bf16 v[52:55], v[174:177], v[182:185], v[52:55]
	v_mfma_f32_16x16x32_bf16 v[32:35], v[166:169], v[190:193], v[32:35]
	v_mfma_f32_16x16x32_bf16 v[36:39], v[174:177], v[190:193], v[36:39]
	v_mfma_f32_16x16x32_bf16 v[16:19], v[166:169], v[198:201], v[16:19]
	v_mfma_f32_16x16x32_bf16 v[20:23], v[174:177], v[198:201], v[20:23]
	v_mfma_f32_16x16x32_bf16 v[0:3], v[166:169], v[206:209], v[0:3]
	v_mfma_f32_16x16x32_bf16 v[4:7], v[174:177], v[206:209], v[4:7]
	v_mfma_f32_16x16x32_bf16 v[48:51], v[170:173], v[186:189], v[48:51]
	v_mfma_f32_16x16x32_bf16 v[52:55], v[178:181], v[186:189], v[52:55]
	v_mfma_f32_16x16x32_bf16 v[32:35], v[170:173], v[194:197], v[32:35]
	v_mfma_f32_16x16x32_bf16 v[36:39], v[178:181], v[194:197], v[36:39]
	v_mfma_f32_16x16x32_bf16 v[16:19], v[170:173], v[202:205], v[16:19]
	v_mfma_f32_16x16x32_bf16 v[20:23], v[178:181], v[202:205], v[20:23]
	v_mfma_f32_16x16x32_bf16 v[0:3], v[170:173], v[210:213], v[0:3]
	v_mfma_f32_16x16x32_bf16 v[4:7], v[178:181], v[210:213], v[4:7]
	s_barrier
	s_setprio 0
	s_add_i32 s43, s43, 2
	s_add_u32 s20, s20, 0x100
	s_addc_u32 s21, s21, 0
	s_add_u32 s41, s41, 0x100
	s_addc_u32 s42, s42, 0
	.p2align	6
